# FFN1 epilogue: bf16 conversions write the store registers directly, 30 v_mov copies per lane-tile dropped
# speedup vs baseline: 1.0003x; 1.0003x over previous
; __device__ __forceinline__ float sigmoidf_(float x) { return __builtin_amdgcn_rcpf(1.0f + __expf(-x)); }
;     __device__ __forceinline__ void operator()(AccRef acc, const Unit& u, int wr, int wc, int fr, int fq) const {
;     ...
;                 float o[4][4];
; #pragma unroll
;                 for (int j = 0; j < 4; ++j) {
;                     const float v0 = acc[ai][0][0][n][j], v1 = acc[ai][0][1][n][j], v2 = acc[ai][0][2][n][j], v3 = acc[ai][0][3][n][j];
;                     const float g0 = acc[ai][1][0][n][j], g1 = acc[ai][1][1][n][j], g2 = acc[ai][1][2][n][j], g3 = acc[ai][1][3][n][j];
;                     const float pv3 = dpp_upd<0x111>(h3v[j], v3), pv2 = dpp_upd<0x111>(h2v[j], v2), pg3 = dpp_upd<0x111>(h3g[j], g3), pg2 = dpp_upd<0x111>(h2g[j], g2);
;                     const float hv0 = bvv[j] + w2v[j] * v0 + w1v[j] * pv3 + w0v[j] * pv2, hv1 = bvv[j] + w2v[j] * v1 + w1v[j] * v0 + w0v[j] * pv3;
;                     const float hv2 = bvv[j] + w2v[j] * v2 + w1v[j] * v1 + w0v[j] * v0, hv3 = bvv[j] + w2v[j] * v3 + w1v[j] * v2 + w0v[j] * v1;
;                     const float hg0 = bvg[j] + w2g[j] * g0 + w1g[j] * pg3 + w0g[j] * pg2, hg1 = bvg[j] + w2g[j] * g1 + w1g[j] * g0 + w0g[j] * pg3;
;                     const float hg2 = bvg[j] + w2g[j] * g2 + w1g[j] * g1 + w0g[j] * g0, hg3 = bvg[j] + w2g[j] * g3 + w1g[j] * g2 + w0g[j] * g1;
;                     o[0][j] = hg0 * sigmoidf_(hg0) * hv0; o[1][j] = hg1 * sigmoidf_(hg1) * hv1; o[2][j] = hg2 * sigmoidf_(hg2) * hv2; o[3][j] = hg3 * sigmoidf_(hg3) * hv3; }
; #pragma unroll
;                 for (int m = 0; m < 4; ++m) { u32x2 w; w.x = cvt_pk_bf16(o[m][0], o[m][1]); w.y = cvt_pk_bf16(o[m][2], o[m][3]);
;                     *(u32x2*)(Aout + (size_t)(row0 + ai * 128 + m) * FH + hc0 + 4 * n) = w; } } }
.LBB0_305:
	s_or_b64 exec, exec, s[34:35]
	s_waitcnt lgkmcnt(0)
	v_mov_b32_dpp v64, v8 row_shr:1 row_mask:0xf bank_mask:0xf
	v_mov_b32_dpp v65, v9 row_shr:1 row_mask:0xf bank_mask:0xf
	v_pk_fma_f32 v[44:45], v[24:25], v[120:121], v[124:125]
	v_mov_b32_dpp v40, v0 row_shr:1 row_mask:0xf bank_mask:0xf
	v_mov_b32_dpp v41, v1 row_shr:1 row_mask:0xf bank_mask:0xf
	v_pk_fma_f32 v[44:45], v[116:117], v[64:65], v[44:45]
	v_mov_b32_dpp v32, v20 row_shr:1 row_mask:0xf bank_mask:0xf
	v_pk_fma_f32 v[40:41], v[112:113], v[40:41], v[44:45]
	v_mov_b32_dpp v33, v21 row_shr:1 row_mask:0xf bank_mask:0xf
	v_exp_f32_e32 v44, v40
	v_exp_f32_e32 v45, v41
	v_pk_fma_f32 v[46:47], v[28:29], v[104:105], v[108:109]
	v_mov_b32_dpp v36, v12 row_shr:1 row_mask:0xf bank_mask:0xf
	v_pk_add_f32 v[44:45], v[44:45], 1.0 op_sel_hi:[1,0]
	v_rcp_f32_e32 v44, v44
	v_rcp_f32_e32 v45, v45
	v_mov_b32_dpp v37, v13 row_shr:1 row_mask:0xf bank_mask:0xf
	v_pk_fma_f32 v[46:47], v[100:101], v[32:33], v[46:47]
	v_mov_b32_dpp v66, v10 row_shr:1 row_mask:0xf bank_mask:0xf
	v_pk_fma_f32 v[36:37], v[96:97], v[36:37], v[46:47]
	v_pk_mul_f32 v[40:41], v[40:41], v[44:45]
	v_mov_b32_dpp v67, v11 row_shr:1 row_mask:0xf bank_mask:0xf
	v_pk_mul_f32 v[36:37], v[36:37], v[40:41]
	v_pk_fma_f32 v[40:41], v[26:27], v[122:123], v[126:127]
	v_mov_b32_dpp v42, v2 row_shr:1 row_mask:0xf bank_mask:0xf
	v_mov_b32_dpp v43, v3 row_shr:1 row_mask:0xf bank_mask:0xf
	v_pk_fma_f32 v[40:41], v[118:119], v[66:67], v[40:41]
	v_cvt_pk_bf16_f32 v146, v36, v37
	v_pk_fma_f32 v[40:41], v[114:115], v[42:43], v[40:41]
	v_mov_b32_dpp v34, v22 row_shr:1 row_mask:0xf bank_mask:0xf
	v_exp_f32_e32 v42, v40
	v_exp_f32_e32 v43, v41
	v_mov_b32_dpp v35, v23 row_shr:1 row_mask:0xf bank_mask:0xf
	v_pk_add_f32 v[42:43], v[42:43], 1.0 op_sel_hi:[1,0]
	v_rcp_f32_e32 v42, v42
	v_rcp_f32_e32 v43, v43
	v_pk_fma_f32 v[44:45], v[30:31], v[106:107], v[110:111]
	v_mov_b32_dpp v38, v14 row_shr:1 row_mask:0xf bank_mask:0xf
	v_mov_b32_dpp v39, v15 row_shr:1 row_mask:0xf bank_mask:0xf
	v_pk_fma_f32 v[44:45], v[102:103], v[34:35], v[44:45]
	v_pk_mul_f32 v[40:41], v[40:41], v[42:43]
	v_pk_fma_f32 v[38:39], v[98:99], v[38:39], v[44:45]
	v_pk_fma_f32 v[8:9], v[8:9], v[120:121], v[124:125]
	v_pk_mul_f32 v[38:39], v[38:39], v[40:41]
	v_pk_fma_f32 v[20:21], v[20:21], v[104:105], v[108:109]
	v_cvt_pk_bf16_f32 v147, v38, v39
	v_pk_fma_f32 v[38:39], v[4:5], v[120:121], v[124:125]
	global_store_dwordx4 v[132:133], v[144:147], off
	v_pk_fma_f32 v[38:39], v[24:25], v[116:117], v[38:39]
	s_and_b64 vcc, exec, s[12:13]
	v_pk_fma_f32 v[38:39], v[112:113], v[64:65], v[38:39]
	s_mov_b32 s35, s24
	v_exp_f32_e32 v36, v38
	v_exp_f32_e32 v37, v39
	s_mov_b32 s34, s26
	s_mov_b64 s[38:39], s[30:31]
	v_pk_add_f32 v[36:37], v[36:37], 1.0 op_sel_hi:[1,0]
	v_rcp_f32_e32 v36, v36
	v_rcp_f32_e32 v37, v37
	v_pk_fma_f32 v[40:41], v[16:17], v[104:105], v[108:109]
	s_mov_b64 s[36:37], s[28:29]
	v_pk_fma_f32 v[40:41], v[28:29], v[100:101], v[40:41]
	v_pk_mul_f32 v[36:37], v[38:39], v[36:37]
	v_pk_fma_f32 v[32:33], v[96:97], v[32:33], v[40:41]
	v_pk_fma_f32 v[40:41], v[18:19], v[106:107], v[110:111]
	v_pk_mul_f32 v[32:33], v[32:33], v[36:37]
	v_pk_fma_f32 v[36:37], v[6:7], v[122:123], v[126:127]
	v_cvt_pk_bf16_f32 v156, v32, v33
	v_pk_fma_f32 v[36:37], v[26:27], v[118:119], v[36:37]
	v_pk_fma_f32 v[40:41], v[30:31], v[102:103], v[40:41]
	v_pk_fma_f32 v[36:37], v[114:115], v[66:67], v[36:37]
	v_pk_fma_f32 v[34:35], v[98:99], v[34:35], v[40:41]
	v_exp_f32_e32 v38, v36
	v_exp_f32_e32 v39, v37
	s_nop 0
	v_pk_add_f32 v[38:39], v[38:39], 1.0 op_sel_hi:[1,0]
	v_rcp_f32_e32 v38, v38
	v_rcp_f32_e32 v39, v39
	s_nop 0
	v_pk_mul_f32 v[36:37], v[36:37], v[38:39]
	s_nop 0
	v_pk_mul_f32 v[34:35], v[34:35], v[36:37]
	s_nop 0
	v_cvt_pk_bf16_f32 v157, v34, v35
	v_pk_fma_f32 v[34:35], v[0:1], v[120:121], v[124:125]
	global_store_dwordx4 v[128:129], v[154:157], off
	v_pk_fma_f32 v[34:35], v[4:5], v[116:117], v[34:35]
	v_pk_fma_f32 v[0:1], v[0:1], v[116:117], v[8:9]
	v_pk_fma_f32 v[24:25], v[24:25], v[112:113], v[34:35]
	v_pk_fma_f32 v[0:1], v[4:5], v[112:113], v[0:1]
	v_exp_f32_e32 v32, v24
	v_exp_f32_e32 v33, v25
	v_exp_f32_e32 v8, v0
	v_pk_add_f32 v[32:33], v[32:33], 1.0 op_sel_hi:[1,0]
	v_rcp_f32_e32 v32, v32
	v_rcp_f32_e32 v33, v33
	v_pk_fma_f32 v[34:35], v[12:13], v[104:105], v[108:109]
	v_pk_fma_f32 v[4:5], v[10:11], v[122:123], v[126:127]
	v_pk_fma_f32 v[34:35], v[16:17], v[100:101], v[34:35]
	v_pk_mul_f32 v[24:25], v[24:25], v[32:33]
	v_pk_fma_f32 v[28:29], v[28:29], v[96:97], v[34:35]
	v_pk_mul_f32 v[24:25], v[28:29], v[24:25]
	v_pk_fma_f32 v[28:29], v[2:3], v[122:123], v[126:127]
	v_pk_fma_f32 v[2:3], v[2:3], v[118:119], v[4:5]
	v_pk_fma_f32 v[28:29], v[6:7], v[118:119], v[28:29]
	v_pk_fma_f32 v[2:3], v[6:7], v[114:115], v[2:3]
	v_pk_fma_f32 v[26:27], v[26:27], v[114:115], v[28:29]
	v_exp_f32_e32 v28, v26
	v_exp_f32_e32 v29, v27
	v_exp_f32_e32 v9, v1
	v_exp_f32_e32 v4, v2
	v_exp_f32_e32 v5, v3
	v_cvt_pk_bf16_f32 v200, v24, v25
	v_pk_add_f32 v[28:29], v[28:29], 1.0 op_sel_hi:[1,0]
	v_pk_add_f32 v[8:9], v[8:9], 1.0 op_sel_hi:[1,0]
	v_pk_add_f32 v[4:5], v[4:5], 1.0 op_sel_hi:[1,0]
	v_rcp_f32_e32 v28, v28
	v_rcp_f32_e32 v29, v29
	v_rcp_f32_e32 v8, v8
	v_rcp_f32_e32 v9, v9
	v_rcp_f32_e32 v4, v4
	v_rcp_f32_e32 v5, v5
	v_pk_fma_f32 v[32:33], v[14:15], v[106:107], v[110:111]
	v_pk_fma_f32 v[10:11], v[22:23], v[106:107], v[110:111]
	v_pk_fma_f32 v[32:33], v[18:19], v[102:103], v[32:33]
	v_pk_fma_f32 v[12:13], v[12:13], v[100:101], v[20:21]
	v_pk_fma_f32 v[6:7], v[14:15], v[102:103], v[10:11]
	v_pk_fma_f32 v[30:31], v[30:31], v[98:99], v[32:33]
	v_pk_mul_f32 v[26:27], v[26:27], v[28:29]
	v_pk_fma_f32 v[12:13], v[16:17], v[96:97], v[12:13]
	v_pk_mul_f32 v[0:1], v[0:1], v[8:9]
	v_pk_fma_f32 v[6:7], v[18:19], v[98:99], v[6:7]
	v_pk_mul_f32 v[2:3], v[2:3], v[4:5]
	v_pk_mul_f32 v[26:27], v[30:31], v[26:27]
	v_pk_mul_f32 v[0:1], v[12:13], v[0:1]
	v_pk_mul_f32 v[2:3], v[6:7], v[2:3]
	v_cvt_pk_bf16_f32 v201, v26, v27
	v_cvt_pk_bf16_f32 v150, v0, v1
	v_cvt_pk_bf16_f32 v151, v2, v3
	global_store_dwordx4 v[88:89], v[198:201], off
	global_store_dwordx4 v[82:83], v[148:151], off
	s_cbranch_vccnz .LBB0_324

; __device__ __forceinline__ float sigmoidf_(float x) { return __builtin_amdgcn_rcpf(1.0f + __expf(-x)); }
;     __device__ __forceinline__ void operator()(AccRef acc, const Unit& u, int wr, int wc, int fr, int fq) const {
;     ...
;                 float o[4][4];
; #pragma unroll
;                 for (int j = 0; j < 4; ++j) {
;                     const float v0 = acc[ai][0][0][n][j], v1 = acc[ai][0][1][n][j], v2 = acc[ai][0][2][n][j], v3 = acc[ai][0][3][n][j];
;                     const float g0 = acc[ai][1][0][n][j], g1 = acc[ai][1][1][n][j], g2 = acc[ai][1][2][n][j], g3 = acc[ai][1][3][n][j];
;                     const float pv3 = dpp_upd<0x111>(h3v[j], v3), pv2 = dpp_upd<0x111>(h2v[j], v2), pg3 = dpp_upd<0x111>(h3g[j], g3), pg2 = dpp_upd<0x111>(h2g[j], g2);
;                     const float hv0 = bvv[j] + w2v[j] * v0 + w1v[j] * pv3 + w0v[j] * pv2, hv1 = bvv[j] + w2v[j] * v1 + w1v[j] * v0 + w0v[j] * pv3;
;                     const float hv2 = bvv[j] + w2v[j] * v2 + w1v[j] * v1 + w0v[j] * v0, hv3 = bvv[j] + w2v[j] * v3 + w1v[j] * v2 + w0v[j] * v1;
;                     const float hg0 = bvg[j] + w2g[j] * g0 + w1g[j] * pg3 + w0g[j] * pg2, hg1 = bvg[j] + w2g[j] * g1 + w1g[j] * g0 + w0g[j] * pg3;
;                     const float hg2 = bvg[j] + w2g[j] * g2 + w1g[j] * g1 + w0g[j] * g0, hg3 = bvg[j] + w2g[j] * g3 + w1g[j] * g2 + w0g[j] * g1;
;                     o[0][j] = hg0 * sigmoidf_(hg0) * hv0; o[1][j] = hg1 * sigmoidf_(hg1) * hv1; o[2][j] = hg2 * sigmoidf_(hg2) * hv2; o[3][j] = hg3 * sigmoidf_(hg3) * hv3; }
; #pragma unroll
;                 for (int m = 0; m < 4; ++m) { u32x2 w; w.x = cvt_pk_bf16(o[m][0], o[m][1]); w.y = cvt_pk_bf16(o[m][2], o[m][3]);
;                     *(u32x2*)(Aout + (size_t)(row0 + ai * 128 + m) * FH + hc0 + 4 * n) = w; } } }
.LBB0_316:
	s_or_b64 exec, exec, s[40:41]
	v_pk_fma_f32 v[248:249], v[152:153], v[184:185], v[188:189]
	v_mov_b32_dpp v206, v128 row_shr:1 row_mask:0xf bank_mask:0xf
	v_mov_b32_dpp v207, v129 row_shr:1 row_mask:0xf bank_mask:0xf
	v_pk_fma_f32 v[248:249], v[180:181], v[198:199], v[248:249]
	v_mov_b32_dpp v194, v148 row_shr:1 row_mask:0xf bank_mask:0xf
	v_pk_fma_f32 v[206:207], v[176:177], v[206:207], v[248:249]
	v_mov_b32_dpp v195, v149 row_shr:1 row_mask:0xf bank_mask:0xf
	v_exp_f32_e32 v248, v206
	v_exp_f32_e32 v249, v207
	v_pk_fma_f32 v[250:251], v[156:157], v[168:169], v[172:173]
	v_pk_add_f32 v[248:249], v[248:249], 1.0 op_sel_hi:[1,0]
	v_rcp_f32_e32 v248, v248
	v_rcp_f32_e32 v249, v249
	v_mov_b32_dpp v202, v136 row_shr:1 row_mask:0xf bank_mask:0xf
	v_mov_b32_dpp v203, v137 row_shr:1 row_mask:0xf bank_mask:0xf
	v_pk_fma_f32 v[250:251], v[164:165], v[194:195], v[250:251]
	v_pk_mul_f32 v[206:207], v[206:207], v[248:249]
	v_pk_fma_f32 v[202:203], v[160:161], v[202:203], v[250:251]
	v_mov_b32_dpp v200, v142 row_shr:1 row_mask:0xf bank_mask:0xf
	v_mov_b32_dpp v201, v143 row_shr:1 row_mask:0xf bank_mask:0xf
	v_pk_mul_f32 v[202:203], v[202:203], v[206:207]
	v_pk_fma_f32 v[206:207], v[154:155], v[186:187], v[190:191]
	v_mov_b32_dpp v208, v130 row_shr:1 row_mask:0xf bank_mask:0xf
	v_mov_b32_dpp v209, v131 row_shr:1 row_mask:0xf bank_mask:0xf
	v_pk_fma_f32 v[206:207], v[182:183], v[200:201], v[206:207]
	v_mov_b32_dpp v196, v150 row_shr:1 row_mask:0xf bank_mask:0xf
	v_pk_fma_f32 v[206:207], v[178:179], v[208:209], v[206:207]
	v_mov_b32_dpp v197, v151 row_shr:1 row_mask:0xf bank_mask:0xf
	v_exp_f32_e32 v193, v206
	v_exp_f32_e32 v209, v207
	v_cvt_pk_bf16_f32 v247, v202, v203
	v_add_f32_e32 v193, 1.0, v193
	v_rcp_f32_e32 v202, v193
	v_add_f32_e32 v193, 1.0, v209
	v_rcp_f32_e32 v203, v193
	v_pk_fma_f32 v[248:249], v[158:159], v[170:171], v[174:175]
	v_mov_b32_dpp v204, v138 row_shr:1 row_mask:0xf bank_mask:0xf
	v_mov_b32_dpp v205, v139 row_shr:1 row_mask:0xf bank_mask:0xf
	v_pk_fma_f32 v[248:249], v[166:167], v[196:197], v[248:249]
	v_pk_mul_f32 v[202:203], v[206:207], v[202:203]
	v_pk_fma_f32 v[204:205], v[162:163], v[204:205], v[248:249]
	v_lshl_add_u32 v246, s34, 8, v236
	v_pk_mul_f32 v[202:203], v[204:205], v[202:203]
	v_lshlrev_b64 v[204:205], 1, v[232:233]
	v_pk_fma_f32 v[232:233], v[132:133], v[184:185], v[188:189]
	v_mov_b64_e32 v[206:207], s[60:61]
	v_pk_fma_f32 v[232:233], v[152:153], v[180:181], v[232:233]
	v_cvt_pk_bf16_f32 v248, v202, v203
	v_pk_fma_f32 v[198:199], v[176:177], v[198:199], v[232:233]
	v_mad_i64_i32 v[202:203], s[34:35], v246, s74, v[206:207]
	v_exp_f32_e32 v193, v198
	v_exp_f32_e32 v232, v199
	v_lshl_add_u64 v[202:203], v[202:203], 0, v[204:205]
	v_add_f32_e32 v193, 1.0, v193
	v_rcp_f32_e32 v208, v193
	v_add_f32_e32 v193, 1.0, v232
	v_rcp_f32_e32 v209, v193
	v_pk_fma_f32 v[232:233], v[144:145], v[168:169], v[172:173]
	v_pk_fma_f32 v[140:141], v[140:141], v[184:185], v[188:189]
	v_pk_fma_f32 v[232:233], v[156:157], v[164:165], v[232:233]
	v_pk_mul_f32 v[198:199], v[198:199], v[208:209]
	v_pk_fma_f32 v[194:195], v[160:161], v[194:195], v[232:233]
	v_pk_fma_f32 v[208:209], v[146:147], v[170:171], v[174:175]
	v_pk_mul_f32 v[194:195], v[194:195], v[198:199]
	v_pk_fma_f32 v[198:199], v[134:135], v[186:187], v[190:191]
	v_pk_fma_f32 v[208:209], v[158:159], v[166:167], v[208:209]
	v_pk_fma_f32 v[198:199], v[154:155], v[182:183], v[198:199]
	v_pk_fma_f32 v[196:197], v[162:163], v[196:197], v[208:209]
	v_pk_fma_f32 v[198:199], v[178:179], v[200:201], v[198:199]
	v_cvt_pk_bf16_f32 v249, v194, v195
	v_exp_f32_e32 v200, v198
	v_exp_f32_e32 v201, v199
	v_pk_fma_f32 v[148:149], v[148:149], v[168:169], v[172:173]
	v_pk_add_f32 v[200:201], v[200:201], 1.0 op_sel_hi:[1,0]
	v_rcp_f32_e32 v200, v200
	v_rcp_f32_e32 v201, v201
	v_or_b32_e32 v193, 1, v246
	v_pk_mul_f32 v[198:199], v[198:199], v[200:201]
	s_nop 0
	v_pk_mul_f32 v[196:197], v[196:197], v[198:199]
	v_pk_fma_f32 v[198:199], v[128:129], v[184:185], v[188:189]
	v_cvt_pk_bf16_f32 v250, v196, v197
	v_pk_fma_f32 v[198:199], v[132:133], v[180:181], v[198:199]
	v_mad_i64_i32 v[196:197], s[34:35], v193, s74, v[206:207]
	v_pk_fma_f32 v[152:153], v[152:153], v[176:177], v[198:199]
	v_lshl_add_u64 v[196:197], v[196:197], 0, v[204:205]
	v_exp_f32_e32 v193, v152
	v_exp_f32_e32 v198, v153
	v_add_f32_e32 v193, 1.0, v193
	v_rcp_f32_e32 v194, v193
	v_add_f32_e32 v193, 1.0, v198
	v_rcp_f32_e32 v195, v193
	v_pk_fma_f32 v[198:199], v[136:137], v[168:169], v[172:173]
	v_pk_fma_f32 v[128:129], v[128:129], v[180:181], v[140:141]
	v_pk_fma_f32 v[198:199], v[144:145], v[164:165], v[198:199]
	v_pk_fma_f32 v[128:129], v[132:133], v[176:177], v[128:129]
	v_pk_fma_f32 v[156:157], v[156:157], v[160:161], v[198:199]
	v_pk_mul_f32 v[152:153], v[152:153], v[194:195]
	v_pk_mul_f32 v[152:153], v[156:157], v[152:153]
	v_pk_fma_f32 v[156:157], v[130:131], v[186:187], v[190:191]
	v_exp_f32_e32 v140, v128
	v_pk_fma_f32 v[132:133], v[142:143], v[186:187], v[190:191]
	v_pk_fma_f32 v[156:157], v[134:135], v[182:183], v[156:157]
	v_pk_fma_f32 v[130:131], v[130:131], v[182:183], v[132:133]
	v_pk_fma_f32 v[154:155], v[154:155], v[178:179], v[156:157]
	v_pk_fma_f32 v[130:131], v[134:135], v[178:179], v[130:131]
	v_exp_f32_e32 v157, v154
	v_exp_f32_e32 v141, v129
	v_exp_f32_e32 v132, v130
	v_exp_f32_e32 v133, v131
	v_exp_f32_e32 v193, v155
	v_pk_add_f32 v[140:141], v[140:141], 1.0 op_sel_hi:[1,0]
	v_pk_add_f32 v[132:133], v[132:133], 1.0 op_sel_hi:[1,0]
	v_cvt_pk_bf16_f32 v254, v152, v153
	v_add_f32_e32 v152, 1.0, v157
	v_add_f32_e32 v153, 1.0, v193
	v_rcp_f32_e32 v140, v140
	v_rcp_f32_e32 v141, v141
	v_rcp_f32_e32 v132, v132
; #define LAS __attribute__((address_space(3)))
; __device__ __forceinline__ float sigmoidf_(float x) { return __builtin_amdgcn_rcpf(1.0f + __expf(-x)); }
;     __device__ __forceinline__ void operator()(AccRef acc, const Unit& u, int wr, int wc, int fr, int fq) const {
;     ...
;                 f32x4 h2v = (f32x4){0.f, 0.f, 0.f, 0.f}, h3v = h2v, h2g = h2v, h3g = h2v;
;                 const int pb = ai * 2 + wr - 1;
;                 if (pb >= 0 && fr == 0) { const LAS float* xp = xch + (pb * 2) * 256 + clb + 4 * n;
;                     h2v = *(const LAS f32x4*)(xp); h3v = *(const LAS f32x4*)(xp + 256); h2g = *(const LAS f32x4*)(xp + 128); h3g = *(const LAS f32x4*)(xp + 256 + 128); }
;                 float o[4][4];
; #pragma unroll
;                 for (int j = 0; j < 4; ++j) {
;                     const float v0 = acc[ai][0][0][n][j], v1 = acc[ai][0][1][n][j], v2 = acc[ai][0][2][n][j], v3 = acc[ai][0][3][n][j];
;                     const float g0 = acc[ai][1][0][n][j], g1 = acc[ai][1][1][n][j], g2 = acc[ai][1][2][n][j], g3 = acc[ai][1][3][n][j];
;                     const float pv3 = dpp_upd<0x111>(h3v[j], v3), pv2 = dpp_upd<0x111>(h2v[j], v2), pg3 = dpp_upd<0x111>(h3g[j], g3), pg2 = dpp_upd<0x111>(h2g[j], g2);
;                     const float hv0 = bvv[j] + w2v[j] * v0 + w1v[j] * pv3 + w0v[j] * pv2, hv1 = bvv[j] + w2v[j] * v1 + w1v[j] * v0 + w0v[j] * pv3;
;                     const float hv2 = bvv[j] + w2v[j] * v2 + w1v[j] * v1 + w0v[j] * v0, hv3 = bvv[j] + w2v[j] * v3 + w1v[j] * v2 + w0v[j] * v1;
;                     const float hg0 = bvg[j] + w2g[j] * g0 + w1g[j] * pg3 + w0g[j] * pg2, hg1 = bvg[j] + w2g[j] * g1 + w1g[j] * g0 + w0g[j] * pg3;
;                     const float hg2 = bvg[j] + w2g[j] * g2 + w1g[j] * g1 + w0g[j] * g0, hg3 = bvg[j] + w2g[j] * g3 + w1g[j] * g2 + w0g[j] * g1;
;                     o[0][j] = hg0 * sigmoidf_(hg0) * hv0; o[1][j] = hg1 * sigmoidf_(hg1) * hv1; o[2][j] = hg2 * sigmoidf_(hg2) * hv2; o[3][j] = hg3 * sigmoidf_(hg3) * hv3; }
; #pragma unroll
;                 for (int m = 0; m < 4; ++m) { u32x2 w; w.x = cvt_pk_bf16(o[m][0], o[m][1]); w.y = cvt_pk_bf16(o[m][2], o[m][3]);
;                     *(u32x2*)(Aout + (size_t)(row0 + ai * 128 + m) * FH + hc0 + 4 * n) = w; } } }
	v_rcp_f32_e32 v133, v133
	v_rcp_f32_e32 v152, v152
	v_rcp_f32_e32 v153, v153
	v_pk_fma_f32 v[142:143], v[150:151], v[170:171], v[174:175]
	v_pk_fma_f32 v[194:195], v[138:139], v[170:171], v[174:175]
	v_pk_fma_f32 v[136:137], v[136:137], v[164:165], v[148:149]
	v_pk_fma_f32 v[134:135], v[138:139], v[166:167], v[142:143]
	v_pk_fma_f32 v[194:195], v[146:147], v[166:167], v[194:195]
	v_pk_fma_f32 v[136:137], v[144:145], v[160:161], v[136:137]
	v_pk_mul_f32 v[128:129], v[128:129], v[140:141]
	v_pk_fma_f32 v[134:135], v[146:147], v[162:163], v[134:135]
	v_pk_mul_f32 v[130:131], v[130:131], v[132:133]
	v_pk_fma_f32 v[158:159], v[158:159], v[162:163], v[194:195]
	v_pk_mul_f32 v[152:153], v[154:155], v[152:153]
	v_pk_mul_f32 v[128:129], v[136:137], v[128:129]
	v_pk_mul_f32 v[130:131], v[134:135], v[130:131]
	v_pk_mul_f32 v[152:153], v[158:159], v[152:153]
	v_cvt_pk_bf16_f32 v251, v128, v129
	v_cvt_pk_bf16_f32 v253, v130, v131
	v_or_b32_e32 v130, 3, v246
	v_cvt_pk_bf16_f32 v255, v152, v153
	v_or_b32_e32 v152, 2, v246
	v_mad_i64_i32 v[130:131], s[34:35], v130, s74, v[206:207]
	v_mad_i64_i32 v[152:153], s[34:35], v152, s74, v[206:207]
	v_lshl_add_u64 v[140:141], v[130:131], 0, v[204:205]
	v_lshl_add_u64 v[152:153], v[152:153], 0, v[204:205]
	v_mov_b32_e32 v193, 0
	v_mov_b64_e32 v[194:195], 0
	v_mov_b64_e32 v[136:137], 0
	v_mov_b64_e32 v[138:139], 0
	v_mov_b64_e32 v[128:129], 0
	v_mov_b64_e32 v[130:131], 0
	v_mov_b64_e32 v[132:133], 0
	v_mov_b64_e32 v[134:135], 0
	s_and_saveexec_b64 s[34:35], s[22:23]
	s_cbranch_execz .LBB0_320
	ds_read_b128 v[132:135], v237 offset:2048
	ds_read_b128 v[136:139], v237 offset:2560
	ds_read_b128 v[128:131], v237 offset:3072
	ds_read_b128 v[192:195], v237 offset:3584
.LBB0_320:
	s_or_b64 exec, exec, s[34:35]
	s_waitcnt lgkmcnt(0)
	v_mov_b32_dpp v192, v72 row_shr:1 row_mask:0xf bank_mask:0xf
	v_mov_b32_dpp v193, v73 row_shr:1 row_mask:0xf bank_mask:0xf
	v_pk_fma_f32 v[142:143], v[88:89], v[184:185], v[188:189]
	v_mov_b32_dpp v136, v64 row_shr:1 row_mask:0xf bank_mask:0xf
	v_mov_b32_dpp v137, v65 row_shr:1 row_mask:0xf bank_mask:0xf
	v_pk_fma_f32 v[142:143], v[180:181], v[192:193], v[142:143]
	v_mov_b32_dpp v128, v84 row_shr:1 row_mask:0xf bank_mask:0xf
	v_pk_fma_f32 v[136:137], v[176:177], v[136:137], v[142:143]
	v_mov_b32_dpp v129, v85 row_shr:1 row_mask:0xf bank_mask:0xf
	v_exp_f32_e32 v142, v136
	v_exp_f32_e32 v143, v137
	v_pk_fma_f32 v[144:145], v[92:93], v[168:169], v[172:173]
	v_mov_b32_dpp v132, v76 row_shr:1 row_mask:0xf bank_mask:0xf
	v_pk_add_f32 v[142:143], v[142:143], 1.0 op_sel_hi:[1,0]
	v_rcp_f32_e32 v142, v142
	v_rcp_f32_e32 v143, v143
	v_mov_b32_dpp v133, v77 row_shr:1 row_mask:0xf bank_mask:0xf
	v_pk_fma_f32 v[144:145], v[164:165], v[128:129], v[144:145]
	v_mov_b32_dpp v194, v74 row_shr:1 row_mask:0xf bank_mask:0xf
	v_pk_fma_f32 v[132:133], v[160:161], v[132:133], v[144:145]
	v_pk_mul_f32 v[136:137], v[136:137], v[142:143]
	v_mov_b32_dpp v195, v75 row_shr:1 row_mask:0xf bank_mask:0xf
	v_pk_mul_f32 v[132:133], v[132:133], v[136:137]
	v_pk_fma_f32 v[136:137], v[90:91], v[186:187], v[190:191]
	v_mov_b32_dpp v138, v66 row_shr:1 row_mask:0xf bank_mask:0xf
	v_mov_b32_dpp v139, v67 row_shr:1 row_mask:0xf bank_mask:0xf
	v_pk_fma_f32 v[136:137], v[182:183], v[194:195], v[136:137]
	v_mov_b32_dpp v130, v86 row_shr:1 row_mask:0xf bank_mask:0xf
	v_pk_fma_f32 v[136:137], v[178:179], v[138:139], v[136:137]
	v_mov_b32_dpp v131, v87 row_shr:1 row_mask:0xf bank_mask:0xf
	v_exp_f32_e32 v139, v136
	v_exp_f32_e32 v142, v137
	v_cvt_pk_bf16_f32 v144, v132, v133
	v_add_f32_e32 v132, 1.0, v139
	v_rcp_f32_e32 v132, v132
	v_add_f32_e32 v133, 1.0, v142
	v_rcp_f32_e32 v133, v133
	v_pk_fma_f32 v[142:143], v[94:95], v[170:171], v[174:175]
	v_mov_b32_dpp v134, v78 row_shr:1 row_mask:0xf bank_mask:0xf
	v_mov_b32_dpp v135, v79 row_shr:1 row_mask:0xf bank_mask:0xf
	v_pk_mul_f32 v[132:133], v[136:137], v[132:133]
	v_pk_fma_f32 v[136:137], v[68:69], v[184:185], v[188:189]
	v_pk_fma_f32 v[142:143], v[166:167], v[130:131], v[142:143]
	v_pk_fma_f32 v[136:137], v[88:89], v[180:181], v[136:137]
	v_pk_fma_f32 v[134:135], v[162:163], v[134:135], v[142:143]
	v_pk_fma_f32 v[136:137], v[176:177], v[192:193], v[136:137]
	v_add_u32_e32 v146, 0x80, v246
	v_exp_f32_e32 v142, v136
	v_exp_f32_e32 v143, v137
	v_pk_mul_f32 v[132:133], v[134:135], v[132:133]
	v_mov_b64_e32 v[134:135], s[60:61]
	v_cvt_pk_bf16_f32 v145, v132, v133
	v_mad_i64_i32 v[132:133], s[34:35], v146, s74, v[134:135]
	v_lshl_add_u64 v[132:133], v[132:133], 0, v[204:205]
	v_add_f32_e32 v138, 1.0, v142
	v_add_f32_e32 v139, 1.0, v143
	v_rcp_f32_e32 v138, v138
	v_rcp_f32_e32 v139, v139
	v_pk_fma_f32 v[142:143], v[80:81], v[168:169], v[172:173]
	v_pk_fma_f32 v[72:73], v[72:73], v[184:185], v[188:189]
	v_pk_fma_f32 v[142:143], v[92:93], v[164:165], v[142:143]
	v_pk_mul_f32 v[136:137], v[136:137], v[138:139]
	v_pk_fma_f32 v[128:129], v[160:161], v[128:129], v[142:143]
	v_pk_fma_f32 v[84:85], v[84:85], v[168:169], v[172:173]
	v_pk_mul_f32 v[128:129], v[128:129], v[136:137]
	v_pk_fma_f32 v[136:137], v[70:71], v[186:187], v[190:191]
	s_nop 0
	v_pk_fma_f32 v[136:137], v[90:91], v[182:183], v[136:137]
	s_nop 0
	v_pk_fma_f32 v[136:137], v[178:179], v[194:195], v[136:137]
	s_nop 0
	v_exp_f32_e32 v139, v136
	v_exp_f32_e32 v142, v137
	v_cvt_pk_bf16_f32 v138, v128, v129
	v_add_f32_e32 v128, 1.0, v139
	v_rcp_f32_e32 v128, v128
	v_add_f32_e32 v129, 1.0, v142
	v_rcp_f32_e32 v129, v129
	v_pk_fma_f32 v[142:143], v[82:83], v[170:171], v[174:175]
	v_pk_mul_f32 v[128:129], v[136:137], v[128:129]
	v_pk_fma_f32 v[142:143], v[94:95], v[166:167], v[142:143]
	v_pk_fma_f32 v[136:137], v[76:77], v[168:169], v[172:173]
; #define LAS __attribute__((address_space(3)))
; __device__ __forceinline__ float sigmoidf_(float x) { return __builtin_amdgcn_rcpf(1.0f + __expf(-x)); }
;     __device__ __forceinline__ void operator()(AccRef acc, const Unit& u, int wr, int wc, int fr, int fq) const {
;     ...
;                 f32x4 h2v = (f32x4){0.f, 0.f, 0.f, 0.f}, h3v = h2v, h2g = h2v, h3g = h2v;
;                 const int pb = ai * 2 + wr - 1;
;                 if (pb >= 0 && fr == 0) { const LAS float* xp = xch + (pb * 2) * 256 + clb + 4 * n;
;                     h2v = *(const LAS f32x4*)(xp); h3v = *(const LAS f32x4*)(xp + 256); h2g = *(const LAS f32x4*)(xp + 128); h3g = *(const LAS f32x4*)(xp + 256 + 128); }
;                 float o[4][4];
; #pragma unroll
;                 for (int j = 0; j < 4; ++j) {
;                     const float v0 = acc[ai][0][0][n][j], v1 = acc[ai][0][1][n][j], v2 = acc[ai][0][2][n][j], v3 = acc[ai][0][3][n][j];
;                     const float g0 = acc[ai][1][0][n][j], g1 = acc[ai][1][1][n][j], g2 = acc[ai][1][2][n][j], g3 = acc[ai][1][3][n][j];
;                     const float pv3 = dpp_upd<0x111>(h3v[j], v3), pv2 = dpp_upd<0x111>(h2v[j], v2), pg3 = dpp_upd<0x111>(h3g[j], g3), pg2 = dpp_upd<0x111>(h2g[j], g2);
;                     const float hv0 = bvv[j] + w2v[j] * v0 + w1v[j] * pv3 + w0v[j] * pv2, hv1 = bvv[j] + w2v[j] * v1 + w1v[j] * v0 + w0v[j] * pv3;
;                     const float hv2 = bvv[j] + w2v[j] * v2 + w1v[j] * v1 + w0v[j] * v0, hv3 = bvv[j] + w2v[j] * v3 + w1v[j] * v2 + w0v[j] * v1;
;                     const float hg0 = bvg[j] + w2g[j] * g0 + w1g[j] * pg3 + w0g[j] * pg2, hg1 = bvg[j] + w2g[j] * g1 + w1g[j] * g0 + w0g[j] * pg3;
;                     const float hg2 = bvg[j] + w2g[j] * g2 + w1g[j] * g1 + w0g[j] * g0, hg3 = bvg[j] + w2g[j] * g3 + w1g[j] * g2 + w0g[j] * g1;
;                     o[0][j] = hg0 * sigmoidf_(hg0) * hv0; o[1][j] = hg1 * sigmoidf_(hg1) * hv1; o[2][j] = hg2 * sigmoidf_(hg2) * hv2; o[3][j] = hg3 * sigmoidf_(hg3) * hv3; }
; #pragma unroll
;                 for (int m = 0; m < 4; ++m) { u32x2 w; w.x = cvt_pk_bf16(o[m][0], o[m][1]); w.y = cvt_pk_bf16(o[m][2], o[m][3]);
;                     *(u32x2*)(Aout + (size_t)(row0 + ai * 128 + m) * FH + hc0 + 4 * n) = w; } } }
	v_pk_fma_f32 v[130:131], v[162:163], v[130:131], v[142:143]
	v_pk_fma_f32 v[136:137], v[80:81], v[164:165], v[136:137]
	v_pk_mul_f32 v[128:129], v[130:131], v[128:129]
	v_pk_fma_f32 v[130:131], v[64:65], v[184:185], v[188:189]
	v_pk_fma_f32 v[64:65], v[64:65], v[180:181], v[72:73]
	v_pk_fma_f32 v[130:131], v[68:69], v[180:181], v[130:131]
	v_pk_fma_f32 v[64:65], v[68:69], v[176:177], v[64:65]
	v_pk_fma_f32 v[88:89], v[88:89], v[176:177], v[130:131]
	v_pk_fma_f32 v[92:93], v[92:93], v[160:161], v[136:137]
	v_exp_f32_e32 v130, v88
	v_exp_f32_e32 v131, v89
	v_exp_f32_e32 v72, v64
	v_pk_add_f32 v[130:131], v[130:131], 1.0 op_sel_hi:[1,0]
	v_rcp_f32_e32 v130, v130
	v_rcp_f32_e32 v131, v131
	v_pk_fma_f32 v[68:69], v[74:75], v[186:187], v[190:191]
	v_exp_f32_e32 v73, v65
	v_pk_mul_f32 v[88:89], v[88:89], v[130:131]
	v_pk_mul_f32 v[88:89], v[92:93], v[88:89]
	v_pk_fma_f32 v[92:93], v[66:67], v[186:187], v[190:191]
	v_pk_fma_f32 v[66:67], v[66:67], v[182:183], v[68:69]
	v_pk_fma_f32 v[92:93], v[70:71], v[182:183], v[92:93]
	v_pk_fma_f32 v[66:67], v[70:71], v[178:179], v[66:67]
	v_pk_fma_f32 v[90:91], v[90:91], v[178:179], v[92:93]
	v_exp_f32_e32 v93, v90
	v_exp_f32_e32 v68, v66
	v_exp_f32_e32 v69, v67
	v_exp_f32_e32 v130, v91
	v_pk_add_f32 v[72:73], v[72:73], 1.0 op_sel_hi:[1,0]
	v_pk_add_f32 v[68:69], v[68:69], 1.0 op_sel_hi:[1,0]
	v_cvt_pk_bf16_f32 v198, v88, v89
	v_add_f32_e32 v88, 1.0, v93
	v_add_f32_e32 v89, 1.0, v130
	v_rcp_f32_e32 v72, v72
	v_rcp_f32_e32 v73, v73
	v_rcp_f32_e32 v68, v68
	v_rcp_f32_e32 v69, v69
	v_rcp_f32_e32 v88, v88
	v_rcp_f32_e32 v89, v89
	v_pk_fma_f32 v[74:75], v[86:87], v[170:171], v[174:175]
	v_pk_fma_f32 v[130:131], v[78:79], v[170:171], v[174:175]
	v_pk_fma_f32 v[76:77], v[76:77], v[164:165], v[84:85]
	v_pk_fma_f32 v[70:71], v[78:79], v[166:167], v[74:75]
	v_pk_fma_f32 v[130:131], v[82:83], v[166:167], v[130:131]
	v_pk_fma_f32 v[76:77], v[80:81], v[160:161], v[76:77]
	v_pk_mul_f32 v[64:65], v[64:65], v[72:73]
	v_pk_fma_f32 v[70:71], v[82:83], v[162:163], v[70:71]
	v_pk_mul_f32 v[66:67], v[66:67], v[68:69]
	v_pk_fma_f32 v[94:95], v[94:95], v[162:163], v[130:131]
	v_pk_mul_f32 v[88:89], v[90:91], v[88:89]
	v_pk_mul_f32 v[64:65], v[76:77], v[64:65]
	v_pk_mul_f32 v[66:67], v[70:71], v[66:67]
	v_pk_mul_f32 v[88:89], v[94:95], v[88:89]
	v_cvt_pk_bf16_f32 v148, v64, v65
	v_cvt_pk_bf16_f32 v149, v66, v67
	v_add_u32_e32 v66, 0x83, v246
	v_cvt_pk_bf16_f32 v155, v128, v129
	v_add_u32_e32 v128, 0x81, v246
	v_cvt_pk_bf16_f32 v199, v88, v89
	v_add_u32_e32 v88, 0x82, v246
	v_mad_i64_i32 v[66:67], s[34:35], v66, s74, v[134:135]
	v_mad_i64_i32 v[128:129], s[34:35], v128, s74, v[134:135]
	v_mad_i64_i32 v[88:89], s[34:35], v88, s74, v[134:135]
	v_lshl_add_u64 v[82:83], v[66:67], 0, v[204:205]
	v_lshl_add_u64 v[128:129], v[128:129], 0, v[204:205]
	v_lshl_add_u64 v[88:89], v[88:89], 0, v[204:205]
	v_mov_b32_e32 v64, 0
	v_mov_b64_e32 v[70:71], 0
	v_mov_b64_e32 v[72:73], 0
	v_mov_b64_e32 v[78:79], 0
	v_mov_b64_e32 v[80:81], 0
	v_mov_b64_e32 v[66:67], 0
	v_mov_b64_e32 v[68:69], 0
	v_mov_b64_e32 v[74:75], 0
	v_mov_b64_e32 v[76:77], 0
	v_mov_b32_e32 v154, v138
	s_and_saveexec_b64 s[34:35], s[18:19]
	s_cbranch_execz .LBB0_322
	ds_read_b128 v[74:77], v242
	ds_read_b128 v[66:69], v241
	ds_read_b128 v[78:81], v240
	ds_read_b128 v[70:73], v239
; #define LAS __attribute__((address_space(3)))
;     __device__ __forceinline__ void operator()(AccRef acc, const Unit& u, int wr, int wc, int fr, int fq) const {
;     ...
;         const int hc0 = 128 * u.pn + clb, row0 = u.pm * 256 + wr * 64 + 4 * fr;
; #pragma unroll
;         for (int n = 0; n < 2; ++n) {
;             const f32x4 w0v = cwv[n][0], w1v = cwv[n][1], w2v = cwv[n][2], bvv = cwv[n][3], w0g = cwv[n][4], w1g = cwv[n][5], w2g = cwv[n][6], bvg = cwv[n][7];
; #pragma unroll
;             for (int ai = 0; ai < 2; ++ai) {
;                 if (n == 0 && ai == 0) {
;                     asm volatile("" ::: "memory");
;                     const float* cv = cw + hc0 + 4; const float* cg = cv + FH; const float* bp = cb + hc0 + 4;
;                     cwv[1][0] = *(const f32x4*)(cv); cwv[1][1] = *(const f32x4*)(cv + F2); cwv[1][2] = *(const f32x4*)(cv + 2 * F2); cwv[1][3] = *(const f32x4*)(bp);
;                     cwv[1][4] = *(const f32x4*)(cg); cwv[1][5] = *(const f32x4*)(cg + F2); cwv[1][6] = *(const f32x4*)(cg + 2 * F2); cwv[1][7] = *(const f32x4*)(bp + FH);
;                     asm volatile("" ::: "memory"); }
;                 f32x4 h2v = (f32x4){0.f, 0.f, 0.f, 0.f}, h3v = h2v, h2g = h2v, h3g = h2v;
;                 const int pb = ai * 2 + wr - 1;
;                 if (pb >= 0 && fr == 0) { const LAS float* xp = xch + (pb * 2) * 256 + clb + 4 * n;
;                     h2v = *(const LAS f32x4*)(xp); h3v = *(const LAS f32x4*)(xp + 256); h2g = *(const LAS f32x4*)(xp + 128); h3g = *(const LAS f32x4*)(xp + 256 + 128); }
;                 float o[4][4];
; #pragma unroll
;                 for (int j = 0; j < 4; ++j) {
;                     const float v0 = acc[ai][0][0][n][j], v1 = acc[ai][0][1][n][j], v2 = acc[ai][0][2][n][j], v3 = acc[ai][0][3][n][j];
;                     const float g0 = acc[ai][1][0][n][j], g1 = acc[ai][1][1][n][j], g2 = acc[ai][1][2][n][j], g3 = acc[ai][1][3][n][j];
;                     const float pv3 = dpp_upd<0x111>(h3v[j], v3), pv2 = dpp_upd<0x111>(h2v[j], v2), pg3 = dpp_upd<0x111>(h3g[j], g3), pg2 = dpp_upd<0x111>(h2g[j], g2);
;                     const float hv0 = bvv[j] + w2v[j] * v0 + w1v[j] * pv3 + w0v[j] * pv2, hv1 = bvv[j] + w2v[j] * v1 + w1v[j] * v0 + w0v[j] * pv3;
;                     const float hv2 = bvv[j] + w2v[j] * v2 + w1v[j] * v1 + w0v[j] * v0, hv3 = bvv[j] + w2v[j] * v3 + w1v[j] * v2 + w0v[j] * v1;
.LBB0_322:
	s_or_b64 exec, exec, s[34:35]
	s_waitcnt lgkmcnt(0)
	v_mov_b32_dpp v70, v44 row_shr:1 row_mask:0xf bank_mask:0xf
	v_mov_b32_dpp v71, v45 row_shr:1 row_mask:0xf bank_mask:0xf
	s_waitcnt vmcnt(0)
	v_pk_fma_f32 v[84:85], v[56:57], v[120:121], v[124:125]
	v_mov_b32_dpp v78, v32 row_shr:1 row_mask:0xf bank_mask:0xf
	v_mov_b32_dpp v79, v33 row_shr:1 row_mask:0xf bank_mask:0xf
	v_pk_fma_f32 v[84:85], v[116:117], v[70:71], v[84:85]
	v_mov_b32_dpp v66, v52 row_shr:1 row_mask:0xf bank_mask:0xf
	v_pk_fma_f32 v[78:79], v[112:113], v[78:79], v[84:85]
	v_mov_b32_dpp v67, v53 row_shr:1 row_mask:0xf bank_mask:0xf
	v_exp_f32_e32 v84, v78
	v_exp_f32_e32 v85, v79
	v_pk_fma_f32 v[86:87], v[60:61], v[104:105], v[108:109]
	v_pk_add_f32 v[84:85], v[84:85], 1.0 op_sel_hi:[1,0]
	v_rcp_f32_e32 v84, v84
	v_rcp_f32_e32 v85, v85
	v_mov_b32_dpp v74, v40 row_shr:1 row_mask:0xf bank_mask:0xf
	v_mov_b32_dpp v75, v41 row_shr:1 row_mask:0xf bank_mask:0xf
	v_pk_fma_f32 v[86:87], v[100:101], v[66:67], v[86:87]
	v_pk_mul_f32 v[78:79], v[78:79], v[84:85]
	v_pk_fma_f32 v[74:75], v[96:97], v[74:75], v[86:87]
	v_mov_b32_dpp v72, v46 row_shr:1 row_mask:0xf bank_mask:0xf
	v_mov_b32_dpp v73, v47 row_shr:1 row_mask:0xf bank_mask:0xf
	v_pk_mul_f32 v[74:75], v[74:75], v[78:79]
	v_pk_fma_f32 v[78:79], v[58:59], v[122:123], v[126:127]
	v_mov_b32_dpp v80, v34 row_shr:1 row_mask:0xf bank_mask:0xf
	v_mov_b32_dpp v81, v35 row_shr:1 row_mask:0xf bank_mask:0xf
	v_pk_fma_f32 v[78:79], v[118:119], v[72:73], v[78:79]
	v_mov_b32_dpp v68, v54 row_shr:1 row_mask:0xf bank_mask:0xf
	v_pk_fma_f32 v[78:79], v[114:115], v[80:81], v[78:79]
	v_mov_b32_dpp v69, v55 row_shr:1 row_mask:0xf bank_mask:0xf
	v_exp_f32_e32 v80, v78
	v_exp_f32_e32 v81, v79
	v_pk_fma_f32 v[84:85], v[62:63], v[106:107], v[110:111]
	v_pk_add_f32 v[80:81], v[80:81], 1.0 op_sel_hi:[1,0]
	v_rcp_f32_e32 v80, v80
	v_rcp_f32_e32 v81, v81
	v_mov_b32_dpp v76, v42 row_shr:1 row_mask:0xf bank_mask:0xf
	v_mov_b32_dpp v77, v43 row_shr:1 row_mask:0xf bank_mask:0xf
	v_pk_fma_f32 v[84:85], v[102:103], v[68:69], v[84:85]
	v_pk_mul_f32 v[78:79], v[78:79], v[80:81]
	v_pk_fma_f32 v[76:77], v[98:99], v[76:77], v[84:85]
	v_cvt_pk_bf16_f32 v92, v74, v75
	v_pk_mul_f32 v[76:77], v[76:77], v[78:79]
	v_pk_fma_f32 v[44:45], v[44:45], v[120:121], v[124:125]
	v_cvt_pk_bf16_f32 v93, v76, v77
	v_pk_fma_f32 v[76:77], v[36:37], v[120:121], v[124:125]
	v_mov_b32_e32 v90, v247
	v_mov_b32_e32 v91, v248
	global_store_dwordx4 v[202:203], v[90:93], off
	v_pk_fma_f32 v[76:77], v[56:57], v[116:117], v[76:77]
	v_pk_fma_f32 v[52:53], v[52:53], v[104:105], v[108:109]
	v_pk_fma_f32 v[70:71], v[112:113], v[70:71], v[76:77]
	s_nop 0
	v_exp_f32_e32 v74, v70
	v_exp_f32_e32 v75, v71
	s_nop 0
	v_pk_add_f32 v[74:75], v[74:75], 1.0 op_sel_hi:[1,0]
	v_rcp_f32_e32 v74, v74
	v_rcp_f32_e32 v75, v75
	v_pk_fma_f32 v[76:77], v[48:49], v[104:105], v[108:109]
	v_pk_mul_f32 v[70:71], v[70:71], v[74:75]
	v_pk_fma_f32 v[76:77], v[60:61], v[100:101], v[76:77]
	v_pk_fma_f32 v[74:75], v[50:51], v[106:107], v[110:111]
	v_pk_fma_f32 v[66:67], v[96:97], v[66:67], v[76:77]
	v_pk_fma_f32 v[74:75], v[62:63], v[102:103], v[74:75]
	v_pk_mul_f32 v[66:67], v[66:67], v[70:71]
	v_pk_fma_f32 v[70:71], v[38:39], v[122:123], v[126:127]
	v_pk_fma_f32 v[68:69], v[98:99], v[68:69], v[74:75]
	v_pk_fma_f32 v[70:71], v[58:59], v[118:119], v[70:71]
	v_cvt_pk_bf16_f32 v136, v66, v67
	v_pk_fma_f32 v[70:71], v[114:115], v[72:73], v[70:71]
	s_nop 0
	v_exp_f32_e32 v72, v70
	v_exp_f32_e32 v73, v71
	s_nop 0
	v_pk_add_f32 v[72:73], v[72:73], 1.0 op_sel_hi:[1,0]
	v_rcp_f32_e32 v72, v72
	v_rcp_f32_e32 v73, v73
	s_nop 0
	v_pk_mul_f32 v[70:71], v[70:71], v[72:73]
	s_nop 0
	v_pk_mul_f32 v[68:69], v[68:69], v[70:71]
	s_nop 0
	v_cvt_pk_bf16_f32 v137, v68, v69
	v_pk_fma_f32 v[68:69], v[32:33], v[120:121], v[124:125]
	v_mov_b32_e32 v134, v249
	v_mov_b32_e32 v135, v250
	global_store_dwordx4 v[196:197], v[134:137], off
	v_pk_fma_f32 v[68:69], v[36:37], v[116:117], v[68:69]
	v_pk_fma_f32 v[32:33], v[32:33], v[116:117], v[44:45]
	v_pk_fma_f32 v[56:57], v[56:57], v[112:113], v[68:69]
	v_pk_fma_f32 v[32:33], v[36:37], v[112:113], v[32:33]
	v_exp_f32_e32 v66, v56
	v_exp_f32_e32 v67, v57
	s_nop 0
	v_pk_add_f32 v[66:67], v[66:67], 1.0 op_sel_hi:[1,0]
	v_rcp_f32_e32 v66, v66
	v_rcp_f32_e32 v67, v67
	v_pk_fma_f32 v[68:69], v[40:41], v[104:105], v[108:109]
	v_exp_f32_e32 v44, v32
	v_pk_fma_f32 v[68:69], v[48:49], v[100:101], v[68:69]
	v_pk_mul_f32 v[56:57], v[56:57], v[66:67]
	v_pk_fma_f32 v[60:61], v[60:61], v[96:97], v[68:69]
	v_pk_fma_f32 v[36:37], v[46:47], v[122:123], v[126:127]
	v_pk_mul_f32 v[56:57], v[60:61], v[56:57]
	v_pk_fma_f32 v[60:61], v[34:35], v[122:123], v[126:127]
	v_pk_fma_f32 v[34:35], v[34:35], v[118:119], v[36:37]
	v_pk_fma_f32 v[60:61], v[38:39], v[118:119], v[60:61]
	v_pk_fma_f32 v[34:35], v[38:39], v[114:115], v[34:35]
	v_pk_fma_f32 v[58:59], v[58:59], v[114:115], v[60:61]
	v_exp_f32_e32 v60, v58
	v_exp_f32_e32 v45, v33
	v_exp_f32_e32 v36, v34
	v_exp_f32_e32 v37, v35
	v_exp_f32_e32 v61, v59
	v_cvt_pk_bf16_f32 v164, v56, v57
	v_pk_add_f32 v[44:45], v[44:45], 1.0 op_sel_hi:[1,0]
	v_pk_add_f32 v[36:37], v[36:37], 1.0 op_sel_hi:[1,0]
	v_pk_add_f32 v[60:61], v[60:61], 1.0 op_sel_hi:[1,0]
	v_rcp_f32_e32 v44, v44
	v_rcp_f32_e32 v45, v45
	v_rcp_f32_e32 v36, v36
	v_rcp_f32_e32 v37, v37
	v_rcp_f32_e32 v60, v60
	v_rcp_f32_e32 v61, v61
	v_pk_fma_f32 v[46:47], v[54:55], v[106:107], v[110:111]
	v_pk_fma_f32 v[66:67], v[42:43], v[106:107], v[110:111]
	v_pk_fma_f32 v[40:41], v[40:41], v[100:101], v[52:53]
	v_pk_fma_f32 v[38:39], v[42:43], v[102:103], v[46:47]
	v_pk_fma_f32 v[66:67], v[50:51], v[102:103], v[66:67]
	v_pk_fma_f32 v[40:41], v[48:49], v[96:97], v[40:41]
	v_pk_mul_f32 v[32:33], v[32:33], v[44:45]
	v_pk_fma_f32 v[38:39], v[50:51], v[98:99], v[38:39]
	v_pk_mul_f32 v[34:35], v[34:35], v[36:37]
	v_pk_fma_f32 v[62:63], v[62:63], v[98:99], v[66:67]
	v_pk_mul_f32 v[58:59], v[58:59], v[60:61]
	v_pk_mul_f32 v[32:33], v[40:41], v[32:33]
	v_pk_mul_f32 v[34:35], v[38:39], v[34:35]
	v_pk_mul_f32 v[58:59], v[62:63], v[58:59]
	v_cvt_pk_bf16_f32 v160, v32, v33
	v_cvt_pk_bf16_f32 v161, v34, v35
	v_cvt_pk_bf16_f32 v57, v58, v59
	v_mov_b32_e32 v158, v251
	v_mov_b32_e32 v159, v253
	global_store_dwordx4 v[140:141], v[158:161], off
	v_mov_b32_e32 v65, 0
	v_mov_b64_e32 v[66:67], 0
	v_mov_b64_e32 v[40:41], 0
	v_mov_b64_e32 v[42:43], 0
	v_mov_b64_e32 v[32:33], 0
	v_mov_b64_e32 v[34:35], 0
	v_mov_b64_e32 v[36:37], 0
	v_mov_b64_e32 v[38:39], 0
	v_mov_b32_e32 v162, v254
	v_mov_b32_e32 v163, v255
	v_mov_b32_e32 v165, v57
	global_store_dwordx4 v[152:153], v[162:165], off
	s_and_saveexec_b64 s[34:35], s[22:23]
	s_cbranch_execz .LBB0_305
	ds_read_b128 v[36:39], v237 offset:2064
	ds_read_b128 v[40:43], v237 offset:2576
	ds_read_b128 v[32:35], v237 offset:3088
	ds_read_b128 v[64:67], v237 offset:3600
	s_branch .LBB0_305

; __device__ __forceinline__ float sigmoidf_(float x) { return __builtin_amdgcn_rcpf(1.0f + __expf(-x)); }
;     __device__ __forceinline__ void operator()(AccRef acc, const Unit& u, int wr, int wc, int fr, int fq) const {
;     ...
;                 float o[4][4];
; #pragma unroll
;                 for (int j = 0; j < 4; ++j) {
;                     const float v0 = acc[ai][0][0][n][j], v1 = acc[ai][0][1][n][j], v2 = acc[ai][0][2][n][j], v3 = acc[ai][0][3][n][j];
;                     const float g0 = acc[ai][1][0][n][j], g1 = acc[ai][1][1][n][j], g2 = acc[ai][1][2][n][j], g3 = acc[ai][1][3][n][j];
;                     const float pv3 = dpp_upd<0x111>(h3v[j], v3), pv2 = dpp_upd<0x111>(h2v[j], v2), pg3 = dpp_upd<0x111>(h3g[j], g3), pg2 = dpp_upd<0x111>(h2g[j], g2);
;                     const float hv0 = bvv[j] + w2v[j] * v0 + w1v[j] * pv3 + w0v[j] * pv2, hv1 = bvv[j] + w2v[j] * v1 + w1v[j] * v0 + w0v[j] * pv3;
;                     const float hv2 = bvv[j] + w2v[j] * v2 + w1v[j] * v1 + w0v[j] * v0, hv3 = bvv[j] + w2v[j] * v3 + w1v[j] * v2 + w0v[j] * v1;
;                     const float hg0 = bvg[j] + w2g[j] * g0 + w1g[j] * pg3 + w0g[j] * pg2, hg1 = bvg[j] + w2g[j] * g1 + w1g[j] * g0 + w0g[j] * pg3;
;                     const float hg2 = bvg[j] + w2g[j] * g2 + w1g[j] * g1 + w0g[j] * g0, hg3 = bvg[j] + w2g[j] * g3 + w1g[j] * g2 + w0g[j] * g1;
;                     o[0][j] = hg0 * sigmoidf_(hg0) * hv0; o[1][j] = hg1 * sigmoidf_(hg1) * hv1; o[2][j] = hg2 * sigmoidf_(hg2) * hv2; o[3][j] = hg3 * sigmoidf_(hg3) * hv3; }
; #pragma unroll
;                 for (int m = 0; m < 4; ++m) { u32x2 w; w.x = cvt_pk_bf16(o[m][0], o[m][1]); w.y = cvt_pk_bf16(o[m][2], o[m][3]);
;                     *(u32x2*)(Aout + (size_t)(row0 + ai * 128 + m) * FH + hc0 + 4 * n) = w; } } }
.LBB0_754:
	s_or_b64 exec, exec, s[40:41]
	s_waitcnt lgkmcnt(0)
	v_mov_b32_dpp v64, v8 row_shr:1 row_mask:0xf bank_mask:0xf
	v_mov_b32_dpp v65, v9 row_shr:1 row_mask:0xf bank_mask:0xf
	v_pk_fma_f32 v[44:45], v[24:25], v[120:121], v[124:125]
	v_mov_b32_dpp v40, v0 row_shr:1 row_mask:0xf bank_mask:0xf
	v_mov_b32_dpp v41, v1 row_shr:1 row_mask:0xf bank_mask:0xf
	v_pk_fma_f32 v[44:45], v[116:117], v[64:65], v[44:45]
	v_mov_b32_dpp v32, v20 row_shr:1 row_mask:0xf bank_mask:0xf
	v_pk_fma_f32 v[40:41], v[112:113], v[40:41], v[44:45]
	v_mov_b32_dpp v33, v21 row_shr:1 row_mask:0xf bank_mask:0xf
	v_exp_f32_e32 v44, v40
	v_exp_f32_e32 v45, v41
	v_pk_fma_f32 v[46:47], v[28:29], v[104:105], v[108:109]
	v_mov_b32_dpp v36, v12 row_shr:1 row_mask:0xf bank_mask:0xf
	v_pk_add_f32 v[44:45], v[44:45], 1.0 op_sel_hi:[1,0]
	v_rcp_f32_e32 v44, v44
	v_rcp_f32_e32 v45, v45
	v_mov_b32_dpp v37, v13 row_shr:1 row_mask:0xf bank_mask:0xf
	v_pk_fma_f32 v[46:47], v[100:101], v[32:33], v[46:47]
	v_mov_b32_dpp v66, v10 row_shr:1 row_mask:0xf bank_mask:0xf
	v_pk_fma_f32 v[36:37], v[96:97], v[36:37], v[46:47]
	v_pk_mul_f32 v[40:41], v[40:41], v[44:45]
	v_mov_b32_dpp v67, v11 row_shr:1 row_mask:0xf bank_mask:0xf
	v_pk_mul_f32 v[36:37], v[36:37], v[40:41]
	v_pk_fma_f32 v[40:41], v[26:27], v[122:123], v[126:127]
	v_mov_b32_dpp v42, v2 row_shr:1 row_mask:0xf bank_mask:0xf
	v_mov_b32_dpp v43, v3 row_shr:1 row_mask:0xf bank_mask:0xf
	v_pk_fma_f32 v[40:41], v[118:119], v[66:67], v[40:41]
	v_cvt_pk_bf16_f32 v146, v36, v37
	v_pk_fma_f32 v[40:41], v[114:115], v[42:43], v[40:41]
	v_mov_b32_dpp v34, v22 row_shr:1 row_mask:0xf bank_mask:0xf
	v_exp_f32_e32 v42, v40
	v_exp_f32_e32 v43, v41
	v_mov_b32_dpp v35, v23 row_shr:1 row_mask:0xf bank_mask:0xf
	v_pk_add_f32 v[42:43], v[42:43], 1.0 op_sel_hi:[1,0]
	v_rcp_f32_e32 v42, v42
	v_rcp_f32_e32 v43, v43
	v_pk_fma_f32 v[44:45], v[30:31], v[106:107], v[110:111]
	v_mov_b32_dpp v38, v14 row_shr:1 row_mask:0xf bank_mask:0xf
	v_mov_b32_dpp v39, v15 row_shr:1 row_mask:0xf bank_mask:0xf
	v_pk_fma_f32 v[44:45], v[102:103], v[34:35], v[44:45]
	v_pk_mul_f32 v[40:41], v[40:41], v[42:43]
	v_pk_fma_f32 v[38:39], v[98:99], v[38:39], v[44:45]
	v_pk_fma_f32 v[8:9], v[8:9], v[120:121], v[124:125]
	v_pk_mul_f32 v[38:39], v[38:39], v[40:41]
	v_pk_fma_f32 v[20:21], v[20:21], v[104:105], v[108:109]
	v_cvt_pk_bf16_f32 v147, v38, v39
	v_pk_fma_f32 v[38:39], v[4:5], v[120:121], v[124:125]
	global_store_dwordx4 v[132:133], v[144:147], off
	v_pk_fma_f32 v[38:39], v[24:25], v[116:117], v[38:39]
	s_and_b64 vcc, exec, s[14:15]
	v_pk_fma_f32 v[38:39], v[112:113], v[64:65], v[38:39]
	s_mov_b32 s41, s30
	v_exp_f32_e32 v36, v38
	v_exp_f32_e32 v37, v39
	s_mov_b32 s40, s34
	s_mov_b64 s[44:45], s[38:39]
	v_pk_add_f32 v[36:37], v[36:37], 1.0 op_sel_hi:[1,0]
	v_rcp_f32_e32 v36, v36
	v_rcp_f32_e32 v37, v37
	v_pk_fma_f32 v[40:41], v[16:17], v[104:105], v[108:109]
	s_mov_b64 s[42:43], s[36:37]
	v_pk_fma_f32 v[40:41], v[28:29], v[100:101], v[40:41]
	v_pk_mul_f32 v[36:37], v[38:39], v[36:37]
	v_pk_fma_f32 v[32:33], v[96:97], v[32:33], v[40:41]
	v_pk_fma_f32 v[40:41], v[18:19], v[106:107], v[110:111]
	v_pk_mul_f32 v[32:33], v[32:33], v[36:37]
	v_pk_fma_f32 v[36:37], v[6:7], v[122:123], v[126:127]
	v_cvt_pk_bf16_f32 v156, v32, v33
	v_pk_fma_f32 v[36:37], v[26:27], v[118:119], v[36:37]
	v_pk_fma_f32 v[40:41], v[30:31], v[102:103], v[40:41]
	v_pk_fma_f32 v[36:37], v[114:115], v[66:67], v[36:37]
	v_pk_fma_f32 v[34:35], v[98:99], v[34:35], v[40:41]
	v_exp_f32_e32 v38, v36
	v_exp_f32_e32 v39, v37
	s_nop 0
	v_pk_add_f32 v[38:39], v[38:39], 1.0 op_sel_hi:[1,0]
	v_rcp_f32_e32 v38, v38
	v_rcp_f32_e32 v39, v39
	s_nop 0
	v_pk_mul_f32 v[36:37], v[36:37], v[38:39]
	s_nop 0
	v_pk_mul_f32 v[34:35], v[34:35], v[36:37]
	s_nop 0
	v_cvt_pk_bf16_f32 v157, v34, v35
	v_pk_fma_f32 v[34:35], v[0:1], v[120:121], v[124:125]
	global_store_dwordx4 v[128:129], v[154:157], off
	v_pk_fma_f32 v[34:35], v[4:5], v[116:117], v[34:35]
	v_pk_fma_f32 v[0:1], v[0:1], v[116:117], v[8:9]
	v_pk_fma_f32 v[24:25], v[24:25], v[112:113], v[34:35]
	v_pk_fma_f32 v[0:1], v[4:5], v[112:113], v[0:1]
	v_exp_f32_e32 v32, v24
	v_exp_f32_e32 v33, v25
	v_exp_f32_e32 v8, v0
	v_pk_add_f32 v[32:33], v[32:33], 1.0 op_sel_hi:[1,0]
	v_rcp_f32_e32 v32, v32
	v_rcp_f32_e32 v33, v33
	v_pk_fma_f32 v[34:35], v[12:13], v[104:105], v[108:109]
	v_pk_fma_f32 v[4:5], v[10:11], v[122:123], v[126:127]
	v_pk_fma_f32 v[34:35], v[16:17], v[100:101], v[34:35]
	v_pk_mul_f32 v[24:25], v[24:25], v[32:33]
	v_pk_fma_f32 v[28:29], v[28:29], v[96:97], v[34:35]
	v_pk_mul_f32 v[24:25], v[28:29], v[24:25]
	v_pk_fma_f32 v[28:29], v[2:3], v[122:123], v[126:127]
	v_pk_fma_f32 v[2:3], v[2:3], v[118:119], v[4:5]
	v_pk_fma_f32 v[28:29], v[6:7], v[118:119], v[28:29]
	v_pk_fma_f32 v[2:3], v[6:7], v[114:115], v[2:3]
	v_pk_fma_f32 v[26:27], v[26:27], v[114:115], v[28:29]
	v_exp_f32_e32 v28, v26
	v_exp_f32_e32 v29, v27
	v_exp_f32_e32 v9, v1
	v_exp_f32_e32 v4, v2
	v_exp_f32_e32 v5, v3
	v_cvt_pk_bf16_f32 v200, v24, v25
	v_pk_add_f32 v[28:29], v[28:29], 1.0 op_sel_hi:[1,0]
	v_pk_add_f32 v[8:9], v[8:9], 1.0 op_sel_hi:[1,0]
	v_pk_add_f32 v[4:5], v[4:5], 1.0 op_sel_hi:[1,0]
	v_rcp_f32_e32 v28, v28
	v_rcp_f32_e32 v29, v29
	v_rcp_f32_e32 v8, v8
	v_rcp_f32_e32 v9, v9
	v_rcp_f32_e32 v4, v4
	v_rcp_f32_e32 v5, v5
	v_pk_fma_f32 v[32:33], v[14:15], v[106:107], v[110:111]
	v_pk_fma_f32 v[10:11], v[22:23], v[106:107], v[110:111]
	v_pk_fma_f32 v[32:33], v[18:19], v[102:103], v[32:33]
	v_pk_fma_f32 v[12:13], v[12:13], v[100:101], v[20:21]
	v_pk_fma_f32 v[6:7], v[14:15], v[102:103], v[10:11]
	v_pk_fma_f32 v[30:31], v[30:31], v[98:99], v[32:33]
	v_pk_mul_f32 v[26:27], v[26:27], v[28:29]
	v_pk_fma_f32 v[12:13], v[16:17], v[96:97], v[12:13]
	v_pk_mul_f32 v[0:1], v[0:1], v[8:9]
	v_pk_fma_f32 v[6:7], v[18:19], v[98:99], v[6:7]
	v_pk_mul_f32 v[2:3], v[2:3], v[4:5]
	v_pk_mul_f32 v[26:27], v[30:31], v[26:27]
	v_pk_mul_f32 v[0:1], v[12:13], v[0:1]
	v_pk_mul_f32 v[2:3], v[6:7], v[2:3]
	v_cvt_pk_bf16_f32 v201, v26, v27
	v_cvt_pk_bf16_f32 v150, v0, v1
	v_cvt_pk_bf16_f32 v151, v2, v3
	global_store_dwordx4 v[88:89], v[198:201], off
	global_store_dwordx4 v[82:83], v[148:151], off
	s_cbranch_vccnz .LBB0_773

; __device__ __forceinline__ float sigmoidf_(float x) { return __builtin_amdgcn_rcpf(1.0f + __expf(-x)); }
;     __device__ __forceinline__ void operator()(AccRef acc, const Unit& u, int wr, int wc, int fr, int fq) const {
;     ...
;                 float o[4][4];
; #pragma unroll
;                 for (int j = 0; j < 4; ++j) {
;                     const float v0 = acc[ai][0][0][n][j], v1 = acc[ai][0][1][n][j], v2 = acc[ai][0][2][n][j], v3 = acc[ai][0][3][n][j];
;                     const float g0 = acc[ai][1][0][n][j], g1 = acc[ai][1][1][n][j], g2 = acc[ai][1][2][n][j], g3 = acc[ai][1][3][n][j];
;                     const float pv3 = dpp_upd<0x111>(h3v[j], v3), pv2 = dpp_upd<0x111>(h2v[j], v2), pg3 = dpp_upd<0x111>(h3g[j], g3), pg2 = dpp_upd<0x111>(h2g[j], g2);
;                     const float hv0 = bvv[j] + w2v[j] * v0 + w1v[j] * pv3 + w0v[j] * pv2, hv1 = bvv[j] + w2v[j] * v1 + w1v[j] * v0 + w0v[j] * pv3;
;                     const float hv2 = bvv[j] + w2v[j] * v2 + w1v[j] * v1 + w0v[j] * v0, hv3 = bvv[j] + w2v[j] * v3 + w1v[j] * v2 + w0v[j] * v1;
;                     const float hg0 = bvg[j] + w2g[j] * g0 + w1g[j] * pg3 + w0g[j] * pg2, hg1 = bvg[j] + w2g[j] * g1 + w1g[j] * g0 + w0g[j] * pg3;
;                     const float hg2 = bvg[j] + w2g[j] * g2 + w1g[j] * g1 + w0g[j] * g0, hg3 = bvg[j] + w2g[j] * g3 + w1g[j] * g2 + w0g[j] * g1;
;                     o[0][j] = hg0 * sigmoidf_(hg0) * hv0; o[1][j] = hg1 * sigmoidf_(hg1) * hv1; o[2][j] = hg2 * sigmoidf_(hg2) * hv2; o[3][j] = hg3 * sigmoidf_(hg3) * hv3; }
; #pragma unroll
;                 for (int m = 0; m < 4; ++m) { u32x2 w; w.x = cvt_pk_bf16(o[m][0], o[m][1]); w.y = cvt_pk_bf16(o[m][2], o[m][3]);
;                     *(u32x2*)(Aout + (size_t)(row0 + ai * 128 + m) * FH + hc0 + 4 * n) = w; } } }
.LBB0_765:
	s_or_b64 exec, exec, s[46:47]
	v_pk_fma_f32 v[248:249], v[152:153], v[184:185], v[188:189]
	v_mov_b32_dpp v206, v128 row_shr:1 row_mask:0xf bank_mask:0xf
	v_mov_b32_dpp v207, v129 row_shr:1 row_mask:0xf bank_mask:0xf
	v_pk_fma_f32 v[248:249], v[180:181], v[198:199], v[248:249]
	v_mov_b32_dpp v194, v148 row_shr:1 row_mask:0xf bank_mask:0xf
	v_pk_fma_f32 v[206:207], v[176:177], v[206:207], v[248:249]
	v_mov_b32_dpp v195, v149 row_shr:1 row_mask:0xf bank_mask:0xf
	v_exp_f32_e32 v248, v206
	v_exp_f32_e32 v249, v207
	v_pk_fma_f32 v[250:251], v[156:157], v[168:169], v[172:173]
	v_pk_add_f32 v[248:249], v[248:249], 1.0 op_sel_hi:[1,0]
	v_rcp_f32_e32 v248, v248
	v_rcp_f32_e32 v249, v249
	v_mov_b32_dpp v202, v136 row_shr:1 row_mask:0xf bank_mask:0xf
	v_mov_b32_dpp v203, v137 row_shr:1 row_mask:0xf bank_mask:0xf
	v_pk_fma_f32 v[250:251], v[164:165], v[194:195], v[250:251]
	v_pk_mul_f32 v[206:207], v[206:207], v[248:249]
	v_pk_fma_f32 v[202:203], v[160:161], v[202:203], v[250:251]
	v_mov_b32_dpp v200, v142 row_shr:1 row_mask:0xf bank_mask:0xf
	v_mov_b32_dpp v201, v143 row_shr:1 row_mask:0xf bank_mask:0xf
	v_pk_mul_f32 v[202:203], v[202:203], v[206:207]
	v_pk_fma_f32 v[206:207], v[154:155], v[186:187], v[190:191]
	v_mov_b32_dpp v208, v130 row_shr:1 row_mask:0xf bank_mask:0xf
	v_mov_b32_dpp v209, v131 row_shr:1 row_mask:0xf bank_mask:0xf
	v_pk_fma_f32 v[206:207], v[182:183], v[200:201], v[206:207]
	v_mov_b32_dpp v196, v150 row_shr:1 row_mask:0xf bank_mask:0xf
	v_pk_fma_f32 v[206:207], v[178:179], v[208:209], v[206:207]
	v_mov_b32_dpp v197, v151 row_shr:1 row_mask:0xf bank_mask:0xf
	v_exp_f32_e32 v193, v206
	v_exp_f32_e32 v209, v207
	v_cvt_pk_bf16_f32 v247, v202, v203
	v_add_f32_e32 v193, 1.0, v193
	v_rcp_f32_e32 v202, v193
	v_add_f32_e32 v193, 1.0, v209
	v_rcp_f32_e32 v203, v193
	v_pk_fma_f32 v[248:249], v[158:159], v[170:171], v[174:175]
	v_mov_b32_dpp v204, v138 row_shr:1 row_mask:0xf bank_mask:0xf
	v_mov_b32_dpp v205, v139 row_shr:1 row_mask:0xf bank_mask:0xf
	v_pk_fma_f32 v[248:249], v[166:167], v[196:197], v[248:249]
	v_pk_mul_f32 v[202:203], v[206:207], v[202:203]
	v_pk_fma_f32 v[204:205], v[162:163], v[204:205], v[248:249]
	v_lshl_add_u32 v246, s40, 8, v236
	v_pk_mul_f32 v[202:203], v[204:205], v[202:203]
	v_lshlrev_b64 v[204:205], 1, v[232:233]
	v_pk_fma_f32 v[232:233], v[132:133], v[184:185], v[188:189]
	v_mov_b64_e32 v[206:207], s[60:61]
	v_pk_fma_f32 v[232:233], v[152:153], v[180:181], v[232:233]
	v_cvt_pk_bf16_f32 v248, v202, v203
	v_pk_fma_f32 v[198:199], v[176:177], v[198:199], v[232:233]
	v_mad_i64_i32 v[202:203], s[40:41], v246, s76, v[206:207]
	v_exp_f32_e32 v193, v198
	v_exp_f32_e32 v232, v199
	v_lshl_add_u64 v[202:203], v[202:203], 0, v[204:205]
	v_add_f32_e32 v193, 1.0, v193
	v_rcp_f32_e32 v208, v193
	v_add_f32_e32 v193, 1.0, v232
	v_rcp_f32_e32 v209, v193
	v_pk_fma_f32 v[232:233], v[144:145], v[168:169], v[172:173]
	v_pk_fma_f32 v[140:141], v[140:141], v[184:185], v[188:189]
	v_pk_fma_f32 v[232:233], v[156:157], v[164:165], v[232:233]
	v_pk_mul_f32 v[198:199], v[198:199], v[208:209]
	v_pk_fma_f32 v[194:195], v[160:161], v[194:195], v[232:233]
	v_pk_fma_f32 v[208:209], v[146:147], v[170:171], v[174:175]
	v_pk_mul_f32 v[194:195], v[194:195], v[198:199]
	v_pk_fma_f32 v[198:199], v[134:135], v[186:187], v[190:191]
	v_pk_fma_f32 v[208:209], v[158:159], v[166:167], v[208:209]
	v_pk_fma_f32 v[198:199], v[154:155], v[182:183], v[198:199]
	v_pk_fma_f32 v[196:197], v[162:163], v[196:197], v[208:209]
	v_pk_fma_f32 v[198:199], v[178:179], v[200:201], v[198:199]
	v_cvt_pk_bf16_f32 v249, v194, v195
	v_exp_f32_e32 v200, v198
	v_exp_f32_e32 v201, v199
	v_pk_fma_f32 v[148:149], v[148:149], v[168:169], v[172:173]
	v_pk_add_f32 v[200:201], v[200:201], 1.0 op_sel_hi:[1,0]
	v_rcp_f32_e32 v200, v200
	v_rcp_f32_e32 v201, v201
	v_or_b32_e32 v193, 1, v246
	v_pk_mul_f32 v[198:199], v[198:199], v[200:201]
	s_nop 0
	v_pk_mul_f32 v[196:197], v[196:197], v[198:199]
	v_pk_fma_f32 v[198:199], v[128:129], v[184:185], v[188:189]
	v_cvt_pk_bf16_f32 v250, v196, v197
	v_pk_fma_f32 v[198:199], v[132:133], v[180:181], v[198:199]
	v_mad_i64_i32 v[196:197], s[40:41], v193, s76, v[206:207]
	v_pk_fma_f32 v[152:153], v[152:153], v[176:177], v[198:199]
	v_lshl_add_u64 v[196:197], v[196:197], 0, v[204:205]
	v_exp_f32_e32 v193, v152
	v_exp_f32_e32 v198, v153
	v_add_f32_e32 v193, 1.0, v193
	v_rcp_f32_e32 v194, v193
	v_add_f32_e32 v193, 1.0, v198
	v_rcp_f32_e32 v195, v193
	v_pk_fma_f32 v[198:199], v[136:137], v[168:169], v[172:173]
	v_pk_fma_f32 v[128:129], v[128:129], v[180:181], v[140:141]
	v_pk_fma_f32 v[198:199], v[144:145], v[164:165], v[198:199]
	v_pk_fma_f32 v[128:129], v[132:133], v[176:177], v[128:129]
	v_pk_fma_f32 v[156:157], v[156:157], v[160:161], v[198:199]
	v_pk_mul_f32 v[152:153], v[152:153], v[194:195]
	v_pk_mul_f32 v[152:153], v[156:157], v[152:153]
	v_pk_fma_f32 v[156:157], v[130:131], v[186:187], v[190:191]
	v_exp_f32_e32 v140, v128
	v_pk_fma_f32 v[132:133], v[142:143], v[186:187], v[190:191]
	v_pk_fma_f32 v[156:157], v[134:135], v[182:183], v[156:157]
	v_pk_fma_f32 v[130:131], v[130:131], v[182:183], v[132:133]
	v_pk_fma_f32 v[154:155], v[154:155], v[178:179], v[156:157]
	v_pk_fma_f32 v[130:131], v[134:135], v[178:179], v[130:131]
	v_exp_f32_e32 v157, v154
	v_exp_f32_e32 v141, v129
	v_exp_f32_e32 v132, v130
	v_exp_f32_e32 v133, v131
	v_exp_f32_e32 v193, v155
	v_pk_add_f32 v[140:141], v[140:141], 1.0 op_sel_hi:[1,0]
	v_pk_add_f32 v[132:133], v[132:133], 1.0 op_sel_hi:[1,0]
	v_cvt_pk_bf16_f32 v254, v152, v153
	v_add_f32_e32 v152, 1.0, v157
	v_add_f32_e32 v153, 1.0, v193
	v_rcp_f32_e32 v140, v140
	v_rcp_f32_e32 v141, v141
	v_rcp_f32_e32 v132, v132
; #define LAS __attribute__((address_space(3)))
; __device__ __forceinline__ float sigmoidf_(float x) { return __builtin_amdgcn_rcpf(1.0f + __expf(-x)); }
;     __device__ __forceinline__ void operator()(AccRef acc, const Unit& u, int wr, int wc, int fr, int fq) const {
;     ...
;                 f32x4 h2v = (f32x4){0.f, 0.f, 0.f, 0.f}, h3v = h2v, h2g = h2v, h3g = h2v;
;                 const int pb = ai * 2 + wr - 1;
;                 if (pb >= 0 && fr == 0) { const LAS float* xp = xch + (pb * 2) * 256 + clb + 4 * n;
;                     h2v = *(const LAS f32x4*)(xp); h3v = *(const LAS f32x4*)(xp + 256); h2g = *(const LAS f32x4*)(xp + 128); h3g = *(const LAS f32x4*)(xp + 256 + 128); }
;                 float o[4][4];
; #pragma unroll
;                 for (int j = 0; j < 4; ++j) {
;                     const float v0 = acc[ai][0][0][n][j], v1 = acc[ai][0][1][n][j], v2 = acc[ai][0][2][n][j], v3 = acc[ai][0][3][n][j];
;                     const float g0 = acc[ai][1][0][n][j], g1 = acc[ai][1][1][n][j], g2 = acc[ai][1][2][n][j], g3 = acc[ai][1][3][n][j];
;                     const float pv3 = dpp_upd<0x111>(h3v[j], v3), pv2 = dpp_upd<0x111>(h2v[j], v2), pg3 = dpp_upd<0x111>(h3g[j], g3), pg2 = dpp_upd<0x111>(h2g[j], g2);
;                     const float hv0 = bvv[j] + w2v[j] * v0 + w1v[j] * pv3 + w0v[j] * pv2, hv1 = bvv[j] + w2v[j] * v1 + w1v[j] * v0 + w0v[j] * pv3;
;                     const float hv2 = bvv[j] + w2v[j] * v2 + w1v[j] * v1 + w0v[j] * v0, hv3 = bvv[j] + w2v[j] * v3 + w1v[j] * v2 + w0v[j] * v1;
;                     const float hg0 = bvg[j] + w2g[j] * g0 + w1g[j] * pg3 + w0g[j] * pg2, hg1 = bvg[j] + w2g[j] * g1 + w1g[j] * g0 + w0g[j] * pg3;
;                     const float hg2 = bvg[j] + w2g[j] * g2 + w1g[j] * g1 + w0g[j] * g0, hg3 = bvg[j] + w2g[j] * g3 + w1g[j] * g2 + w0g[j] * g1;
;                     o[0][j] = hg0 * sigmoidf_(hg0) * hv0; o[1][j] = hg1 * sigmoidf_(hg1) * hv1; o[2][j] = hg2 * sigmoidf_(hg2) * hv2; o[3][j] = hg3 * sigmoidf_(hg3) * hv3; }
; #pragma unroll
;                 for (int m = 0; m < 4; ++m) { u32x2 w; w.x = cvt_pk_bf16(o[m][0], o[m][1]); w.y = cvt_pk_bf16(o[m][2], o[m][3]);
;                     *(u32x2*)(Aout + (size_t)(row0 + ai * 128 + m) * FH + hc0 + 4 * n) = w; } } }
	v_rcp_f32_e32 v133, v133
	v_rcp_f32_e32 v152, v152
	v_rcp_f32_e32 v153, v153
	v_pk_fma_f32 v[142:143], v[150:151], v[170:171], v[174:175]
	v_pk_fma_f32 v[194:195], v[138:139], v[170:171], v[174:175]
	v_pk_fma_f32 v[136:137], v[136:137], v[164:165], v[148:149]
	v_pk_fma_f32 v[134:135], v[138:139], v[166:167], v[142:143]
	v_pk_fma_f32 v[194:195], v[146:147], v[166:167], v[194:195]
	v_pk_fma_f32 v[136:137], v[144:145], v[160:161], v[136:137]
	v_pk_mul_f32 v[128:129], v[128:129], v[140:141]
	v_pk_fma_f32 v[134:135], v[146:147], v[162:163], v[134:135]
	v_pk_mul_f32 v[130:131], v[130:131], v[132:133]
	v_pk_fma_f32 v[158:159], v[158:159], v[162:163], v[194:195]
	v_pk_mul_f32 v[152:153], v[154:155], v[152:153]
	v_pk_mul_f32 v[128:129], v[136:137], v[128:129]
	v_pk_mul_f32 v[130:131], v[134:135], v[130:131]
	v_pk_mul_f32 v[152:153], v[158:159], v[152:153]
	v_cvt_pk_bf16_f32 v251, v128, v129
	v_cvt_pk_bf16_f32 v253, v130, v131
	v_or_b32_e32 v130, 3, v246
	v_cvt_pk_bf16_f32 v255, v152, v153
	v_or_b32_e32 v152, 2, v246
	v_mad_i64_i32 v[130:131], s[40:41], v130, s76, v[206:207]
	v_mad_i64_i32 v[152:153], s[40:41], v152, s76, v[206:207]
	v_lshl_add_u64 v[140:141], v[130:131], 0, v[204:205]
	v_lshl_add_u64 v[152:153], v[152:153], 0, v[204:205]
	v_mov_b32_e32 v193, 0
	v_mov_b64_e32 v[194:195], 0
	v_mov_b64_e32 v[136:137], 0
	v_mov_b64_e32 v[138:139], 0
	v_mov_b64_e32 v[128:129], 0
	v_mov_b64_e32 v[130:131], 0
	v_mov_b64_e32 v[132:133], 0
	v_mov_b64_e32 v[134:135], 0
	s_and_saveexec_b64 s[40:41], s[28:29]
	s_cbranch_execz .LBB0_769
	ds_read_b128 v[132:135], v237 offset:2048
	ds_read_b128 v[136:139], v237 offset:2560
	ds_read_b128 v[128:131], v237 offset:3072
	ds_read_b128 v[192:195], v237 offset:3584
.LBB0_769:
	s_or_b64 exec, exec, s[40:41]
	s_waitcnt lgkmcnt(0)
	v_mov_b32_dpp v192, v72 row_shr:1 row_mask:0xf bank_mask:0xf
	v_mov_b32_dpp v193, v73 row_shr:1 row_mask:0xf bank_mask:0xf
	v_pk_fma_f32 v[142:143], v[88:89], v[184:185], v[188:189]
	v_mov_b32_dpp v136, v64 row_shr:1 row_mask:0xf bank_mask:0xf
	v_mov_b32_dpp v137, v65 row_shr:1 row_mask:0xf bank_mask:0xf
	v_pk_fma_f32 v[142:143], v[180:181], v[192:193], v[142:143]
	v_mov_b32_dpp v128, v84 row_shr:1 row_mask:0xf bank_mask:0xf
	v_pk_fma_f32 v[136:137], v[176:177], v[136:137], v[142:143]
	v_mov_b32_dpp v129, v85 row_shr:1 row_mask:0xf bank_mask:0xf
	v_exp_f32_e32 v142, v136
	v_exp_f32_e32 v143, v137
	v_pk_fma_f32 v[144:145], v[92:93], v[168:169], v[172:173]
	v_mov_b32_dpp v132, v76 row_shr:1 row_mask:0xf bank_mask:0xf
	v_pk_add_f32 v[142:143], v[142:143], 1.0 op_sel_hi:[1,0]
	v_rcp_f32_e32 v142, v142
	v_rcp_f32_e32 v143, v143
	v_mov_b32_dpp v133, v77 row_shr:1 row_mask:0xf bank_mask:0xf
	v_pk_fma_f32 v[144:145], v[164:165], v[128:129], v[144:145]
	v_mov_b32_dpp v194, v74 row_shr:1 row_mask:0xf bank_mask:0xf
	v_pk_fma_f32 v[132:133], v[160:161], v[132:133], v[144:145]
	v_pk_mul_f32 v[136:137], v[136:137], v[142:143]
	v_mov_b32_dpp v195, v75 row_shr:1 row_mask:0xf bank_mask:0xf
	v_pk_mul_f32 v[132:133], v[132:133], v[136:137]
	v_pk_fma_f32 v[136:137], v[90:91], v[186:187], v[190:191]
	v_mov_b32_dpp v138, v66 row_shr:1 row_mask:0xf bank_mask:0xf
	v_mov_b32_dpp v139, v67 row_shr:1 row_mask:0xf bank_mask:0xf
	v_pk_fma_f32 v[136:137], v[182:183], v[194:195], v[136:137]
	v_mov_b32_dpp v130, v86 row_shr:1 row_mask:0xf bank_mask:0xf
	v_pk_fma_f32 v[136:137], v[178:179], v[138:139], v[136:137]
	v_mov_b32_dpp v131, v87 row_shr:1 row_mask:0xf bank_mask:0xf
	v_exp_f32_e32 v139, v136
	v_exp_f32_e32 v142, v137
	v_cvt_pk_bf16_f32 v144, v132, v133
	v_add_f32_e32 v132, 1.0, v139
	v_rcp_f32_e32 v132, v132
	v_add_f32_e32 v133, 1.0, v142
	v_rcp_f32_e32 v133, v133
	v_pk_fma_f32 v[142:143], v[94:95], v[170:171], v[174:175]
	v_mov_b32_dpp v134, v78 row_shr:1 row_mask:0xf bank_mask:0xf
	v_mov_b32_dpp v135, v79 row_shr:1 row_mask:0xf bank_mask:0xf
	v_pk_mul_f32 v[132:133], v[136:137], v[132:133]
	v_pk_fma_f32 v[136:137], v[68:69], v[184:185], v[188:189]
	v_pk_fma_f32 v[142:143], v[166:167], v[130:131], v[142:143]
	v_pk_fma_f32 v[136:137], v[88:89], v[180:181], v[136:137]
	v_pk_fma_f32 v[134:135], v[162:163], v[134:135], v[142:143]
	v_pk_fma_f32 v[136:137], v[176:177], v[192:193], v[136:137]
	v_add_u32_e32 v146, 0x80, v246
	v_exp_f32_e32 v142, v136
	v_exp_f32_e32 v143, v137
	v_pk_mul_f32 v[132:133], v[134:135], v[132:133]
	v_mov_b64_e32 v[134:135], s[60:61]
	v_cvt_pk_bf16_f32 v145, v132, v133
	v_mad_i64_i32 v[132:133], s[40:41], v146, s76, v[134:135]
	v_lshl_add_u64 v[132:133], v[132:133], 0, v[204:205]
	v_add_f32_e32 v138, 1.0, v142
	v_add_f32_e32 v139, 1.0, v143
	v_rcp_f32_e32 v138, v138
	v_rcp_f32_e32 v139, v139
	v_pk_fma_f32 v[142:143], v[80:81], v[168:169], v[172:173]
	v_pk_fma_f32 v[72:73], v[72:73], v[184:185], v[188:189]
	v_pk_fma_f32 v[142:143], v[92:93], v[164:165], v[142:143]
	v_pk_mul_f32 v[136:137], v[136:137], v[138:139]
	v_pk_fma_f32 v[128:129], v[160:161], v[128:129], v[142:143]
	v_pk_fma_f32 v[84:85], v[84:85], v[168:169], v[172:173]
	v_pk_mul_f32 v[128:129], v[128:129], v[136:137]
	v_pk_fma_f32 v[136:137], v[70:71], v[186:187], v[190:191]
	s_nop 0
	v_pk_fma_f32 v[136:137], v[90:91], v[182:183], v[136:137]
	s_nop 0
	v_pk_fma_f32 v[136:137], v[178:179], v[194:195], v[136:137]
	s_nop 0
	v_exp_f32_e32 v139, v136
	v_exp_f32_e32 v142, v137
	v_cvt_pk_bf16_f32 v138, v128, v129
	v_add_f32_e32 v128, 1.0, v139
	v_rcp_f32_e32 v128, v128
	v_add_f32_e32 v129, 1.0, v142
	v_rcp_f32_e32 v129, v129
	v_pk_fma_f32 v[142:143], v[82:83], v[170:171], v[174:175]
	v_pk_mul_f32 v[128:129], v[136:137], v[128:129]
	v_pk_fma_f32 v[142:143], v[94:95], v[166:167], v[142:143]
	v_pk_fma_f32 v[136:137], v[76:77], v[168:169], v[172:173]
; #define LAS __attribute__((address_space(3)))
; __device__ __forceinline__ float sigmoidf_(float x) { return __builtin_amdgcn_rcpf(1.0f + __expf(-x)); }
;     __device__ __forceinline__ void operator()(AccRef acc, const Unit& u, int wr, int wc, int fr, int fq) const {
;     ...
;                 f32x4 h2v = (f32x4){0.f, 0.f, 0.f, 0.f}, h3v = h2v, h2g = h2v, h3g = h2v;
;                 const int pb = ai * 2 + wr - 1;
;                 if (pb >= 0 && fr == 0) { const LAS float* xp = xch + (pb * 2) * 256 + clb + 4 * n;
;                     h2v = *(const LAS f32x4*)(xp); h3v = *(const LAS f32x4*)(xp + 256); h2g = *(const LAS f32x4*)(xp + 128); h3g = *(const LAS f32x4*)(xp + 256 + 128); }
;                 float o[4][4];
; #pragma unroll
;                 for (int j = 0; j < 4; ++j) {
;                     const float v0 = acc[ai][0][0][n][j], v1 = acc[ai][0][1][n][j], v2 = acc[ai][0][2][n][j], v3 = acc[ai][0][3][n][j];
;                     const float g0 = acc[ai][1][0][n][j], g1 = acc[ai][1][1][n][j], g2 = acc[ai][1][2][n][j], g3 = acc[ai][1][3][n][j];
;                     const float pv3 = dpp_upd<0x111>(h3v[j], v3), pv2 = dpp_upd<0x111>(h2v[j], v2), pg3 = dpp_upd<0x111>(h3g[j], g3), pg2 = dpp_upd<0x111>(h2g[j], g2);
;                     const float hv0 = bvv[j] + w2v[j] * v0 + w1v[j] * pv3 + w0v[j] * pv2, hv1 = bvv[j] + w2v[j] * v1 + w1v[j] * v0 + w0v[j] * pv3;
;                     const float hv2 = bvv[j] + w2v[j] * v2 + w1v[j] * v1 + w0v[j] * v0, hv3 = bvv[j] + w2v[j] * v3 + w1v[j] * v2 + w0v[j] * v1;
;                     const float hg0 = bvg[j] + w2g[j] * g0 + w1g[j] * pg3 + w0g[j] * pg2, hg1 = bvg[j] + w2g[j] * g1 + w1g[j] * g0 + w0g[j] * pg3;
;                     const float hg2 = bvg[j] + w2g[j] * g2 + w1g[j] * g1 + w0g[j] * g0, hg3 = bvg[j] + w2g[j] * g3 + w1g[j] * g2 + w0g[j] * g1;
;                     o[0][j] = hg0 * sigmoidf_(hg0) * hv0; o[1][j] = hg1 * sigmoidf_(hg1) * hv1; o[2][j] = hg2 * sigmoidf_(hg2) * hv2; o[3][j] = hg3 * sigmoidf_(hg3) * hv3; }
; #pragma unroll
;                 for (int m = 0; m < 4; ++m) { u32x2 w; w.x = cvt_pk_bf16(o[m][0], o[m][1]); w.y = cvt_pk_bf16(o[m][2], o[m][3]);
;                     *(u32x2*)(Aout + (size_t)(row0 + ai * 128 + m) * FH + hc0 + 4 * n) = w; } } }
	v_pk_fma_f32 v[130:131], v[162:163], v[130:131], v[142:143]
	v_pk_fma_f32 v[136:137], v[80:81], v[164:165], v[136:137]
	v_pk_mul_f32 v[128:129], v[130:131], v[128:129]
	v_pk_fma_f32 v[130:131], v[64:65], v[184:185], v[188:189]
	v_pk_fma_f32 v[64:65], v[64:65], v[180:181], v[72:73]
	v_pk_fma_f32 v[130:131], v[68:69], v[180:181], v[130:131]
	v_pk_fma_f32 v[64:65], v[68:69], v[176:177], v[64:65]
	v_pk_fma_f32 v[88:89], v[88:89], v[176:177], v[130:131]
	v_pk_fma_f32 v[92:93], v[92:93], v[160:161], v[136:137]
	v_exp_f32_e32 v130, v88
	v_exp_f32_e32 v131, v89
	v_exp_f32_e32 v72, v64
	v_pk_add_f32 v[130:131], v[130:131], 1.0 op_sel_hi:[1,0]
	v_rcp_f32_e32 v130, v130
	v_rcp_f32_e32 v131, v131
	v_pk_fma_f32 v[68:69], v[74:75], v[186:187], v[190:191]
	v_exp_f32_e32 v73, v65
	v_pk_mul_f32 v[88:89], v[88:89], v[130:131]
	v_pk_mul_f32 v[88:89], v[92:93], v[88:89]
	v_pk_fma_f32 v[92:93], v[66:67], v[186:187], v[190:191]
	v_pk_fma_f32 v[66:67], v[66:67], v[182:183], v[68:69]
	v_pk_fma_f32 v[92:93], v[70:71], v[182:183], v[92:93]
	v_pk_fma_f32 v[66:67], v[70:71], v[178:179], v[66:67]
	v_pk_fma_f32 v[90:91], v[90:91], v[178:179], v[92:93]
	v_exp_f32_e32 v93, v90
	v_exp_f32_e32 v68, v66
	v_exp_f32_e32 v69, v67
	v_exp_f32_e32 v130, v91
	v_pk_add_f32 v[72:73], v[72:73], 1.0 op_sel_hi:[1,0]
	v_pk_add_f32 v[68:69], v[68:69], 1.0 op_sel_hi:[1,0]
	v_cvt_pk_bf16_f32 v198, v88, v89
	v_add_f32_e32 v88, 1.0, v93
	v_add_f32_e32 v89, 1.0, v130
	v_rcp_f32_e32 v72, v72
	v_rcp_f32_e32 v73, v73
	v_rcp_f32_e32 v68, v68
	v_rcp_f32_e32 v69, v69
	v_rcp_f32_e32 v88, v88
	v_rcp_f32_e32 v89, v89
	v_pk_fma_f32 v[74:75], v[86:87], v[170:171], v[174:175]
	v_pk_fma_f32 v[130:131], v[78:79], v[170:171], v[174:175]
	v_pk_fma_f32 v[76:77], v[76:77], v[164:165], v[84:85]
	v_pk_fma_f32 v[70:71], v[78:79], v[166:167], v[74:75]
	v_pk_fma_f32 v[130:131], v[82:83], v[166:167], v[130:131]
	v_pk_fma_f32 v[76:77], v[80:81], v[160:161], v[76:77]
	v_pk_mul_f32 v[64:65], v[64:65], v[72:73]
	v_pk_fma_f32 v[70:71], v[82:83], v[162:163], v[70:71]
	v_pk_mul_f32 v[66:67], v[66:67], v[68:69]
	v_pk_fma_f32 v[94:95], v[94:95], v[162:163], v[130:131]
	v_pk_mul_f32 v[88:89], v[90:91], v[88:89]
	v_pk_mul_f32 v[64:65], v[76:77], v[64:65]
	v_pk_mul_f32 v[66:67], v[70:71], v[66:67]
	v_pk_mul_f32 v[88:89], v[94:95], v[88:89]
	v_cvt_pk_bf16_f32 v148, v64, v65
	v_cvt_pk_bf16_f32 v149, v66, v67
	v_add_u32_e32 v66, 0x83, v246
	v_cvt_pk_bf16_f32 v155, v128, v129
	v_add_u32_e32 v128, 0x81, v246
	v_cvt_pk_bf16_f32 v199, v88, v89
	v_add_u32_e32 v88, 0x82, v246
	v_mad_i64_i32 v[66:67], s[40:41], v66, s76, v[134:135]
	v_mad_i64_i32 v[128:129], s[40:41], v128, s76, v[134:135]
	v_mad_i64_i32 v[88:89], s[40:41], v88, s76, v[134:135]
	v_lshl_add_u64 v[82:83], v[66:67], 0, v[204:205]
	v_lshl_add_u64 v[128:129], v[128:129], 0, v[204:205]
	v_lshl_add_u64 v[88:89], v[88:89], 0, v[204:205]
	v_mov_b32_e32 v64, 0
	v_mov_b64_e32 v[70:71], 0
	v_mov_b64_e32 v[72:73], 0
	v_mov_b64_e32 v[78:79], 0
	v_mov_b64_e32 v[80:81], 0
	v_mov_b64_e32 v[66:67], 0
	v_mov_b64_e32 v[68:69], 0
	v_mov_b64_e32 v[74:75], 0
	v_mov_b64_e32 v[76:77], 0
	v_mov_b32_e32 v154, v138
	s_and_saveexec_b64 s[40:41], s[26:27]
	s_cbranch_execz .LBB0_771
	ds_read_b128 v[74:77], v242
	ds_read_b128 v[66:69], v241
	ds_read_b128 v[78:81], v240
	ds_read_b128 v[70:73], v239
; #define LAS __attribute__((address_space(3)))
;     __device__ __forceinline__ void operator()(AccRef acc, const Unit& u, int wr, int wc, int fr, int fq) const {
;     ...
;         const int hc0 = 128 * u.pn + clb, row0 = u.pm * 256 + wr * 64 + 4 * fr;
; #pragma unroll
;         for (int n = 0; n < 2; ++n) {
;             const f32x4 w0v = cwv[n][0], w1v = cwv[n][1], w2v = cwv[n][2], bvv = cwv[n][3], w0g = cwv[n][4], w1g = cwv[n][5], w2g = cwv[n][6], bvg = cwv[n][7];
; #pragma unroll
;             for (int ai = 0; ai < 2; ++ai) {
;                 if (n == 0 && ai == 0) {
;                     asm volatile("" ::: "memory");
;                     const float* cv = cw + hc0 + 4; const float* cg = cv + FH; const float* bp = cb + hc0 + 4;
;                     cwv[1][0] = *(const f32x4*)(cv); cwv[1][1] = *(const f32x4*)(cv + F2); cwv[1][2] = *(const f32x4*)(cv + 2 * F2); cwv[1][3] = *(const f32x4*)(bp);
;                     cwv[1][4] = *(const f32x4*)(cg); cwv[1][5] = *(const f32x4*)(cg + F2); cwv[1][6] = *(const f32x4*)(cg + 2 * F2); cwv[1][7] = *(const f32x4*)(bp + FH);
;                     asm volatile("" ::: "memory"); }
;                 f32x4 h2v = (f32x4){0.f, 0.f, 0.f, 0.f}, h3v = h2v, h2g = h2v, h3g = h2v;
;                 const int pb = ai * 2 + wr - 1;
;                 if (pb >= 0 && fr == 0) { const LAS float* xp = xch + (pb * 2) * 256 + clb + 4 * n;
;                     h2v = *(const LAS f32x4*)(xp); h3v = *(const LAS f32x4*)(xp + 256); h2g = *(const LAS f32x4*)(xp + 128); h3g = *(const LAS f32x4*)(xp + 256 + 128); }
;                 float o[4][4];
; #pragma unroll
;                 for (int j = 0; j < 4; ++j) {
;                     const float v0 = acc[ai][0][0][n][j], v1 = acc[ai][0][1][n][j], v2 = acc[ai][0][2][n][j], v3 = acc[ai][0][3][n][j];
;                     const float g0 = acc[ai][1][0][n][j], g1 = acc[ai][1][1][n][j], g2 = acc[ai][1][2][n][j], g3 = acc[ai][1][3][n][j];
;                     const float pv3 = dpp_upd<0x111>(h3v[j], v3), pv2 = dpp_upd<0x111>(h2v[j], v2), pg3 = dpp_upd<0x111>(h3g[j], g3), pg2 = dpp_upd<0x111>(h2g[j], g2);
;                     const float hv0 = bvv[j] + w2v[j] * v0 + w1v[j] * pv3 + w0v[j] * pv2, hv1 = bvv[j] + w2v[j] * v1 + w1v[j] * v0 + w0v[j] * pv3;
;                     const float hv2 = bvv[j] + w2v[j] * v2 + w1v[j] * v1 + w0v[j] * v0, hv3 = bvv[j] + w2v[j] * v3 + w1v[j] * v2 + w0v[j] * v1;
.LBB0_771:
	s_or_b64 exec, exec, s[40:41]
	s_waitcnt lgkmcnt(0)
	v_mov_b32_dpp v70, v44 row_shr:1 row_mask:0xf bank_mask:0xf
	v_mov_b32_dpp v71, v45 row_shr:1 row_mask:0xf bank_mask:0xf
	s_waitcnt vmcnt(0)
	v_pk_fma_f32 v[84:85], v[56:57], v[120:121], v[124:125]
	v_mov_b32_dpp v78, v32 row_shr:1 row_mask:0xf bank_mask:0xf
	v_mov_b32_dpp v79, v33 row_shr:1 row_mask:0xf bank_mask:0xf
	v_pk_fma_f32 v[84:85], v[116:117], v[70:71], v[84:85]
	v_mov_b32_dpp v66, v52 row_shr:1 row_mask:0xf bank_mask:0xf
	v_pk_fma_f32 v[78:79], v[112:113], v[78:79], v[84:85]
	v_mov_b32_dpp v67, v53 row_shr:1 row_mask:0xf bank_mask:0xf
	v_exp_f32_e32 v84, v78
	v_exp_f32_e32 v85, v79
	v_pk_fma_f32 v[86:87], v[60:61], v[104:105], v[108:109]
	v_pk_add_f32 v[84:85], v[84:85], 1.0 op_sel_hi:[1,0]
	v_rcp_f32_e32 v84, v84
	v_rcp_f32_e32 v85, v85
	v_mov_b32_dpp v74, v40 row_shr:1 row_mask:0xf bank_mask:0xf
	v_mov_b32_dpp v75, v41 row_shr:1 row_mask:0xf bank_mask:0xf
	v_pk_fma_f32 v[86:87], v[100:101], v[66:67], v[86:87]
	v_pk_mul_f32 v[78:79], v[78:79], v[84:85]
	v_pk_fma_f32 v[74:75], v[96:97], v[74:75], v[86:87]
	v_mov_b32_dpp v72, v46 row_shr:1 row_mask:0xf bank_mask:0xf
	v_mov_b32_dpp v73, v47 row_shr:1 row_mask:0xf bank_mask:0xf
	v_pk_mul_f32 v[74:75], v[74:75], v[78:79]
	v_pk_fma_f32 v[78:79], v[58:59], v[122:123], v[126:127]
	v_mov_b32_dpp v80, v34 row_shr:1 row_mask:0xf bank_mask:0xf
	v_mov_b32_dpp v81, v35 row_shr:1 row_mask:0xf bank_mask:0xf
	v_pk_fma_f32 v[78:79], v[118:119], v[72:73], v[78:79]
	v_mov_b32_dpp v68, v54 row_shr:1 row_mask:0xf bank_mask:0xf
	v_pk_fma_f32 v[78:79], v[114:115], v[80:81], v[78:79]
	v_mov_b32_dpp v69, v55 row_shr:1 row_mask:0xf bank_mask:0xf
	v_exp_f32_e32 v80, v78
	v_exp_f32_e32 v81, v79
	v_pk_fma_f32 v[84:85], v[62:63], v[106:107], v[110:111]
	v_pk_add_f32 v[80:81], v[80:81], 1.0 op_sel_hi:[1,0]
	v_rcp_f32_e32 v80, v80
	v_rcp_f32_e32 v81, v81
	v_mov_b32_dpp v76, v42 row_shr:1 row_mask:0xf bank_mask:0xf
	v_mov_b32_dpp v77, v43 row_shr:1 row_mask:0xf bank_mask:0xf
	v_pk_fma_f32 v[84:85], v[102:103], v[68:69], v[84:85]
	v_pk_mul_f32 v[78:79], v[78:79], v[80:81]
	v_pk_fma_f32 v[76:77], v[98:99], v[76:77], v[84:85]
	v_cvt_pk_bf16_f32 v92, v74, v75
	v_pk_mul_f32 v[76:77], v[76:77], v[78:79]
	v_pk_fma_f32 v[44:45], v[44:45], v[120:121], v[124:125]
	v_cvt_pk_bf16_f32 v93, v76, v77
	v_pk_fma_f32 v[76:77], v[36:37], v[120:121], v[124:125]
	v_mov_b32_e32 v90, v247
	v_mov_b32_e32 v91, v248
	global_store_dwordx4 v[202:203], v[90:93], off
	v_pk_fma_f32 v[76:77], v[56:57], v[116:117], v[76:77]
	v_pk_fma_f32 v[52:53], v[52:53], v[104:105], v[108:109]
	v_pk_fma_f32 v[70:71], v[112:113], v[70:71], v[76:77]
	s_nop 0
	v_exp_f32_e32 v74, v70
	v_exp_f32_e32 v75, v71
	s_nop 0
	v_pk_add_f32 v[74:75], v[74:75], 1.0 op_sel_hi:[1,0]
	v_rcp_f32_e32 v74, v74
	v_rcp_f32_e32 v75, v75
	v_pk_fma_f32 v[76:77], v[48:49], v[104:105], v[108:109]
	v_pk_mul_f32 v[70:71], v[70:71], v[74:75]
	v_pk_fma_f32 v[76:77], v[60:61], v[100:101], v[76:77]
	v_pk_fma_f32 v[74:75], v[50:51], v[106:107], v[110:111]
	v_pk_fma_f32 v[66:67], v[96:97], v[66:67], v[76:77]
	v_pk_fma_f32 v[74:75], v[62:63], v[102:103], v[74:75]
	v_pk_mul_f32 v[66:67], v[66:67], v[70:71]
	v_pk_fma_f32 v[70:71], v[38:39], v[122:123], v[126:127]
	v_pk_fma_f32 v[68:69], v[98:99], v[68:69], v[74:75]
	v_pk_fma_f32 v[70:71], v[58:59], v[118:119], v[70:71]
	v_cvt_pk_bf16_f32 v136, v66, v67
	v_pk_fma_f32 v[70:71], v[114:115], v[72:73], v[70:71]
	s_nop 0
	v_exp_f32_e32 v72, v70
	v_exp_f32_e32 v73, v71
	s_nop 0
	v_pk_add_f32 v[72:73], v[72:73], 1.0 op_sel_hi:[1,0]
	v_rcp_f32_e32 v72, v72
	v_rcp_f32_e32 v73, v73
	s_nop 0
	v_pk_mul_f32 v[70:71], v[70:71], v[72:73]
	s_nop 0
	v_pk_mul_f32 v[68:69], v[68:69], v[70:71]
	s_nop 0
	v_cvt_pk_bf16_f32 v137, v68, v69
	v_pk_fma_f32 v[68:69], v[32:33], v[120:121], v[124:125]
	v_mov_b32_e32 v134, v249
	v_mov_b32_e32 v135, v250
	global_store_dwordx4 v[196:197], v[134:137], off
	v_pk_fma_f32 v[68:69], v[36:37], v[116:117], v[68:69]
	v_pk_fma_f32 v[32:33], v[32:33], v[116:117], v[44:45]
	v_pk_fma_f32 v[56:57], v[56:57], v[112:113], v[68:69]
	v_pk_fma_f32 v[32:33], v[36:37], v[112:113], v[32:33]
	v_exp_f32_e32 v66, v56
	v_exp_f32_e32 v67, v57
	s_nop 0
	v_pk_add_f32 v[66:67], v[66:67], 1.0 op_sel_hi:[1,0]
	v_rcp_f32_e32 v66, v66
	v_rcp_f32_e32 v67, v67
	v_pk_fma_f32 v[68:69], v[40:41], v[104:105], v[108:109]
	v_exp_f32_e32 v44, v32
	v_pk_fma_f32 v[68:69], v[48:49], v[100:101], v[68:69]
	v_pk_mul_f32 v[56:57], v[56:57], v[66:67]
	v_pk_fma_f32 v[60:61], v[60:61], v[96:97], v[68:69]
	v_pk_fma_f32 v[36:37], v[46:47], v[122:123], v[126:127]
	v_pk_mul_f32 v[56:57], v[60:61], v[56:57]
	v_pk_fma_f32 v[60:61], v[34:35], v[122:123], v[126:127]
	v_pk_fma_f32 v[34:35], v[34:35], v[118:119], v[36:37]
	v_pk_fma_f32 v[60:61], v[38:39], v[118:119], v[60:61]
	v_pk_fma_f32 v[34:35], v[38:39], v[114:115], v[34:35]
	v_pk_fma_f32 v[58:59], v[58:59], v[114:115], v[60:61]
	v_exp_f32_e32 v60, v58
	v_exp_f32_e32 v45, v33
	v_exp_f32_e32 v36, v34
	v_exp_f32_e32 v37, v35
	v_exp_f32_e32 v61, v59
	v_cvt_pk_bf16_f32 v164, v56, v57
	v_pk_add_f32 v[44:45], v[44:45], 1.0 op_sel_hi:[1,0]
	v_pk_add_f32 v[36:37], v[36:37], 1.0 op_sel_hi:[1,0]
	v_pk_add_f32 v[60:61], v[60:61], 1.0 op_sel_hi:[1,0]
	v_rcp_f32_e32 v44, v44
	v_rcp_f32_e32 v45, v45
	v_rcp_f32_e32 v36, v36
	v_rcp_f32_e32 v37, v37
	v_rcp_f32_e32 v60, v60
	v_rcp_f32_e32 v61, v61
	v_pk_fma_f32 v[46:47], v[54:55], v[106:107], v[110:111]
	v_pk_fma_f32 v[66:67], v[42:43], v[106:107], v[110:111]
	v_pk_fma_f32 v[40:41], v[40:41], v[100:101], v[52:53]
	v_pk_fma_f32 v[38:39], v[42:43], v[102:103], v[46:47]
	v_pk_fma_f32 v[66:67], v[50:51], v[102:103], v[66:67]
	v_pk_fma_f32 v[40:41], v[48:49], v[96:97], v[40:41]
	v_pk_mul_f32 v[32:33], v[32:33], v[44:45]
	v_pk_fma_f32 v[38:39], v[50:51], v[98:99], v[38:39]
	v_pk_mul_f32 v[34:35], v[34:35], v[36:37]
	v_pk_fma_f32 v[62:63], v[62:63], v[98:99], v[66:67]
	v_pk_mul_f32 v[58:59], v[58:59], v[60:61]
	v_pk_mul_f32 v[32:33], v[40:41], v[32:33]
	v_pk_mul_f32 v[34:35], v[38:39], v[34:35]
	v_pk_mul_f32 v[58:59], v[62:63], v[58:59]
	v_cvt_pk_bf16_f32 v160, v32, v33
	v_cvt_pk_bf16_f32 v161, v34, v35
	v_cvt_pk_bf16_f32 v57, v58, v59
	v_mov_b32_e32 v158, v251
	v_mov_b32_e32 v159, v253
	global_store_dwordx4 v[140:141], v[158:161], off
	v_mov_b32_e32 v65, 0
	v_mov_b64_e32 v[66:67], 0
	v_mov_b64_e32 v[40:41], 0
	v_mov_b64_e32 v[42:43], 0
	v_mov_b64_e32 v[32:33], 0
	v_mov_b64_e32 v[34:35], 0
	v_mov_b64_e32 v[36:37], 0
	v_mov_b64_e32 v[38:39], 0
	v_mov_b32_e32 v162, v254
	v_mov_b32_e32 v163, v255
	v_mov_b32_e32 v165, v57
	global_store_dwordx4 v[152:153], v[162:165], off
	s_and_saveexec_b64 s[40:41], s[28:29]
	s_cbranch_execz .LBB0_754
	ds_read_b128 v[36:39], v237 offset:2064
	ds_read_b128 v[40:43], v237 offset:2576
	ds_read_b128 v[32:35], v237 offset:3088
	ds_read_b128 v[64:67], v237 offset:3600
	s_branch .LBB0_754

; #define LAS __attribute__((address_space(3)))
; __device__ __forceinline__ float sigmoidf_(float x) { return __builtin_amdgcn_rcpf(1.0f + __expf(-x)); }
;     __device__ __forceinline__ void operator()(AccRef acc, const Unit& u, int wr, int wc, int fr, int fq) const {
;     ...
;                 f32x4 h2v = (f32x4){0.f, 0.f, 0.f, 0.f}, h3v = h2v, h2g = h2v, h3g = h2v;
;                 const int pb = ai * 2 + wr - 1;
;                 if (pb >= 0 && fr == 0) { const LAS float* xp = xch + (pb * 2) * 256 + clb + 4 * n;
;                     h2v = *(const LAS f32x4*)(xp); h3v = *(const LAS f32x4*)(xp + 256); h2g = *(const LAS f32x4*)(xp + 128); h3g = *(const LAS f32x4*)(xp + 256 + 128); }
;                 float o[4][4];
; #pragma unroll
;                 for (int j = 0; j < 4; ++j) {
;                     const float v0 = acc[ai][0][0][n][j], v1 = acc[ai][0][1][n][j], v2 = acc[ai][0][2][n][j], v3 = acc[ai][0][3][n][j];
;                     const float g0 = acc[ai][1][0][n][j], g1 = acc[ai][1][1][n][j], g2 = acc[ai][1][2][n][j], g3 = acc[ai][1][3][n][j];
;                     const float pv3 = dpp_upd<0x111>(h3v[j], v3), pv2 = dpp_upd<0x111>(h2v[j], v2), pg3 = dpp_upd<0x111>(h3g[j], g3), pg2 = dpp_upd<0x111>(h2g[j], g2);
;                     const float hv0 = bvv[j] + w2v[j] * v0 + w1v[j] * pv3 + w0v[j] * pv2, hv1 = bvv[j] + w2v[j] * v1 + w1v[j] * v0 + w0v[j] * pv3;
;                     const float hv2 = bvv[j] + w2v[j] * v2 + w1v[j] * v1 + w0v[j] * v0, hv3 = bvv[j] + w2v[j] * v3 + w1v[j] * v2 + w0v[j] * v1;
;                     const float hg0 = bvg[j] + w2g[j] * g0 + w1g[j] * pg3 + w0g[j] * pg2, hg1 = bvg[j] + w2g[j] * g1 + w1g[j] * g0 + w0g[j] * pg3;
;                     const float hg2 = bvg[j] + w2g[j] * g2 + w1g[j] * g1 + w0g[j] * g0, hg3 = bvg[j] + w2g[j] * g3 + w1g[j] * g2 + w0g[j] * g1;
;                     o[0][j] = hg0 * sigmoidf_(hg0) * hv0; o[1][j] = hg1 * sigmoidf_(hg1) * hv1; o[2][j] = hg2 * sigmoidf_(hg2) * hv2; o[3][j] = hg3 * sigmoidf_(hg3) * hv3; }
; #pragma unroll
;                 for (int m = 0; m < 4; ++m) { u32x2 w; w.x = cvt_pk_bf16(o[m][0], o[m][1]); w.y = cvt_pk_bf16(o[m][2], o[m][3]);
;                     *(u32x2*)(Aout + (size_t)(row0 + ai * 128 + m) * FH + hc0 + 4 * n) = w; } } }
.LBB0_1355:
	s_or_b64 exec, exec, s[42:43]
	s_waitcnt lgkmcnt(0)
	v_mov_b32_dpp v64, v8 row_shr:1 row_mask:0xf bank_mask:0xf
	v_mov_b32_dpp v65, v9 row_shr:1 row_mask:0xf bank_mask:0xf
	v_pk_fma_f32 v[44:45], v[24:25], v[120:121], v[124:125]
	v_mov_b32_dpp v40, v0 row_shr:1 row_mask:0xf bank_mask:0xf
	v_mov_b32_dpp v41, v1 row_shr:1 row_mask:0xf bank_mask:0xf
	v_pk_fma_f32 v[44:45], v[116:117], v[64:65], v[44:45]
	v_mov_b32_dpp v32, v20 row_shr:1 row_mask:0xf bank_mask:0xf
	v_pk_fma_f32 v[40:41], v[112:113], v[40:41], v[44:45]
	v_mov_b32_dpp v33, v21 row_shr:1 row_mask:0xf bank_mask:0xf
	v_exp_f32_e32 v44, v40
	v_exp_f32_e32 v45, v41
	v_pk_fma_f32 v[46:47], v[28:29], v[104:105], v[108:109]
	v_mov_b32_dpp v36, v12 row_shr:1 row_mask:0xf bank_mask:0xf
	v_pk_add_f32 v[44:45], v[44:45], 1.0 op_sel_hi:[1,0]
	v_rcp_f32_e32 v44, v44
	v_rcp_f32_e32 v45, v45
	v_mov_b32_dpp v37, v13 row_shr:1 row_mask:0xf bank_mask:0xf
	v_pk_fma_f32 v[46:47], v[100:101], v[32:33], v[46:47]
	v_mov_b32_dpp v66, v10 row_shr:1 row_mask:0xf bank_mask:0xf
	v_pk_fma_f32 v[36:37], v[96:97], v[36:37], v[46:47]
	v_pk_mul_f32 v[40:41], v[40:41], v[44:45]
	v_mov_b32_dpp v67, v11 row_shr:1 row_mask:0xf bank_mask:0xf
	v_pk_mul_f32 v[36:37], v[36:37], v[40:41]
	v_pk_fma_f32 v[40:41], v[26:27], v[122:123], v[126:127]
	v_mov_b32_dpp v42, v2 row_shr:1 row_mask:0xf bank_mask:0xf
	v_mov_b32_dpp v43, v3 row_shr:1 row_mask:0xf bank_mask:0xf
	v_pk_fma_f32 v[40:41], v[118:119], v[66:67], v[40:41]
	v_cvt_pk_bf16_f32 v146, v36, v37
	v_pk_fma_f32 v[40:41], v[114:115], v[42:43], v[40:41]
	v_mov_b32_dpp v34, v22 row_shr:1 row_mask:0xf bank_mask:0xf
	v_exp_f32_e32 v42, v40
	v_exp_f32_e32 v43, v41
	v_mov_b32_dpp v35, v23 row_shr:1 row_mask:0xf bank_mask:0xf
	v_pk_add_f32 v[42:43], v[42:43], 1.0 op_sel_hi:[1,0]
	v_rcp_f32_e32 v42, v42
	v_rcp_f32_e32 v43, v43
	v_pk_fma_f32 v[44:45], v[30:31], v[106:107], v[110:111]
	v_mov_b32_dpp v38, v14 row_shr:1 row_mask:0xf bank_mask:0xf
	v_mov_b32_dpp v39, v15 row_shr:1 row_mask:0xf bank_mask:0xf
	v_pk_fma_f32 v[44:45], v[102:103], v[34:35], v[44:45]
	v_pk_mul_f32 v[40:41], v[40:41], v[42:43]
	v_pk_fma_f32 v[38:39], v[98:99], v[38:39], v[44:45]
	v_pk_fma_f32 v[8:9], v[8:9], v[120:121], v[124:125]
	v_pk_mul_f32 v[38:39], v[38:39], v[40:41]
	v_pk_fma_f32 v[20:21], v[20:21], v[104:105], v[108:109]
	v_cvt_pk_bf16_f32 v147, v38, v39
	v_pk_fma_f32 v[38:39], v[4:5], v[120:121], v[124:125]
	global_store_dwordx4 v[132:133], v[144:147], off
	v_pk_fma_f32 v[38:39], v[24:25], v[116:117], v[38:39]
	s_and_b64 vcc, exec, s[14:15]
	v_pk_fma_f32 v[38:39], v[112:113], v[64:65], v[38:39]
	s_mov_b32 s43, s34
	v_exp_f32_e32 v36, v38
	v_exp_f32_e32 v37, v39
	s_mov_b32 s42, s36
	s_mov_b64 s[46:47], s[40:41]
	v_pk_add_f32 v[36:37], v[36:37], 1.0 op_sel_hi:[1,0]
	v_rcp_f32_e32 v36, v36
	v_rcp_f32_e32 v37, v37
	v_pk_fma_f32 v[40:41], v[16:17], v[104:105], v[108:109]
	s_mov_b64 s[44:45], s[38:39]
	v_pk_fma_f32 v[40:41], v[28:29], v[100:101], v[40:41]
	v_pk_mul_f32 v[36:37], v[38:39], v[36:37]
	v_pk_fma_f32 v[32:33], v[96:97], v[32:33], v[40:41]
	v_pk_fma_f32 v[40:41], v[18:19], v[106:107], v[110:111]
	v_pk_mul_f32 v[32:33], v[32:33], v[36:37]
	v_pk_fma_f32 v[36:37], v[6:7], v[122:123], v[126:127]
	v_cvt_pk_bf16_f32 v156, v32, v33
	v_pk_fma_f32 v[36:37], v[26:27], v[118:119], v[36:37]
	v_pk_fma_f32 v[40:41], v[30:31], v[102:103], v[40:41]
	v_pk_fma_f32 v[36:37], v[114:115], v[66:67], v[36:37]
	v_pk_fma_f32 v[34:35], v[98:99], v[34:35], v[40:41]
	v_exp_f32_e32 v38, v36
	v_exp_f32_e32 v39, v37
	s_nop 0
	v_pk_add_f32 v[38:39], v[38:39], 1.0 op_sel_hi:[1,0]
	v_rcp_f32_e32 v38, v38
	v_rcp_f32_e32 v39, v39
	s_nop 0
	v_pk_mul_f32 v[36:37], v[36:37], v[38:39]
	s_nop 0
	v_pk_mul_f32 v[34:35], v[34:35], v[36:37]
	s_nop 0
	v_cvt_pk_bf16_f32 v157, v34, v35
	v_pk_fma_f32 v[34:35], v[0:1], v[120:121], v[124:125]
	global_store_dwordx4 v[128:129], v[154:157], off
	v_pk_fma_f32 v[34:35], v[4:5], v[116:117], v[34:35]
	v_pk_fma_f32 v[0:1], v[0:1], v[116:117], v[8:9]
	v_pk_fma_f32 v[24:25], v[24:25], v[112:113], v[34:35]
	v_pk_fma_f32 v[0:1], v[4:5], v[112:113], v[0:1]
	v_exp_f32_e32 v32, v24
	v_exp_f32_e32 v33, v25
	v_exp_f32_e32 v8, v0
	v_pk_add_f32 v[32:33], v[32:33], 1.0 op_sel_hi:[1,0]
	v_rcp_f32_e32 v32, v32
	v_rcp_f32_e32 v33, v33
	v_pk_fma_f32 v[34:35], v[12:13], v[104:105], v[108:109]
	v_pk_fma_f32 v[4:5], v[10:11], v[122:123], v[126:127]
	v_pk_fma_f32 v[34:35], v[16:17], v[100:101], v[34:35]
	v_pk_mul_f32 v[24:25], v[24:25], v[32:33]
	v_pk_fma_f32 v[28:29], v[28:29], v[96:97], v[34:35]
	v_pk_mul_f32 v[24:25], v[28:29], v[24:25]
	v_pk_fma_f32 v[28:29], v[2:3], v[122:123], v[126:127]
	v_pk_fma_f32 v[2:3], v[2:3], v[118:119], v[4:5]
	v_pk_fma_f32 v[28:29], v[6:7], v[118:119], v[28:29]
	v_pk_fma_f32 v[2:3], v[6:7], v[114:115], v[2:3]
	v_pk_fma_f32 v[26:27], v[26:27], v[114:115], v[28:29]
	v_exp_f32_e32 v28, v26
	v_exp_f32_e32 v29, v27
	v_exp_f32_e32 v9, v1
	v_exp_f32_e32 v4, v2
	v_exp_f32_e32 v5, v3
	v_cvt_pk_bf16_f32 v200, v24, v25
	v_pk_add_f32 v[28:29], v[28:29], 1.0 op_sel_hi:[1,0]
	v_pk_add_f32 v[8:9], v[8:9], 1.0 op_sel_hi:[1,0]
	v_pk_add_f32 v[4:5], v[4:5], 1.0 op_sel_hi:[1,0]
	v_rcp_f32_e32 v28, v28
	v_rcp_f32_e32 v29, v29
	v_rcp_f32_e32 v8, v8
	v_rcp_f32_e32 v9, v9
	v_rcp_f32_e32 v4, v4
	v_rcp_f32_e32 v5, v5
	v_pk_fma_f32 v[32:33], v[14:15], v[106:107], v[110:111]
	v_pk_fma_f32 v[10:11], v[22:23], v[106:107], v[110:111]
	v_pk_fma_f32 v[32:33], v[18:19], v[102:103], v[32:33]
	v_pk_fma_f32 v[12:13], v[12:13], v[100:101], v[20:21]
	v_pk_fma_f32 v[6:7], v[14:15], v[102:103], v[10:11]
	v_pk_fma_f32 v[30:31], v[30:31], v[98:99], v[32:33]
	v_pk_mul_f32 v[26:27], v[26:27], v[28:29]
	v_pk_fma_f32 v[12:13], v[16:17], v[96:97], v[12:13]
	v_pk_mul_f32 v[0:1], v[0:1], v[8:9]
	v_pk_fma_f32 v[6:7], v[18:19], v[98:99], v[6:7]
	v_pk_mul_f32 v[2:3], v[2:3], v[4:5]
	v_pk_mul_f32 v[26:27], v[30:31], v[26:27]
	v_pk_mul_f32 v[0:1], v[12:13], v[0:1]
	v_pk_mul_f32 v[2:3], v[6:7], v[2:3]
	v_cvt_pk_bf16_f32 v201, v26, v27
	v_cvt_pk_bf16_f32 v150, v0, v1
	v_cvt_pk_bf16_f32 v151, v2, v3
	global_store_dwordx4 v[88:89], v[198:201], off
	global_store_dwordx4 v[82:83], v[148:151], off
	s_cbranch_vccnz .LBB0_1374

; #define LAS __attribute__((address_space(3)))
; __device__ __forceinline__ float sigmoidf_(float x) { return __builtin_amdgcn_rcpf(1.0f + __expf(-x)); }
;     __device__ __forceinline__ void operator()(AccRef acc, const Unit& u, int wr, int wc, int fr, int fq) const {
;     ...
;                 f32x4 h2v = (f32x4){0.f, 0.f, 0.f, 0.f}, h3v = h2v, h2g = h2v, h3g = h2v;
;                 const int pb = ai * 2 + wr - 1;
;                 if (pb >= 0 && fr == 0) { const LAS float* xp = xch + (pb * 2) * 256 + clb + 4 * n;
;                     h2v = *(const LAS f32x4*)(xp); h3v = *(const LAS f32x4*)(xp + 256); h2g = *(const LAS f32x4*)(xp + 128); h3g = *(const LAS f32x4*)(xp + 256 + 128); }
;                 float o[4][4];
; #pragma unroll
;                 for (int j = 0; j < 4; ++j) {
;                     const float v0 = acc[ai][0][0][n][j], v1 = acc[ai][0][1][n][j], v2 = acc[ai][0][2][n][j], v3 = acc[ai][0][3][n][j];
;                     const float g0 = acc[ai][1][0][n][j], g1 = acc[ai][1][1][n][j], g2 = acc[ai][1][2][n][j], g3 = acc[ai][1][3][n][j];
;                     const float pv3 = dpp_upd<0x111>(h3v[j], v3), pv2 = dpp_upd<0x111>(h2v[j], v2), pg3 = dpp_upd<0x111>(h3g[j], g3), pg2 = dpp_upd<0x111>(h2g[j], g2);
;                     const float hv0 = bvv[j] + w2v[j] * v0 + w1v[j] * pv3 + w0v[j] * pv2, hv1 = bvv[j] + w2v[j] * v1 + w1v[j] * v0 + w0v[j] * pv3;
;                     const float hv2 = bvv[j] + w2v[j] * v2 + w1v[j] * v1 + w0v[j] * v0, hv3 = bvv[j] + w2v[j] * v3 + w1v[j] * v2 + w0v[j] * v1;
;                     const float hg0 = bvg[j] + w2g[j] * g0 + w1g[j] * pg3 + w0g[j] * pg2, hg1 = bvg[j] + w2g[j] * g1 + w1g[j] * g0 + w0g[j] * pg3;
;                     const float hg2 = bvg[j] + w2g[j] * g2 + w1g[j] * g1 + w0g[j] * g0, hg3 = bvg[j] + w2g[j] * g3 + w1g[j] * g2 + w0g[j] * g1;
;                     o[0][j] = hg0 * sigmoidf_(hg0) * hv0; o[1][j] = hg1 * sigmoidf_(hg1) * hv1; o[2][j] = hg2 * sigmoidf_(hg2) * hv2; o[3][j] = hg3 * sigmoidf_(hg3) * hv3; }
; #pragma unroll
;                 for (int m = 0; m < 4; ++m) { u32x2 w; w.x = cvt_pk_bf16(o[m][0], o[m][1]); w.y = cvt_pk_bf16(o[m][2], o[m][3]);
;                     *(u32x2*)(Aout + (size_t)(row0 + ai * 128 + m) * FH + hc0 + 4 * n) = w; } } }
.LBB0_1366:
	s_or_b64 exec, exec, s[48:49]
	v_pk_fma_f32 v[248:249], v[152:153], v[184:185], v[188:189]
	v_mov_b32_dpp v206, v128 row_shr:1 row_mask:0xf bank_mask:0xf
	v_mov_b32_dpp v207, v129 row_shr:1 row_mask:0xf bank_mask:0xf
	v_pk_fma_f32 v[248:249], v[180:181], v[198:199], v[248:249]
	v_mov_b32_dpp v194, v148 row_shr:1 row_mask:0xf bank_mask:0xf
	v_pk_fma_f32 v[206:207], v[176:177], v[206:207], v[248:249]
	v_mov_b32_dpp v195, v149 row_shr:1 row_mask:0xf bank_mask:0xf
	v_exp_f32_e32 v248, v206
	v_exp_f32_e32 v249, v207
	v_pk_fma_f32 v[250:251], v[156:157], v[168:169], v[172:173]
	v_pk_add_f32 v[248:249], v[248:249], 1.0 op_sel_hi:[1,0]
	v_rcp_f32_e32 v248, v248
	v_rcp_f32_e32 v249, v249
	v_mov_b32_dpp v202, v136 row_shr:1 row_mask:0xf bank_mask:0xf
	v_mov_b32_dpp v203, v137 row_shr:1 row_mask:0xf bank_mask:0xf
	v_pk_fma_f32 v[250:251], v[164:165], v[194:195], v[250:251]
	v_pk_mul_f32 v[206:207], v[206:207], v[248:249]
	v_pk_fma_f32 v[202:203], v[160:161], v[202:203], v[250:251]
	v_mov_b32_dpp v200, v142 row_shr:1 row_mask:0xf bank_mask:0xf
	v_mov_b32_dpp v201, v143 row_shr:1 row_mask:0xf bank_mask:0xf
	v_pk_mul_f32 v[202:203], v[202:203], v[206:207]
	v_pk_fma_f32 v[206:207], v[154:155], v[186:187], v[190:191]
	v_mov_b32_dpp v208, v130 row_shr:1 row_mask:0xf bank_mask:0xf
	v_mov_b32_dpp v209, v131 row_shr:1 row_mask:0xf bank_mask:0xf
	v_pk_fma_f32 v[206:207], v[182:183], v[200:201], v[206:207]
	v_mov_b32_dpp v196, v150 row_shr:1 row_mask:0xf bank_mask:0xf
	v_pk_fma_f32 v[206:207], v[178:179], v[208:209], v[206:207]
	v_mov_b32_dpp v197, v151 row_shr:1 row_mask:0xf bank_mask:0xf
	v_exp_f32_e32 v193, v206
	v_exp_f32_e32 v209, v207
	v_cvt_pk_bf16_f32 v247, v202, v203
	v_add_f32_e32 v193, 1.0, v193
	v_rcp_f32_e32 v202, v193
	v_add_f32_e32 v193, 1.0, v209
	v_rcp_f32_e32 v203, v193
	v_pk_fma_f32 v[248:249], v[158:159], v[170:171], v[174:175]
	v_mov_b32_dpp v204, v138 row_shr:1 row_mask:0xf bank_mask:0xf
	v_mov_b32_dpp v205, v139 row_shr:1 row_mask:0xf bank_mask:0xf
	v_pk_fma_f32 v[248:249], v[166:167], v[196:197], v[248:249]
	v_pk_mul_f32 v[202:203], v[206:207], v[202:203]
	v_pk_fma_f32 v[204:205], v[162:163], v[204:205], v[248:249]
	v_lshl_add_u32 v246, s42, 8, v236
	v_pk_mul_f32 v[202:203], v[204:205], v[202:203]
	v_lshlrev_b64 v[204:205], 1, v[232:233]
	v_pk_fma_f32 v[232:233], v[132:133], v[184:185], v[188:189]
	v_mov_b64_e32 v[206:207], s[60:61]
	v_pk_fma_f32 v[232:233], v[152:153], v[180:181], v[232:233]
	v_cvt_pk_bf16_f32 v248, v202, v203
	v_pk_fma_f32 v[198:199], v[176:177], v[198:199], v[232:233]
	v_mad_i64_i32 v[202:203], s[42:43], v246, s82, v[206:207]
	v_exp_f32_e32 v193, v198
	v_exp_f32_e32 v232, v199
	v_lshl_add_u64 v[202:203], v[202:203], 0, v[204:205]
	v_add_f32_e32 v193, 1.0, v193
	v_rcp_f32_e32 v208, v193
	v_add_f32_e32 v193, 1.0, v232
	v_rcp_f32_e32 v209, v193
	v_pk_fma_f32 v[232:233], v[144:145], v[168:169], v[172:173]
	v_pk_fma_f32 v[140:141], v[140:141], v[184:185], v[188:189]
	v_pk_fma_f32 v[232:233], v[156:157], v[164:165], v[232:233]
	v_pk_mul_f32 v[198:199], v[198:199], v[208:209]
	v_pk_fma_f32 v[194:195], v[160:161], v[194:195], v[232:233]
	v_pk_fma_f32 v[208:209], v[146:147], v[170:171], v[174:175]
	v_pk_mul_f32 v[194:195], v[194:195], v[198:199]
	v_pk_fma_f32 v[198:199], v[134:135], v[186:187], v[190:191]
	v_pk_fma_f32 v[208:209], v[158:159], v[166:167], v[208:209]
	v_pk_fma_f32 v[198:199], v[154:155], v[182:183], v[198:199]
	v_pk_fma_f32 v[196:197], v[162:163], v[196:197], v[208:209]
	v_pk_fma_f32 v[198:199], v[178:179], v[200:201], v[198:199]
	v_cvt_pk_bf16_f32 v249, v194, v195
	v_exp_f32_e32 v200, v198
	v_exp_f32_e32 v201, v199
	v_pk_fma_f32 v[148:149], v[148:149], v[168:169], v[172:173]
	v_pk_add_f32 v[200:201], v[200:201], 1.0 op_sel_hi:[1,0]
	v_rcp_f32_e32 v200, v200
	v_rcp_f32_e32 v201, v201
	v_or_b32_e32 v193, 1, v246
	v_pk_mul_f32 v[198:199], v[198:199], v[200:201]
	s_nop 0
	v_pk_mul_f32 v[196:197], v[196:197], v[198:199]
	v_pk_fma_f32 v[198:199], v[128:129], v[184:185], v[188:189]
	v_cvt_pk_bf16_f32 v250, v196, v197
	v_pk_fma_f32 v[198:199], v[132:133], v[180:181], v[198:199]
	v_mad_i64_i32 v[196:197], s[42:43], v193, s82, v[206:207]
	v_pk_fma_f32 v[152:153], v[152:153], v[176:177], v[198:199]
	v_lshl_add_u64 v[196:197], v[196:197], 0, v[204:205]
	v_exp_f32_e32 v193, v152
	v_exp_f32_e32 v198, v153
	v_add_f32_e32 v193, 1.0, v193
	v_rcp_f32_e32 v194, v193
	v_add_f32_e32 v193, 1.0, v198
	v_rcp_f32_e32 v195, v193
	v_pk_fma_f32 v[198:199], v[136:137], v[168:169], v[172:173]
	v_pk_fma_f32 v[128:129], v[128:129], v[180:181], v[140:141]
	v_pk_fma_f32 v[198:199], v[144:145], v[164:165], v[198:199]
	v_pk_fma_f32 v[128:129], v[132:133], v[176:177], v[128:129]
	v_pk_fma_f32 v[156:157], v[156:157], v[160:161], v[198:199]
	v_pk_mul_f32 v[152:153], v[152:153], v[194:195]
	v_pk_mul_f32 v[152:153], v[156:157], v[152:153]
	v_pk_fma_f32 v[156:157], v[130:131], v[186:187], v[190:191]
	v_exp_f32_e32 v140, v128
	v_pk_fma_f32 v[132:133], v[142:143], v[186:187], v[190:191]
	v_pk_fma_f32 v[156:157], v[134:135], v[182:183], v[156:157]
	v_pk_fma_f32 v[130:131], v[130:131], v[182:183], v[132:133]
	v_pk_fma_f32 v[154:155], v[154:155], v[178:179], v[156:157]
	v_pk_fma_f32 v[130:131], v[134:135], v[178:179], v[130:131]
	v_exp_f32_e32 v157, v154
	v_exp_f32_e32 v141, v129
	v_exp_f32_e32 v132, v130
	v_exp_f32_e32 v133, v131
	v_exp_f32_e32 v193, v155
	v_pk_add_f32 v[140:141], v[140:141], 1.0 op_sel_hi:[1,0]
	v_pk_add_f32 v[132:133], v[132:133], 1.0 op_sel_hi:[1,0]
	v_cvt_pk_bf16_f32 v254, v152, v153
	v_add_f32_e32 v152, 1.0, v157
	v_add_f32_e32 v153, 1.0, v193
	v_rcp_f32_e32 v140, v140
	v_rcp_f32_e32 v141, v141
	v_rcp_f32_e32 v132, v132
; #define LAS __attribute__((address_space(3)))
; __device__ __forceinline__ float sigmoidf_(float x) { return __builtin_amdgcn_rcpf(1.0f + __expf(-x)); }
;     __device__ __forceinline__ void operator()(AccRef acc, const Unit& u, int wr, int wc, int fr, int fq) const {
;     ...
;                 f32x4 h2v = (f32x4){0.f, 0.f, 0.f, 0.f}, h3v = h2v, h2g = h2v, h3g = h2v;
;                 const int pb = ai * 2 + wr - 1;
;                 if (pb >= 0 && fr == 0) { const LAS float* xp = xch + (pb * 2) * 256 + clb + 4 * n;
;                     h2v = *(const LAS f32x4*)(xp); h3v = *(const LAS f32x4*)(xp + 256); h2g = *(const LAS f32x4*)(xp + 128); h3g = *(const LAS f32x4*)(xp + 256 + 128); }
;                 float o[4][4];
; #pragma unroll
;                 for (int j = 0; j < 4; ++j) {
;                     const float v0 = acc[ai][0][0][n][j], v1 = acc[ai][0][1][n][j], v2 = acc[ai][0][2][n][j], v3 = acc[ai][0][3][n][j];
;                     const float g0 = acc[ai][1][0][n][j], g1 = acc[ai][1][1][n][j], g2 = acc[ai][1][2][n][j], g3 = acc[ai][1][3][n][j];
;                     const float pv3 = dpp_upd<0x111>(h3v[j], v3), pv2 = dpp_upd<0x111>(h2v[j], v2), pg3 = dpp_upd<0x111>(h3g[j], g3), pg2 = dpp_upd<0x111>(h2g[j], g2);
;                     const float hv0 = bvv[j] + w2v[j] * v0 + w1v[j] * pv3 + w0v[j] * pv2, hv1 = bvv[j] + w2v[j] * v1 + w1v[j] * v0 + w0v[j] * pv3;
;                     const float hv2 = bvv[j] + w2v[j] * v2 + w1v[j] * v1 + w0v[j] * v0, hv3 = bvv[j] + w2v[j] * v3 + w1v[j] * v2 + w0v[j] * v1;
;                     const float hg0 = bvg[j] + w2g[j] * g0 + w1g[j] * pg3 + w0g[j] * pg2, hg1 = bvg[j] + w2g[j] * g1 + w1g[j] * g0 + w0g[j] * pg3;
;                     const float hg2 = bvg[j] + w2g[j] * g2 + w1g[j] * g1 + w0g[j] * g0, hg3 = bvg[j] + w2g[j] * g3 + w1g[j] * g2 + w0g[j] * g1;
;                     o[0][j] = hg0 * sigmoidf_(hg0) * hv0; o[1][j] = hg1 * sigmoidf_(hg1) * hv1; o[2][j] = hg2 * sigmoidf_(hg2) * hv2; o[3][j] = hg3 * sigmoidf_(hg3) * hv3; }
; #pragma unroll
;                 for (int m = 0; m < 4; ++m) { u32x2 w; w.x = cvt_pk_bf16(o[m][0], o[m][1]); w.y = cvt_pk_bf16(o[m][2], o[m][3]);
;                     *(u32x2*)(Aout + (size_t)(row0 + ai * 128 + m) * FH + hc0 + 4 * n) = w; } } }
	v_rcp_f32_e32 v133, v133
	v_rcp_f32_e32 v152, v152
	v_rcp_f32_e32 v153, v153
	v_pk_fma_f32 v[142:143], v[150:151], v[170:171], v[174:175]
	v_pk_fma_f32 v[194:195], v[138:139], v[170:171], v[174:175]
	v_pk_fma_f32 v[136:137], v[136:137], v[164:165], v[148:149]
	v_pk_fma_f32 v[134:135], v[138:139], v[166:167], v[142:143]
	v_pk_fma_f32 v[194:195], v[146:147], v[166:167], v[194:195]
	v_pk_fma_f32 v[136:137], v[144:145], v[160:161], v[136:137]
	v_pk_mul_f32 v[128:129], v[128:129], v[140:141]
	v_pk_fma_f32 v[134:135], v[146:147], v[162:163], v[134:135]
	v_pk_mul_f32 v[130:131], v[130:131], v[132:133]
	v_pk_fma_f32 v[158:159], v[158:159], v[162:163], v[194:195]
	v_pk_mul_f32 v[152:153], v[154:155], v[152:153]
	v_pk_mul_f32 v[128:129], v[136:137], v[128:129]
	v_pk_mul_f32 v[130:131], v[134:135], v[130:131]
	v_pk_mul_f32 v[152:153], v[158:159], v[152:153]
	v_cvt_pk_bf16_f32 v251, v128, v129
	v_cvt_pk_bf16_f32 v253, v130, v131
	v_or_b32_e32 v130, 3, v246
	v_cvt_pk_bf16_f32 v255, v152, v153
	v_or_b32_e32 v152, 2, v246
	v_mad_i64_i32 v[130:131], s[42:43], v130, s82, v[206:207]
	v_mad_i64_i32 v[152:153], s[42:43], v152, s82, v[206:207]
	v_lshl_add_u64 v[140:141], v[130:131], 0, v[204:205]
	v_lshl_add_u64 v[152:153], v[152:153], 0, v[204:205]
	v_mov_b32_e32 v193, 0
	v_mov_b64_e32 v[194:195], 0
	v_mov_b64_e32 v[136:137], 0
	v_mov_b64_e32 v[138:139], 0
	v_mov_b64_e32 v[128:129], 0
	v_mov_b64_e32 v[130:131], 0
	v_mov_b64_e32 v[132:133], 0
	v_mov_b64_e32 v[134:135], 0
	s_and_saveexec_b64 s[42:43], s[30:31]
	s_cbranch_execz .LBB0_1370
	ds_read_b128 v[132:135], v237 offset:2048
	ds_read_b128 v[136:139], v237 offset:2560
	ds_read_b128 v[128:131], v237 offset:3072
	ds_read_b128 v[192:195], v237 offset:3584
.LBB0_1370:
	s_or_b64 exec, exec, s[42:43]
	s_waitcnt lgkmcnt(0)
	v_mov_b32_dpp v192, v72 row_shr:1 row_mask:0xf bank_mask:0xf
	v_mov_b32_dpp v193, v73 row_shr:1 row_mask:0xf bank_mask:0xf
	v_pk_fma_f32 v[142:143], v[88:89], v[184:185], v[188:189]
	v_mov_b32_dpp v136, v64 row_shr:1 row_mask:0xf bank_mask:0xf
	v_mov_b32_dpp v137, v65 row_shr:1 row_mask:0xf bank_mask:0xf
	v_pk_fma_f32 v[142:143], v[180:181], v[192:193], v[142:143]
	v_mov_b32_dpp v128, v84 row_shr:1 row_mask:0xf bank_mask:0xf
	v_pk_fma_f32 v[136:137], v[176:177], v[136:137], v[142:143]
	v_mov_b32_dpp v129, v85 row_shr:1 row_mask:0xf bank_mask:0xf
	v_exp_f32_e32 v142, v136
	v_exp_f32_e32 v143, v137
	v_pk_fma_f32 v[144:145], v[92:93], v[168:169], v[172:173]
	v_mov_b32_dpp v132, v76 row_shr:1 row_mask:0xf bank_mask:0xf
	v_pk_add_f32 v[142:143], v[142:143], 1.0 op_sel_hi:[1,0]
	v_rcp_f32_e32 v142, v142
	v_rcp_f32_e32 v143, v143
	v_mov_b32_dpp v133, v77 row_shr:1 row_mask:0xf bank_mask:0xf
	v_pk_fma_f32 v[144:145], v[164:165], v[128:129], v[144:145]
	v_mov_b32_dpp v194, v74 row_shr:1 row_mask:0xf bank_mask:0xf
	v_pk_fma_f32 v[132:133], v[160:161], v[132:133], v[144:145]
	v_pk_mul_f32 v[136:137], v[136:137], v[142:143]
	v_mov_b32_dpp v195, v75 row_shr:1 row_mask:0xf bank_mask:0xf
	v_pk_mul_f32 v[132:133], v[132:133], v[136:137]
	v_pk_fma_f32 v[136:137], v[90:91], v[186:187], v[190:191]
	v_mov_b32_dpp v138, v66 row_shr:1 row_mask:0xf bank_mask:0xf
	v_mov_b32_dpp v139, v67 row_shr:1 row_mask:0xf bank_mask:0xf
	v_pk_fma_f32 v[136:137], v[182:183], v[194:195], v[136:137]
	v_mov_b32_dpp v130, v86 row_shr:1 row_mask:0xf bank_mask:0xf
	v_pk_fma_f32 v[136:137], v[178:179], v[138:139], v[136:137]
	v_mov_b32_dpp v131, v87 row_shr:1 row_mask:0xf bank_mask:0xf
	v_exp_f32_e32 v139, v136
	v_exp_f32_e32 v142, v137
	v_cvt_pk_bf16_f32 v144, v132, v133
	v_add_f32_e32 v132, 1.0, v139
	v_rcp_f32_e32 v132, v132
	v_add_f32_e32 v133, 1.0, v142
	v_rcp_f32_e32 v133, v133
	v_pk_fma_f32 v[142:143], v[94:95], v[170:171], v[174:175]
	v_mov_b32_dpp v134, v78 row_shr:1 row_mask:0xf bank_mask:0xf
	v_mov_b32_dpp v135, v79 row_shr:1 row_mask:0xf bank_mask:0xf
	v_pk_mul_f32 v[132:133], v[136:137], v[132:133]
	v_pk_fma_f32 v[136:137], v[68:69], v[184:185], v[188:189]
	v_pk_fma_f32 v[142:143], v[166:167], v[130:131], v[142:143]
	v_pk_fma_f32 v[136:137], v[88:89], v[180:181], v[136:137]
	v_pk_fma_f32 v[134:135], v[162:163], v[134:135], v[142:143]
	v_pk_fma_f32 v[136:137], v[176:177], v[192:193], v[136:137]
	v_add_u32_e32 v146, 0x80, v246
	v_exp_f32_e32 v142, v136
	v_exp_f32_e32 v143, v137
	v_pk_mul_f32 v[132:133], v[134:135], v[132:133]
	v_mov_b64_e32 v[134:135], s[60:61]
	v_cvt_pk_bf16_f32 v145, v132, v133
	v_mad_i64_i32 v[132:133], s[42:43], v146, s82, v[134:135]
	v_lshl_add_u64 v[132:133], v[132:133], 0, v[204:205]
	v_add_f32_e32 v138, 1.0, v142
	v_add_f32_e32 v139, 1.0, v143
	v_rcp_f32_e32 v138, v138
	v_rcp_f32_e32 v139, v139
	v_pk_fma_f32 v[142:143], v[80:81], v[168:169], v[172:173]
	v_pk_fma_f32 v[72:73], v[72:73], v[184:185], v[188:189]
	v_pk_fma_f32 v[142:143], v[92:93], v[164:165], v[142:143]
	v_pk_mul_f32 v[136:137], v[136:137], v[138:139]
	v_pk_fma_f32 v[128:129], v[160:161], v[128:129], v[142:143]
	v_pk_fma_f32 v[84:85], v[84:85], v[168:169], v[172:173]
	v_pk_mul_f32 v[128:129], v[128:129], v[136:137]
	v_pk_fma_f32 v[136:137], v[70:71], v[186:187], v[190:191]
	s_nop 0
	v_pk_fma_f32 v[136:137], v[90:91], v[182:183], v[136:137]
	s_nop 0
	v_pk_fma_f32 v[136:137], v[178:179], v[194:195], v[136:137]
	s_nop 0
	v_exp_f32_e32 v139, v136
	v_exp_f32_e32 v142, v137
	v_cvt_pk_bf16_f32 v138, v128, v129
	v_add_f32_e32 v128, 1.0, v139
	v_rcp_f32_e32 v128, v128
	v_add_f32_e32 v129, 1.0, v142
	v_rcp_f32_e32 v129, v129
	v_pk_fma_f32 v[142:143], v[82:83], v[170:171], v[174:175]
	v_pk_mul_f32 v[128:129], v[136:137], v[128:129]
	v_pk_fma_f32 v[142:143], v[94:95], v[166:167], v[142:143]
	v_pk_fma_f32 v[136:137], v[76:77], v[168:169], v[172:173]
; #define LAS __attribute__((address_space(3)))
; __device__ __forceinline__ float sigmoidf_(float x) { return __builtin_amdgcn_rcpf(1.0f + __expf(-x)); }
;     __device__ __forceinline__ void operator()(AccRef acc, const Unit& u, int wr, int wc, int fr, int fq) const {
;     ...
;                 f32x4 h2v = (f32x4){0.f, 0.f, 0.f, 0.f}, h3v = h2v, h2g = h2v, h3g = h2v;
;                 const int pb = ai * 2 + wr - 1;
;                 if (pb >= 0 && fr == 0) { const LAS float* xp = xch + (pb * 2) * 256 + clb + 4 * n;
;                     h2v = *(const LAS f32x4*)(xp); h3v = *(const LAS f32x4*)(xp + 256); h2g = *(const LAS f32x4*)(xp + 128); h3g = *(const LAS f32x4*)(xp + 256 + 128); }
;                 float o[4][4];
; #pragma unroll
;                 for (int j = 0; j < 4; ++j) {
;                     const float v0 = acc[ai][0][0][n][j], v1 = acc[ai][0][1][n][j], v2 = acc[ai][0][2][n][j], v3 = acc[ai][0][3][n][j];
;                     const float g0 = acc[ai][1][0][n][j], g1 = acc[ai][1][1][n][j], g2 = acc[ai][1][2][n][j], g3 = acc[ai][1][3][n][j];
;                     const float pv3 = dpp_upd<0x111>(h3v[j], v3), pv2 = dpp_upd<0x111>(h2v[j], v2), pg3 = dpp_upd<0x111>(h3g[j], g3), pg2 = dpp_upd<0x111>(h2g[j], g2);
;                     const float hv0 = bvv[j] + w2v[j] * v0 + w1v[j] * pv3 + w0v[j] * pv2, hv1 = bvv[j] + w2v[j] * v1 + w1v[j] * v0 + w0v[j] * pv3;
;                     const float hv2 = bvv[j] + w2v[j] * v2 + w1v[j] * v1 + w0v[j] * v0, hv3 = bvv[j] + w2v[j] * v3 + w1v[j] * v2 + w0v[j] * v1;
;                     const float hg0 = bvg[j] + w2g[j] * g0 + w1g[j] * pg3 + w0g[j] * pg2, hg1 = bvg[j] + w2g[j] * g1 + w1g[j] * g0 + w0g[j] * pg3;
;                     const float hg2 = bvg[j] + w2g[j] * g2 + w1g[j] * g1 + w0g[j] * g0, hg3 = bvg[j] + w2g[j] * g3 + w1g[j] * g2 + w0g[j] * g1;
;                     o[0][j] = hg0 * sigmoidf_(hg0) * hv0; o[1][j] = hg1 * sigmoidf_(hg1) * hv1; o[2][j] = hg2 * sigmoidf_(hg2) * hv2; o[3][j] = hg3 * sigmoidf_(hg3) * hv3; }
; #pragma unroll
;                 for (int m = 0; m < 4; ++m) { u32x2 w; w.x = cvt_pk_bf16(o[m][0], o[m][1]); w.y = cvt_pk_bf16(o[m][2], o[m][3]);
;                     *(u32x2*)(Aout + (size_t)(row0 + ai * 128 + m) * FH + hc0 + 4 * n) = w; } } }
	v_pk_fma_f32 v[130:131], v[162:163], v[130:131], v[142:143]
	v_pk_fma_f32 v[136:137], v[80:81], v[164:165], v[136:137]
	v_pk_mul_f32 v[128:129], v[130:131], v[128:129]
	v_pk_fma_f32 v[130:131], v[64:65], v[184:185], v[188:189]
	v_pk_fma_f32 v[64:65], v[64:65], v[180:181], v[72:73]
	v_pk_fma_f32 v[130:131], v[68:69], v[180:181], v[130:131]
	v_pk_fma_f32 v[64:65], v[68:69], v[176:177], v[64:65]
	v_pk_fma_f32 v[88:89], v[88:89], v[176:177], v[130:131]
	v_pk_fma_f32 v[92:93], v[92:93], v[160:161], v[136:137]
	v_exp_f32_e32 v130, v88
	v_exp_f32_e32 v131, v89
	v_exp_f32_e32 v72, v64
	v_pk_add_f32 v[130:131], v[130:131], 1.0 op_sel_hi:[1,0]
	v_rcp_f32_e32 v130, v130
	v_rcp_f32_e32 v131, v131
	v_pk_fma_f32 v[68:69], v[74:75], v[186:187], v[190:191]
	v_exp_f32_e32 v73, v65
	v_pk_mul_f32 v[88:89], v[88:89], v[130:131]
	v_pk_mul_f32 v[88:89], v[92:93], v[88:89]
	v_pk_fma_f32 v[92:93], v[66:67], v[186:187], v[190:191]
	v_pk_fma_f32 v[66:67], v[66:67], v[182:183], v[68:69]
	v_pk_fma_f32 v[92:93], v[70:71], v[182:183], v[92:93]
	v_pk_fma_f32 v[66:67], v[70:71], v[178:179], v[66:67]
	v_pk_fma_f32 v[90:91], v[90:91], v[178:179], v[92:93]
	v_exp_f32_e32 v93, v90
	v_exp_f32_e32 v68, v66
	v_exp_f32_e32 v69, v67
	v_exp_f32_e32 v130, v91
	v_pk_add_f32 v[72:73], v[72:73], 1.0 op_sel_hi:[1,0]
	v_pk_add_f32 v[68:69], v[68:69], 1.0 op_sel_hi:[1,0]
	v_cvt_pk_bf16_f32 v198, v88, v89
	v_add_f32_e32 v88, 1.0, v93
	v_add_f32_e32 v89, 1.0, v130
	v_rcp_f32_e32 v72, v72
	v_rcp_f32_e32 v73, v73
	v_rcp_f32_e32 v68, v68
	v_rcp_f32_e32 v69, v69
	v_rcp_f32_e32 v88, v88
	v_rcp_f32_e32 v89, v89
	v_pk_fma_f32 v[74:75], v[86:87], v[170:171], v[174:175]
	v_pk_fma_f32 v[130:131], v[78:79], v[170:171], v[174:175]
	v_pk_fma_f32 v[76:77], v[76:77], v[164:165], v[84:85]
	v_pk_fma_f32 v[70:71], v[78:79], v[166:167], v[74:75]
	v_pk_fma_f32 v[130:131], v[82:83], v[166:167], v[130:131]
	v_pk_fma_f32 v[76:77], v[80:81], v[160:161], v[76:77]
	v_pk_mul_f32 v[64:65], v[64:65], v[72:73]
	v_pk_fma_f32 v[70:71], v[82:83], v[162:163], v[70:71]
	v_pk_mul_f32 v[66:67], v[66:67], v[68:69]
	v_pk_fma_f32 v[94:95], v[94:95], v[162:163], v[130:131]
	v_pk_mul_f32 v[88:89], v[90:91], v[88:89]
	v_pk_mul_f32 v[64:65], v[76:77], v[64:65]
	v_pk_mul_f32 v[66:67], v[70:71], v[66:67]
	v_pk_mul_f32 v[88:89], v[94:95], v[88:89]
	v_cvt_pk_bf16_f32 v148, v64, v65
	v_cvt_pk_bf16_f32 v149, v66, v67
	v_add_u32_e32 v66, 0x83, v246
	v_cvt_pk_bf16_f32 v155, v128, v129
	v_add_u32_e32 v128, 0x81, v246
	v_cvt_pk_bf16_f32 v199, v88, v89
	v_add_u32_e32 v88, 0x82, v246
	v_mad_i64_i32 v[66:67], s[42:43], v66, s82, v[134:135]
	v_mad_i64_i32 v[128:129], s[42:43], v128, s82, v[134:135]
	v_mad_i64_i32 v[88:89], s[42:43], v88, s82, v[134:135]
	v_lshl_add_u64 v[82:83], v[66:67], 0, v[204:205]
	v_lshl_add_u64 v[128:129], v[128:129], 0, v[204:205]
	v_lshl_add_u64 v[88:89], v[88:89], 0, v[204:205]
	v_mov_b32_e32 v64, 0
	v_mov_b64_e32 v[70:71], 0
	v_mov_b64_e32 v[72:73], 0
	v_mov_b64_e32 v[78:79], 0
	v_mov_b64_e32 v[80:81], 0
	v_mov_b64_e32 v[66:67], 0
	v_mov_b64_e32 v[68:69], 0
	v_mov_b64_e32 v[74:75], 0
	v_mov_b64_e32 v[76:77], 0
	v_mov_b32_e32 v154, v138
	s_and_saveexec_b64 s[42:43], s[28:29]
	s_cbranch_execz .LBB0_1372
	ds_read_b128 v[74:77], v242
	ds_read_b128 v[66:69], v241
	ds_read_b128 v[78:81], v240
	ds_read_b128 v[70:73], v239
; #define LAS __attribute__((address_space(3)))
; __device__ __forceinline__ float sigmoidf_(float x) { return __builtin_amdgcn_rcpf(1.0f + __expf(-x)); }
;     __device__ __forceinline__ void operator()(AccRef acc, const Unit& u, int wr, int wc, int fr, int fq) const {
;     ...
;                 f32x4 h2v = (f32x4){0.f, 0.f, 0.f, 0.f}, h3v = h2v, h2g = h2v, h3g = h2v;
;                 const int pb = ai * 2 + wr - 1;
;                 if (pb >= 0 && fr == 0) { const LAS float* xp = xch + (pb * 2) * 256 + clb + 4 * n;
;                     h2v = *(const LAS f32x4*)(xp); h3v = *(const LAS f32x4*)(xp + 256); h2g = *(const LAS f32x4*)(xp + 128); h3g = *(const LAS f32x4*)(xp + 256 + 128); }
;                 float o[4][4];
; #pragma unroll
;                 for (int j = 0; j < 4; ++j) {
;                     const float v0 = acc[ai][0][0][n][j], v1 = acc[ai][0][1][n][j], v2 = acc[ai][0][2][n][j], v3 = acc[ai][0][3][n][j];
;                     const float g0 = acc[ai][1][0][n][j], g1 = acc[ai][1][1][n][j], g2 = acc[ai][1][2][n][j], g3 = acc[ai][1][3][n][j];
;                     const float pv3 = dpp_upd<0x111>(h3v[j], v3), pv2 = dpp_upd<0x111>(h2v[j], v2), pg3 = dpp_upd<0x111>(h3g[j], g3), pg2 = dpp_upd<0x111>(h2g[j], g2);
;                     const float hv0 = bvv[j] + w2v[j] * v0 + w1v[j] * pv3 + w0v[j] * pv2, hv1 = bvv[j] + w2v[j] * v1 + w1v[j] * v0 + w0v[j] * pv3;
;                     const float hv2 = bvv[j] + w2v[j] * v2 + w1v[j] * v1 + w0v[j] * v0, hv3 = bvv[j] + w2v[j] * v3 + w1v[j] * v2 + w0v[j] * v1;
;                     const float hg0 = bvg[j] + w2g[j] * g0 + w1g[j] * pg3 + w0g[j] * pg2, hg1 = bvg[j] + w2g[j] * g1 + w1g[j] * g0 + w0g[j] * pg3;
;                     const float hg2 = bvg[j] + w2g[j] * g2 + w1g[j] * g1 + w0g[j] * g0, hg3 = bvg[j] + w2g[j] * g3 + w1g[j] * g2 + w0g[j] * g1;
;                     o[0][j] = hg0 * sigmoidf_(hg0) * hv0; o[1][j] = hg1 * sigmoidf_(hg1) * hv1; o[2][j] = hg2 * sigmoidf_(hg2) * hv2; o[3][j] = hg3 * sigmoidf_(hg3) * hv3; }
; #pragma unroll
;                 for (int m = 0; m < 4; ++m) { u32x2 w; w.x = cvt_pk_bf16(o[m][0], o[m][1]); w.y = cvt_pk_bf16(o[m][2], o[m][3]);
;                     *(u32x2*)(Aout + (size_t)(row0 + ai * 128 + m) * FH + hc0 + 4 * n) = w; } } }
.LBB0_1372:
	s_or_b64 exec, exec, s[42:43]
	s_waitcnt lgkmcnt(0)
	v_mov_b32_dpp v70, v44 row_shr:1 row_mask:0xf bank_mask:0xf
	v_mov_b32_dpp v71, v45 row_shr:1 row_mask:0xf bank_mask:0xf
	s_waitcnt vmcnt(0)
	v_pk_fma_f32 v[84:85], v[56:57], v[120:121], v[124:125]
	v_mov_b32_dpp v78, v32 row_shr:1 row_mask:0xf bank_mask:0xf
	v_mov_b32_dpp v79, v33 row_shr:1 row_mask:0xf bank_mask:0xf
	v_pk_fma_f32 v[84:85], v[116:117], v[70:71], v[84:85]
	v_mov_b32_dpp v66, v52 row_shr:1 row_mask:0xf bank_mask:0xf
	v_pk_fma_f32 v[78:79], v[112:113], v[78:79], v[84:85]
	v_mov_b32_dpp v67, v53 row_shr:1 row_mask:0xf bank_mask:0xf
	v_exp_f32_e32 v84, v78
	v_exp_f32_e32 v85, v79
	v_pk_fma_f32 v[86:87], v[60:61], v[104:105], v[108:109]
	v_pk_add_f32 v[84:85], v[84:85], 1.0 op_sel_hi:[1,0]
	v_rcp_f32_e32 v84, v84
	v_rcp_f32_e32 v85, v85
	v_mov_b32_dpp v74, v40 row_shr:1 row_mask:0xf bank_mask:0xf
	v_mov_b32_dpp v75, v41 row_shr:1 row_mask:0xf bank_mask:0xf
	v_pk_fma_f32 v[86:87], v[100:101], v[66:67], v[86:87]
	v_pk_mul_f32 v[78:79], v[78:79], v[84:85]
	v_pk_fma_f32 v[74:75], v[96:97], v[74:75], v[86:87]
	v_mov_b32_dpp v72, v46 row_shr:1 row_mask:0xf bank_mask:0xf
	v_mov_b32_dpp v73, v47 row_shr:1 row_mask:0xf bank_mask:0xf
	v_pk_mul_f32 v[74:75], v[74:75], v[78:79]
	v_pk_fma_f32 v[78:79], v[58:59], v[122:123], v[126:127]
	v_mov_b32_dpp v80, v34 row_shr:1 row_mask:0xf bank_mask:0xf
	v_mov_b32_dpp v81, v35 row_shr:1 row_mask:0xf bank_mask:0xf
	v_pk_fma_f32 v[78:79], v[118:119], v[72:73], v[78:79]
	v_mov_b32_dpp v68, v54 row_shr:1 row_mask:0xf bank_mask:0xf
	v_pk_fma_f32 v[78:79], v[114:115], v[80:81], v[78:79]
	v_mov_b32_dpp v69, v55 row_shr:1 row_mask:0xf bank_mask:0xf
	v_exp_f32_e32 v80, v78
	v_exp_f32_e32 v81, v79
	v_pk_fma_f32 v[84:85], v[62:63], v[106:107], v[110:111]
	v_pk_add_f32 v[80:81], v[80:81], 1.0 op_sel_hi:[1,0]
	v_rcp_f32_e32 v80, v80
	v_rcp_f32_e32 v81, v81
	v_mov_b32_dpp v76, v42 row_shr:1 row_mask:0xf bank_mask:0xf
	v_mov_b32_dpp v77, v43 row_shr:1 row_mask:0xf bank_mask:0xf
	v_pk_fma_f32 v[84:85], v[102:103], v[68:69], v[84:85]
	v_pk_mul_f32 v[78:79], v[78:79], v[80:81]
	v_pk_fma_f32 v[76:77], v[98:99], v[76:77], v[84:85]
	v_cvt_pk_bf16_f32 v92, v74, v75
	v_pk_mul_f32 v[76:77], v[76:77], v[78:79]
	v_pk_fma_f32 v[44:45], v[44:45], v[120:121], v[124:125]
	v_cvt_pk_bf16_f32 v93, v76, v77
	v_pk_fma_f32 v[76:77], v[36:37], v[120:121], v[124:125]
	v_mov_b32_e32 v90, v247
	v_mov_b32_e32 v91, v248
	global_store_dwordx4 v[202:203], v[90:93], off
	v_pk_fma_f32 v[76:77], v[56:57], v[116:117], v[76:77]
	v_pk_fma_f32 v[52:53], v[52:53], v[104:105], v[108:109]
	v_pk_fma_f32 v[70:71], v[112:113], v[70:71], v[76:77]
	s_nop 0
	v_exp_f32_e32 v74, v70
	v_exp_f32_e32 v75, v71
	s_nop 0
	v_pk_add_f32 v[74:75], v[74:75], 1.0 op_sel_hi:[1,0]
	v_rcp_f32_e32 v74, v74
	v_rcp_f32_e32 v75, v75
	v_pk_fma_f32 v[76:77], v[48:49], v[104:105], v[108:109]
	v_pk_mul_f32 v[70:71], v[70:71], v[74:75]
	v_pk_fma_f32 v[76:77], v[60:61], v[100:101], v[76:77]
	v_pk_fma_f32 v[74:75], v[50:51], v[106:107], v[110:111]
	v_pk_fma_f32 v[66:67], v[96:97], v[66:67], v[76:77]
	v_pk_fma_f32 v[74:75], v[62:63], v[102:103], v[74:75]
	v_pk_mul_f32 v[66:67], v[66:67], v[70:71]
	v_pk_fma_f32 v[70:71], v[38:39], v[122:123], v[126:127]
	v_pk_fma_f32 v[68:69], v[98:99], v[68:69], v[74:75]
	v_pk_fma_f32 v[70:71], v[58:59], v[118:119], v[70:71]
	v_cvt_pk_bf16_f32 v136, v66, v67
	v_pk_fma_f32 v[70:71], v[114:115], v[72:73], v[70:71]
	s_nop 0
	v_exp_f32_e32 v72, v70
	v_exp_f32_e32 v73, v71
	s_nop 0
	v_pk_add_f32 v[72:73], v[72:73], 1.0 op_sel_hi:[1,0]
	v_rcp_f32_e32 v72, v72
	v_rcp_f32_e32 v73, v73
	s_nop 0
	v_pk_mul_f32 v[70:71], v[70:71], v[72:73]
	s_nop 0
	v_pk_mul_f32 v[68:69], v[68:69], v[70:71]
	s_nop 0
	v_cvt_pk_bf16_f32 v137, v68, v69
	v_pk_fma_f32 v[68:69], v[32:33], v[120:121], v[124:125]
	v_mov_b32_e32 v134, v249
	v_mov_b32_e32 v135, v250
	global_store_dwordx4 v[196:197], v[134:137], off
	v_pk_fma_f32 v[68:69], v[36:37], v[116:117], v[68:69]
	v_pk_fma_f32 v[32:33], v[32:33], v[116:117], v[44:45]
	v_pk_fma_f32 v[56:57], v[56:57], v[112:113], v[68:69]
	v_pk_fma_f32 v[32:33], v[36:37], v[112:113], v[32:33]
	v_exp_f32_e32 v66, v56
	v_exp_f32_e32 v67, v57
	s_nop 0
	v_pk_add_f32 v[66:67], v[66:67], 1.0 op_sel_hi:[1,0]
	v_rcp_f32_e32 v66, v66
	v_rcp_f32_e32 v67, v67
	v_pk_fma_f32 v[68:69], v[40:41], v[104:105], v[108:109]
	v_exp_f32_e32 v44, v32
	v_pk_fma_f32 v[68:69], v[48:49], v[100:101], v[68:69]
	v_pk_mul_f32 v[56:57], v[56:57], v[66:67]
	v_pk_fma_f32 v[60:61], v[60:61], v[96:97], v[68:69]
	v_pk_fma_f32 v[36:37], v[46:47], v[122:123], v[126:127]
	v_pk_mul_f32 v[56:57], v[60:61], v[56:57]
	v_pk_fma_f32 v[60:61], v[34:35], v[122:123], v[126:127]
	v_pk_fma_f32 v[34:35], v[34:35], v[118:119], v[36:37]
	v_pk_fma_f32 v[60:61], v[38:39], v[118:119], v[60:61]
	v_pk_fma_f32 v[34:35], v[38:39], v[114:115], v[34:35]
	v_pk_fma_f32 v[58:59], v[58:59], v[114:115], v[60:61]
	v_exp_f32_e32 v60, v58
	v_exp_f32_e32 v45, v33
	v_exp_f32_e32 v36, v34
	v_exp_f32_e32 v37, v35
	v_exp_f32_e32 v61, v59
	v_cvt_pk_bf16_f32 v164, v56, v57
	v_pk_add_f32 v[44:45], v[44:45], 1.0 op_sel_hi:[1,0]
	v_pk_add_f32 v[36:37], v[36:37], 1.0 op_sel_hi:[1,0]
	v_pk_add_f32 v[60:61], v[60:61], 1.0 op_sel_hi:[1,0]
	v_rcp_f32_e32 v44, v44
	v_rcp_f32_e32 v45, v45
	v_rcp_f32_e32 v36, v36
	v_rcp_f32_e32 v37, v37
	v_rcp_f32_e32 v60, v60
	v_rcp_f32_e32 v61, v61
	v_pk_fma_f32 v[46:47], v[54:55], v[106:107], v[110:111]
	v_pk_fma_f32 v[66:67], v[42:43], v[106:107], v[110:111]
	v_pk_fma_f32 v[40:41], v[40:41], v[100:101], v[52:53]
	v_pk_fma_f32 v[38:39], v[42:43], v[102:103], v[46:47]
	v_pk_fma_f32 v[66:67], v[50:51], v[102:103], v[66:67]
	v_pk_fma_f32 v[40:41], v[48:49], v[96:97], v[40:41]
	v_pk_mul_f32 v[32:33], v[32:33], v[44:45]
	v_pk_fma_f32 v[38:39], v[50:51], v[98:99], v[38:39]
	v_pk_mul_f32 v[34:35], v[34:35], v[36:37]
	v_pk_fma_f32 v[62:63], v[62:63], v[98:99], v[66:67]
	v_pk_mul_f32 v[58:59], v[58:59], v[60:61]
	v_pk_mul_f32 v[32:33], v[40:41], v[32:33]
	v_pk_mul_f32 v[34:35], v[38:39], v[34:35]
	v_pk_mul_f32 v[58:59], v[62:63], v[58:59]
	v_cvt_pk_bf16_f32 v160, v32, v33
	v_cvt_pk_bf16_f32 v161, v34, v35
	v_cvt_pk_bf16_f32 v57, v58, v59
	v_mov_b32_e32 v158, v251
	v_mov_b32_e32 v159, v253
	global_store_dwordx4 v[140:141], v[158:161], off
	v_mov_b32_e32 v65, 0
	v_mov_b64_e32 v[66:67], 0
	v_mov_b64_e32 v[40:41], 0
	v_mov_b64_e32 v[42:43], 0
	v_mov_b64_e32 v[32:33], 0
	v_mov_b64_e32 v[34:35], 0
	v_mov_b64_e32 v[36:37], 0
	v_mov_b64_e32 v[38:39], 0
	v_mov_b32_e32 v162, v254
	v_mov_b32_e32 v163, v255
	v_mov_b32_e32 v165, v57
	global_store_dwordx4 v[152:153], v[162:165], off
	s_and_saveexec_b64 s[42:43], s[30:31]
	s_cbranch_execz .LBB0_1355
	ds_read_b128 v[36:39], v237 offset:2064
	ds_read_b128 v[40:43], v237 offset:2576
	ds_read_b128 v[32:35], v237 offset:3088
	ds_read_b128 v[64:67], v237 offset:3600
	s_branch .LBB0_1355

; #define LAS __attribute__((address_space(3)))
; __device__ __forceinline__ float sigmoidf_(float x) { return __builtin_amdgcn_rcpf(1.0f + __expf(-x)); }
;     __device__ __forceinline__ void operator()(AccRef acc, const Unit& u, int wr, int wc, int fr, int fq) const {
;     ...
;                 f32x4 h2v = (f32x4){0.f, 0.f, 0.f, 0.f}, h3v = h2v, h2g = h2v, h3g = h2v;
;                 const int pb = ai * 2 + wr - 1;
;                 if (pb >= 0 && fr == 0) { const LAS float* xp = xch + (pb * 2) * 256 + clb + 4 * n;
;                     h2v = *(const LAS f32x4*)(xp); h3v = *(const LAS f32x4*)(xp + 256); h2g = *(const LAS f32x4*)(xp + 128); h3g = *(const LAS f32x4*)(xp + 256 + 128); }
;                 float o[4][4];
; #pragma unroll
;                 for (int j = 0; j < 4; ++j) {
;                     const float v0 = acc[ai][0][0][n][j], v1 = acc[ai][0][1][n][j], v2 = acc[ai][0][2][n][j], v3 = acc[ai][0][3][n][j];
;                     const float g0 = acc[ai][1][0][n][j], g1 = acc[ai][1][1][n][j], g2 = acc[ai][1][2][n][j], g3 = acc[ai][1][3][n][j];
;                     const float pv3 = dpp_upd<0x111>(h3v[j], v3), pv2 = dpp_upd<0x111>(h2v[j], v2), pg3 = dpp_upd<0x111>(h3g[j], g3), pg2 = dpp_upd<0x111>(h2g[j], g2);
;                     const float hv0 = bvv[j] + w2v[j] * v0 + w1v[j] * pv3 + w0v[j] * pv2, hv1 = bvv[j] + w2v[j] * v1 + w1v[j] * v0 + w0v[j] * pv3;
;                     const float hv2 = bvv[j] + w2v[j] * v2 + w1v[j] * v1 + w0v[j] * v0, hv3 = bvv[j] + w2v[j] * v3 + w1v[j] * v2 + w0v[j] * v1;
;                     const float hg0 = bvg[j] + w2g[j] * g0 + w1g[j] * pg3 + w0g[j] * pg2, hg1 = bvg[j] + w2g[j] * g1 + w1g[j] * g0 + w0g[j] * pg3;
;                     const float hg2 = bvg[j] + w2g[j] * g2 + w1g[j] * g1 + w0g[j] * g0, hg3 = bvg[j] + w2g[j] * g3 + w1g[j] * g2 + w0g[j] * g1;
;                     o[0][j] = hg0 * sigmoidf_(hg0) * hv0; o[1][j] = hg1 * sigmoidf_(hg1) * hv1; o[2][j] = hg2 * sigmoidf_(hg2) * hv2; o[3][j] = hg3 * sigmoidf_(hg3) * hv3; }
; #pragma unroll
;                 for (int m = 0; m < 4; ++m) { u32x2 w; w.x = cvt_pk_bf16(o[m][0], o[m][1]); w.y = cvt_pk_bf16(o[m][2], o[m][3]);
;                     *(u32x2*)(Aout + (size_t)(row0 + ai * 128 + m) * FH + hc0 + 4 * n) = w; } } }
.LBB0_1936:
	s_or_b64 exec, exec, s[34:35]
	s_waitcnt lgkmcnt(0)
	v_mov_b32_dpp v64, v8 row_shr:1 row_mask:0xf bank_mask:0xf
	v_mov_b32_dpp v65, v9 row_shr:1 row_mask:0xf bank_mask:0xf
	v_pk_fma_f32 v[44:45], v[24:25], v[120:121], v[124:125]
	v_mov_b32_dpp v40, v0 row_shr:1 row_mask:0xf bank_mask:0xf
	v_mov_b32_dpp v41, v1 row_shr:1 row_mask:0xf bank_mask:0xf
	v_pk_fma_f32 v[44:45], v[116:117], v[64:65], v[44:45]
	v_mov_b32_dpp v32, v20 row_shr:1 row_mask:0xf bank_mask:0xf
	v_pk_fma_f32 v[40:41], v[112:113], v[40:41], v[44:45]
	v_mov_b32_dpp v33, v21 row_shr:1 row_mask:0xf bank_mask:0xf
	v_exp_f32_e32 v44, v40
	v_exp_f32_e32 v45, v41
	v_pk_fma_f32 v[46:47], v[28:29], v[104:105], v[108:109]
	v_mov_b32_dpp v36, v12 row_shr:1 row_mask:0xf bank_mask:0xf
	v_pk_add_f32 v[44:45], v[44:45], 1.0 op_sel_hi:[1,0]
	v_rcp_f32_e32 v44, v44
	v_rcp_f32_e32 v45, v45
	v_mov_b32_dpp v37, v13 row_shr:1 row_mask:0xf bank_mask:0xf
	v_pk_fma_f32 v[46:47], v[100:101], v[32:33], v[46:47]
	v_mov_b32_dpp v66, v10 row_shr:1 row_mask:0xf bank_mask:0xf
	v_pk_fma_f32 v[36:37], v[96:97], v[36:37], v[46:47]
	v_pk_mul_f32 v[40:41], v[40:41], v[44:45]
	v_mov_b32_dpp v67, v11 row_shr:1 row_mask:0xf bank_mask:0xf
	v_pk_mul_f32 v[36:37], v[36:37], v[40:41]
	v_pk_fma_f32 v[40:41], v[26:27], v[122:123], v[126:127]
	v_mov_b32_dpp v42, v2 row_shr:1 row_mask:0xf bank_mask:0xf
	v_mov_b32_dpp v43, v3 row_shr:1 row_mask:0xf bank_mask:0xf
	v_pk_fma_f32 v[40:41], v[118:119], v[66:67], v[40:41]
	v_cvt_pk_bf16_f32 v146, v36, v37
	v_pk_fma_f32 v[40:41], v[114:115], v[42:43], v[40:41]
	v_mov_b32_dpp v34, v22 row_shr:1 row_mask:0xf bank_mask:0xf
	v_exp_f32_e32 v42, v40
	v_exp_f32_e32 v43, v41
	v_mov_b32_dpp v35, v23 row_shr:1 row_mask:0xf bank_mask:0xf
	v_pk_add_f32 v[42:43], v[42:43], 1.0 op_sel_hi:[1,0]
	v_rcp_f32_e32 v42, v42
	v_rcp_f32_e32 v43, v43
	v_pk_fma_f32 v[44:45], v[30:31], v[106:107], v[110:111]
	v_mov_b32_dpp v38, v14 row_shr:1 row_mask:0xf bank_mask:0xf
	v_mov_b32_dpp v39, v15 row_shr:1 row_mask:0xf bank_mask:0xf
	v_pk_fma_f32 v[44:45], v[102:103], v[34:35], v[44:45]
	v_pk_mul_f32 v[40:41], v[40:41], v[42:43]
	v_pk_fma_f32 v[38:39], v[98:99], v[38:39], v[44:45]
	v_pk_fma_f32 v[8:9], v[8:9], v[120:121], v[124:125]
	v_pk_mul_f32 v[38:39], v[38:39], v[40:41]
	v_pk_fma_f32 v[20:21], v[20:21], v[104:105], v[108:109]
	v_cvt_pk_bf16_f32 v147, v38, v39
	v_pk_fma_f32 v[38:39], v[4:5], v[120:121], v[124:125]
	global_store_dwordx4 v[132:133], v[144:147], off
	v_pk_fma_f32 v[38:39], v[24:25], v[116:117], v[38:39]
	s_and_b64 vcc, exec, s[10:11]
	v_pk_fma_f32 v[38:39], v[112:113], v[64:65], v[38:39]
	s_mov_b32 s35, s24
	v_exp_f32_e32 v36, v38
	v_exp_f32_e32 v37, v39
	s_mov_b32 s34, s26
	s_mov_b64 s[38:39], s[30:31]
	v_pk_add_f32 v[36:37], v[36:37], 1.0 op_sel_hi:[1,0]
	v_rcp_f32_e32 v36, v36
	v_rcp_f32_e32 v37, v37
	v_pk_fma_f32 v[40:41], v[16:17], v[104:105], v[108:109]
	s_mov_b64 s[36:37], s[28:29]
	v_pk_fma_f32 v[40:41], v[28:29], v[100:101], v[40:41]
	v_pk_mul_f32 v[36:37], v[38:39], v[36:37]
	v_pk_fma_f32 v[32:33], v[96:97], v[32:33], v[40:41]
	v_pk_fma_f32 v[40:41], v[18:19], v[106:107], v[110:111]
	v_pk_mul_f32 v[32:33], v[32:33], v[36:37]
	v_pk_fma_f32 v[36:37], v[6:7], v[122:123], v[126:127]
	v_cvt_pk_bf16_f32 v156, v32, v33
	v_pk_fma_f32 v[36:37], v[26:27], v[118:119], v[36:37]
	v_pk_fma_f32 v[40:41], v[30:31], v[102:103], v[40:41]
	v_pk_fma_f32 v[36:37], v[114:115], v[66:67], v[36:37]
	v_pk_fma_f32 v[34:35], v[98:99], v[34:35], v[40:41]
	v_exp_f32_e32 v38, v36
	v_exp_f32_e32 v39, v37
	s_nop 0
	v_pk_add_f32 v[38:39], v[38:39], 1.0 op_sel_hi:[1,0]
	v_rcp_f32_e32 v38, v38
	v_rcp_f32_e32 v39, v39
	s_nop 0
	v_pk_mul_f32 v[36:37], v[36:37], v[38:39]
	s_nop 0
	v_pk_mul_f32 v[34:35], v[34:35], v[36:37]
	s_nop 0
	v_cvt_pk_bf16_f32 v157, v34, v35
	v_pk_fma_f32 v[34:35], v[0:1], v[120:121], v[124:125]
	global_store_dwordx4 v[128:129], v[154:157], off
	v_pk_fma_f32 v[34:35], v[4:5], v[116:117], v[34:35]
	v_pk_fma_f32 v[0:1], v[0:1], v[116:117], v[8:9]
	v_pk_fma_f32 v[24:25], v[24:25], v[112:113], v[34:35]
	v_pk_fma_f32 v[0:1], v[4:5], v[112:113], v[0:1]
	v_exp_f32_e32 v32, v24
	v_exp_f32_e32 v33, v25
	v_exp_f32_e32 v8, v0
	v_pk_add_f32 v[32:33], v[32:33], 1.0 op_sel_hi:[1,0]
	v_rcp_f32_e32 v32, v32
	v_rcp_f32_e32 v33, v33
	v_pk_fma_f32 v[34:35], v[12:13], v[104:105], v[108:109]
	v_pk_fma_f32 v[4:5], v[10:11], v[122:123], v[126:127]
	v_pk_fma_f32 v[34:35], v[16:17], v[100:101], v[34:35]
	v_pk_mul_f32 v[24:25], v[24:25], v[32:33]
	v_pk_fma_f32 v[28:29], v[28:29], v[96:97], v[34:35]
	v_pk_mul_f32 v[24:25], v[28:29], v[24:25]
	v_pk_fma_f32 v[28:29], v[2:3], v[122:123], v[126:127]
	v_pk_fma_f32 v[2:3], v[2:3], v[118:119], v[4:5]
	v_pk_fma_f32 v[28:29], v[6:7], v[118:119], v[28:29]
	v_pk_fma_f32 v[2:3], v[6:7], v[114:115], v[2:3]
	v_pk_fma_f32 v[26:27], v[26:27], v[114:115], v[28:29]
	v_exp_f32_e32 v28, v26
	v_exp_f32_e32 v29, v27
	v_exp_f32_e32 v9, v1
	v_exp_f32_e32 v4, v2
	v_exp_f32_e32 v5, v3
	v_cvt_pk_bf16_f32 v200, v24, v25
	v_pk_add_f32 v[28:29], v[28:29], 1.0 op_sel_hi:[1,0]
	v_pk_add_f32 v[8:9], v[8:9], 1.0 op_sel_hi:[1,0]
	v_pk_add_f32 v[4:5], v[4:5], 1.0 op_sel_hi:[1,0]
	v_rcp_f32_e32 v28, v28
	v_rcp_f32_e32 v29, v29
	v_rcp_f32_e32 v8, v8
	v_rcp_f32_e32 v9, v9
	v_rcp_f32_e32 v4, v4
	v_rcp_f32_e32 v5, v5
	v_pk_fma_f32 v[32:33], v[14:15], v[106:107], v[110:111]
	v_pk_fma_f32 v[10:11], v[22:23], v[106:107], v[110:111]
	v_pk_fma_f32 v[32:33], v[18:19], v[102:103], v[32:33]
	v_pk_fma_f32 v[12:13], v[12:13], v[100:101], v[20:21]
	v_pk_fma_f32 v[6:7], v[14:15], v[102:103], v[10:11]
	v_pk_fma_f32 v[30:31], v[30:31], v[98:99], v[32:33]
	v_pk_mul_f32 v[26:27], v[26:27], v[28:29]
	v_pk_fma_f32 v[12:13], v[16:17], v[96:97], v[12:13]
	v_pk_mul_f32 v[0:1], v[0:1], v[8:9]
	v_pk_fma_f32 v[6:7], v[18:19], v[98:99], v[6:7]
	v_pk_mul_f32 v[2:3], v[2:3], v[4:5]
	v_pk_mul_f32 v[26:27], v[30:31], v[26:27]
	v_pk_mul_f32 v[0:1], v[12:13], v[0:1]
	v_pk_mul_f32 v[2:3], v[6:7], v[2:3]
	v_cvt_pk_bf16_f32 v201, v26, v27
	v_cvt_pk_bf16_f32 v150, v0, v1
	v_cvt_pk_bf16_f32 v151, v2, v3
	global_store_dwordx4 v[88:89], v[198:201], off
	global_store_dwordx4 v[82:83], v[148:151], off
	s_cbranch_vccnz .LBB0_1955

; #define LAS __attribute__((address_space(3)))
; __device__ __forceinline__ float sigmoidf_(float x) { return __builtin_amdgcn_rcpf(1.0f + __expf(-x)); }
;     __device__ __forceinline__ void operator()(AccRef acc, const Unit& u, int wr, int wc, int fr, int fq) const {
;     ...
;                 f32x4 h2v = (f32x4){0.f, 0.f, 0.f, 0.f}, h3v = h2v, h2g = h2v, h3g = h2v;
;                 const int pb = ai * 2 + wr - 1;
;                 if (pb >= 0 && fr == 0) { const LAS float* xp = xch + (pb * 2) * 256 + clb + 4 * n;
;                     h2v = *(const LAS f32x4*)(xp); h3v = *(const LAS f32x4*)(xp + 256); h2g = *(const LAS f32x4*)(xp + 128); h3g = *(const LAS f32x4*)(xp + 256 + 128); }
;                 float o[4][4];
; #pragma unroll
;                 for (int j = 0; j < 4; ++j) {
;                     const float v0 = acc[ai][0][0][n][j], v1 = acc[ai][0][1][n][j], v2 = acc[ai][0][2][n][j], v3 = acc[ai][0][3][n][j];
;                     const float g0 = acc[ai][1][0][n][j], g1 = acc[ai][1][1][n][j], g2 = acc[ai][1][2][n][j], g3 = acc[ai][1][3][n][j];
;                     const float pv3 = dpp_upd<0x111>(h3v[j], v3), pv2 = dpp_upd<0x111>(h2v[j], v2), pg3 = dpp_upd<0x111>(h3g[j], g3), pg2 = dpp_upd<0x111>(h2g[j], g2);
;                     const float hv0 = bvv[j] + w2v[j] * v0 + w1v[j] * pv3 + w0v[j] * pv2, hv1 = bvv[j] + w2v[j] * v1 + w1v[j] * v0 + w0v[j] * pv3;
;                     const float hv2 = bvv[j] + w2v[j] * v2 + w1v[j] * v1 + w0v[j] * v0, hv3 = bvv[j] + w2v[j] * v3 + w1v[j] * v2 + w0v[j] * v1;
;                     const float hg0 = bvg[j] + w2g[j] * g0 + w1g[j] * pg3 + w0g[j] * pg2, hg1 = bvg[j] + w2g[j] * g1 + w1g[j] * g0 + w0g[j] * pg3;
;                     const float hg2 = bvg[j] + w2g[j] * g2 + w1g[j] * g1 + w0g[j] * g0, hg3 = bvg[j] + w2g[j] * g3 + w1g[j] * g2 + w0g[j] * g1;
;                     o[0][j] = hg0 * sigmoidf_(hg0) * hv0; o[1][j] = hg1 * sigmoidf_(hg1) * hv1; o[2][j] = hg2 * sigmoidf_(hg2) * hv2; o[3][j] = hg3 * sigmoidf_(hg3) * hv3; }
; #pragma unroll
;                 for (int m = 0; m < 4; ++m) { u32x2 w; w.x = cvt_pk_bf16(o[m][0], o[m][1]); w.y = cvt_pk_bf16(o[m][2], o[m][3]);
;                     *(u32x2*)(Aout + (size_t)(row0 + ai * 128 + m) * FH + hc0 + 4 * n) = w; } } }
.LBB0_1947:
	s_or_b64 exec, exec, s[40:41]
	v_pk_fma_f32 v[246:247], v[152:153], v[184:185], v[188:189]
	v_mov_b32_dpp v206, v128 row_shr:1 row_mask:0xf bank_mask:0xf
	v_mov_b32_dpp v207, v129 row_shr:1 row_mask:0xf bank_mask:0xf
	v_pk_fma_f32 v[246:247], v[180:181], v[198:199], v[246:247]
	v_mov_b32_dpp v194, v148 row_shr:1 row_mask:0xf bank_mask:0xf
	v_pk_fma_f32 v[206:207], v[176:177], v[206:207], v[246:247]
	v_mov_b32_dpp v195, v149 row_shr:1 row_mask:0xf bank_mask:0xf
	v_exp_f32_e32 v246, v206
	v_exp_f32_e32 v247, v207
	v_pk_fma_f32 v[248:249], v[156:157], v[168:169], v[172:173]
	v_pk_add_f32 v[246:247], v[246:247], 1.0 op_sel_hi:[1,0]
	v_rcp_f32_e32 v246, v246
	v_rcp_f32_e32 v247, v247
	v_mov_b32_dpp v202, v136 row_shr:1 row_mask:0xf bank_mask:0xf
	v_mov_b32_dpp v203, v137 row_shr:1 row_mask:0xf bank_mask:0xf
	v_pk_fma_f32 v[248:249], v[164:165], v[194:195], v[248:249]
	v_pk_mul_f32 v[206:207], v[206:207], v[246:247]
	v_pk_fma_f32 v[202:203], v[160:161], v[202:203], v[248:249]
	v_mov_b32_dpp v200, v142 row_shr:1 row_mask:0xf bank_mask:0xf
	v_mov_b32_dpp v201, v143 row_shr:1 row_mask:0xf bank_mask:0xf
	v_pk_mul_f32 v[202:203], v[202:203], v[206:207]
	v_pk_fma_f32 v[206:207], v[154:155], v[186:187], v[190:191]
	v_mov_b32_dpp v208, v130 row_shr:1 row_mask:0xf bank_mask:0xf
	v_mov_b32_dpp v209, v131 row_shr:1 row_mask:0xf bank_mask:0xf
	v_pk_fma_f32 v[206:207], v[182:183], v[200:201], v[206:207]
	v_mov_b32_dpp v196, v150 row_shr:1 row_mask:0xf bank_mask:0xf
	v_pk_fma_f32 v[206:207], v[178:179], v[208:209], v[206:207]
	v_mov_b32_dpp v197, v151 row_shr:1 row_mask:0xf bank_mask:0xf
	v_exp_f32_e32 v193, v206
	v_exp_f32_e32 v209, v207
	v_cvt_pk_bf16_f32 v208, v202, v203
	v_add_f32_e32 v193, 1.0, v193
	v_rcp_f32_e32 v202, v193
	v_add_f32_e32 v193, 1.0, v209
	v_rcp_f32_e32 v203, v193
	v_pk_fma_f32 v[246:247], v[158:159], v[170:171], v[174:175]
	v_mov_b32_dpp v204, v138 row_shr:1 row_mask:0xf bank_mask:0xf
	v_mov_b32_dpp v205, v139 row_shr:1 row_mask:0xf bank_mask:0xf
	v_pk_fma_f32 v[246:247], v[166:167], v[196:197], v[246:247]
	v_pk_mul_f32 v[202:203], v[206:207], v[202:203]
	v_pk_fma_f32 v[204:205], v[162:163], v[204:205], v[246:247]
	v_lshl_add_u32 v245, s34, 8, v235
	v_pk_mul_f32 v[202:203], v[204:205], v[202:203]
	v_lshlrev_b64 v[204:205], 1, v[232:233]
	v_pk_fma_f32 v[232:233], v[132:133], v[184:185], v[188:189]
	v_mov_b64_e32 v[206:207], s[60:61]
	v_pk_fma_f32 v[232:233], v[152:153], v[180:181], v[232:233]
	v_cvt_pk_bf16_f32 v247, v202, v203
	v_pk_fma_f32 v[198:199], v[176:177], v[198:199], v[232:233]
	v_mad_i64_i32 v[202:203], s[34:35], v245, s63, v[206:207]
	v_exp_f32_e32 v193, v198
	v_exp_f32_e32 v232, v199
	v_lshl_add_u64 v[202:203], v[202:203], 0, v[204:205]
	v_add_f32_e32 v193, 1.0, v193
	v_mov_b32_e32 v246, v208
	v_rcp_f32_e32 v208, v193
	v_add_f32_e32 v193, 1.0, v232
	v_rcp_f32_e32 v209, v193
	v_pk_fma_f32 v[232:233], v[144:145], v[168:169], v[172:173]
	v_pk_fma_f32 v[140:141], v[140:141], v[184:185], v[188:189]
	v_pk_fma_f32 v[232:233], v[156:157], v[164:165], v[232:233]
	v_pk_mul_f32 v[198:199], v[198:199], v[208:209]
	v_pk_fma_f32 v[194:195], v[160:161], v[194:195], v[232:233]
	v_pk_fma_f32 v[208:209], v[146:147], v[170:171], v[174:175]
	v_pk_mul_f32 v[194:195], v[194:195], v[198:199]
	v_pk_fma_f32 v[198:199], v[134:135], v[186:187], v[190:191]
	v_pk_fma_f32 v[208:209], v[158:159], v[166:167], v[208:209]
	v_pk_fma_f32 v[198:199], v[154:155], v[182:183], v[198:199]
	v_pk_fma_f32 v[196:197], v[162:163], v[196:197], v[208:209]
	v_pk_fma_f32 v[198:199], v[178:179], v[200:201], v[198:199]
	v_cvt_pk_bf16_f32 v248, v194, v195
	v_exp_f32_e32 v200, v198
	v_exp_f32_e32 v201, v199
	v_pk_fma_f32 v[148:149], v[148:149], v[168:169], v[172:173]
	v_pk_add_f32 v[200:201], v[200:201], 1.0 op_sel_hi:[1,0]
	v_rcp_f32_e32 v200, v200
	v_rcp_f32_e32 v201, v201
	v_or_b32_e32 v193, 1, v245
	v_pk_mul_f32 v[198:199], v[198:199], v[200:201]
	s_nop 0
	v_pk_mul_f32 v[196:197], v[196:197], v[198:199]
	v_pk_fma_f32 v[198:199], v[128:129], v[184:185], v[188:189]
	v_cvt_pk_bf16_f32 v249, v196, v197
	v_pk_fma_f32 v[198:199], v[132:133], v[180:181], v[198:199]
	v_mad_i64_i32 v[196:197], s[34:35], v193, s63, v[206:207]
	v_pk_fma_f32 v[152:153], v[152:153], v[176:177], v[198:199]
	v_lshl_add_u64 v[196:197], v[196:197], 0, v[204:205]
	v_exp_f32_e32 v193, v152
	v_exp_f32_e32 v198, v153
	v_add_f32_e32 v193, 1.0, v193
	v_rcp_f32_e32 v194, v193
	v_add_f32_e32 v193, 1.0, v198
	v_rcp_f32_e32 v195, v193
	v_pk_fma_f32 v[198:199], v[136:137], v[168:169], v[172:173]
	v_pk_fma_f32 v[128:129], v[128:129], v[180:181], v[140:141]
	v_pk_fma_f32 v[198:199], v[144:145], v[164:165], v[198:199]
	v_pk_fma_f32 v[128:129], v[132:133], v[176:177], v[128:129]
	v_pk_fma_f32 v[156:157], v[156:157], v[160:161], v[198:199]
	v_pk_mul_f32 v[152:153], v[152:153], v[194:195]
	v_pk_mul_f32 v[152:153], v[156:157], v[152:153]
	v_pk_fma_f32 v[156:157], v[130:131], v[186:187], v[190:191]
	v_exp_f32_e32 v140, v128
	v_pk_fma_f32 v[132:133], v[142:143], v[186:187], v[190:191]
	v_pk_fma_f32 v[156:157], v[134:135], v[182:183], v[156:157]
	v_pk_fma_f32 v[130:131], v[130:131], v[182:183], v[132:133]
	v_pk_fma_f32 v[154:155], v[154:155], v[178:179], v[156:157]
	v_pk_fma_f32 v[130:131], v[134:135], v[178:179], v[130:131]
	v_exp_f32_e32 v157, v154
	v_exp_f32_e32 v141, v129
	v_exp_f32_e32 v132, v130
	v_exp_f32_e32 v133, v131
	v_exp_f32_e32 v193, v155
	v_pk_add_f32 v[140:141], v[140:141], 1.0 op_sel_hi:[1,0]
	v_pk_add_f32 v[132:133], v[132:133], 1.0 op_sel_hi:[1,0]
	v_cvt_pk_bf16_f32 v253, v152, v153
	v_add_f32_e32 v152, 1.0, v157
	v_add_f32_e32 v153, 1.0, v193
	v_rcp_f32_e32 v140, v140
	v_rcp_f32_e32 v141, v141
; #define LAS __attribute__((address_space(3)))
; __device__ __forceinline__ float sigmoidf_(float x) { return __builtin_amdgcn_rcpf(1.0f + __expf(-x)); }
;     __device__ __forceinline__ void operator()(AccRef acc, const Unit& u, int wr, int wc, int fr, int fq) const {
;     ...
;                 f32x4 h2v = (f32x4){0.f, 0.f, 0.f, 0.f}, h3v = h2v, h2g = h2v, h3g = h2v;
;                 const int pb = ai * 2 + wr - 1;
;                 if (pb >= 0 && fr == 0) { const LAS float* xp = xch + (pb * 2) * 256 + clb + 4 * n;
;                     h2v = *(const LAS f32x4*)(xp); h3v = *(const LAS f32x4*)(xp + 256); h2g = *(const LAS f32x4*)(xp + 128); h3g = *(const LAS f32x4*)(xp + 256 + 128); }
;                 float o[4][4];
; #pragma unroll
;                 for (int j = 0; j < 4; ++j) {
;                     const float v0 = acc[ai][0][0][n][j], v1 = acc[ai][0][1][n][j], v2 = acc[ai][0][2][n][j], v3 = acc[ai][0][3][n][j];
;                     const float g0 = acc[ai][1][0][n][j], g1 = acc[ai][1][1][n][j], g2 = acc[ai][1][2][n][j], g3 = acc[ai][1][3][n][j];
;                     const float pv3 = dpp_upd<0x111>(h3v[j], v3), pv2 = dpp_upd<0x111>(h2v[j], v2), pg3 = dpp_upd<0x111>(h3g[j], g3), pg2 = dpp_upd<0x111>(h2g[j], g2);
;                     const float hv0 = bvv[j] + w2v[j] * v0 + w1v[j] * pv3 + w0v[j] * pv2, hv1 = bvv[j] + w2v[j] * v1 + w1v[j] * v0 + w0v[j] * pv3;
;                     const float hv2 = bvv[j] + w2v[j] * v2 + w1v[j] * v1 + w0v[j] * v0, hv3 = bvv[j] + w2v[j] * v3 + w1v[j] * v2 + w0v[j] * v1;
;                     const float hg0 = bvg[j] + w2g[j] * g0 + w1g[j] * pg3 + w0g[j] * pg2, hg1 = bvg[j] + w2g[j] * g1 + w1g[j] * g0 + w0g[j] * pg3;
;                     const float hg2 = bvg[j] + w2g[j] * g2 + w1g[j] * g1 + w0g[j] * g0, hg3 = bvg[j] + w2g[j] * g3 + w1g[j] * g2 + w0g[j] * g1;
;                     o[0][j] = hg0 * sigmoidf_(hg0) * hv0; o[1][j] = hg1 * sigmoidf_(hg1) * hv1; o[2][j] = hg2 * sigmoidf_(hg2) * hv2; o[3][j] = hg3 * sigmoidf_(hg3) * hv3; }
; #pragma unroll
;                 for (int m = 0; m < 4; ++m) { u32x2 w; w.x = cvt_pk_bf16(o[m][0], o[m][1]); w.y = cvt_pk_bf16(o[m][2], o[m][3]);
;                     *(u32x2*)(Aout + (size_t)(row0 + ai * 128 + m) * FH + hc0 + 4 * n) = w; } } }
	v_rcp_f32_e32 v132, v132
	v_rcp_f32_e32 v133, v133
	v_rcp_f32_e32 v152, v152
	v_rcp_f32_e32 v153, v153
	v_pk_fma_f32 v[142:143], v[150:151], v[170:171], v[174:175]
	v_pk_fma_f32 v[194:195], v[138:139], v[170:171], v[174:175]
	v_pk_fma_f32 v[136:137], v[136:137], v[164:165], v[148:149]
	v_pk_fma_f32 v[134:135], v[138:139], v[166:167], v[142:143]
	v_pk_fma_f32 v[194:195], v[146:147], v[166:167], v[194:195]
	v_pk_fma_f32 v[136:137], v[144:145], v[160:161], v[136:137]
	v_pk_mul_f32 v[128:129], v[128:129], v[140:141]
	v_pk_fma_f32 v[134:135], v[146:147], v[162:163], v[134:135]
	v_pk_mul_f32 v[130:131], v[130:131], v[132:133]
	v_pk_fma_f32 v[158:159], v[158:159], v[162:163], v[194:195]
	v_pk_mul_f32 v[152:153], v[154:155], v[152:153]
	v_pk_mul_f32 v[128:129], v[136:137], v[128:129]
	v_pk_mul_f32 v[130:131], v[134:135], v[130:131]
	v_pk_mul_f32 v[152:153], v[158:159], v[152:153]
	v_cvt_pk_bf16_f32 v250, v128, v129
	v_cvt_pk_bf16_f32 v251, v130, v131
	v_or_b32_e32 v130, 3, v245
	v_cvt_pk_bf16_f32 v254, v152, v153
	v_or_b32_e32 v152, 2, v245
	v_mad_i64_i32 v[130:131], s[34:35], v130, s63, v[206:207]
	v_mad_i64_i32 v[152:153], s[34:35], v152, s63, v[206:207]
	v_lshl_add_u64 v[140:141], v[130:131], 0, v[204:205]
	v_lshl_add_u64 v[152:153], v[152:153], 0, v[204:205]
	v_mov_b32_e32 v193, 0
	v_mov_b64_e32 v[194:195], 0
	v_mov_b64_e32 v[136:137], 0
	v_mov_b64_e32 v[138:139], 0
	v_mov_b64_e32 v[128:129], 0
	v_mov_b64_e32 v[130:131], 0
	v_mov_b64_e32 v[132:133], 0
	v_mov_b64_e32 v[134:135], 0
	s_and_saveexec_b64 s[34:35], s[22:23]
	s_cbranch_execz .LBB0_1951
	ds_read_b128 v[132:135], v236 offset:2048
	ds_read_b128 v[136:139], v236 offset:2560
	ds_read_b128 v[128:131], v236 offset:3072
	ds_read_b128 v[192:195], v236 offset:3584
.LBB0_1951:
	s_or_b64 exec, exec, s[34:35]
	s_waitcnt lgkmcnt(0)
	v_mov_b32_dpp v192, v72 row_shr:1 row_mask:0xf bank_mask:0xf
	v_mov_b32_dpp v193, v73 row_shr:1 row_mask:0xf bank_mask:0xf
	v_pk_fma_f32 v[142:143], v[88:89], v[184:185], v[188:189]
	v_mov_b32_dpp v136, v64 row_shr:1 row_mask:0xf bank_mask:0xf
	v_mov_b32_dpp v137, v65 row_shr:1 row_mask:0xf bank_mask:0xf
	v_pk_fma_f32 v[142:143], v[180:181], v[192:193], v[142:143]
	v_mov_b32_dpp v128, v84 row_shr:1 row_mask:0xf bank_mask:0xf
	v_pk_fma_f32 v[136:137], v[176:177], v[136:137], v[142:143]
	v_mov_b32_dpp v129, v85 row_shr:1 row_mask:0xf bank_mask:0xf
	v_exp_f32_e32 v142, v136
	v_exp_f32_e32 v143, v137
	v_pk_fma_f32 v[144:145], v[92:93], v[168:169], v[172:173]
	v_mov_b32_dpp v132, v76 row_shr:1 row_mask:0xf bank_mask:0xf
	v_pk_add_f32 v[142:143], v[142:143], 1.0 op_sel_hi:[1,0]
	v_rcp_f32_e32 v142, v142
	v_rcp_f32_e32 v143, v143
	v_mov_b32_dpp v133, v77 row_shr:1 row_mask:0xf bank_mask:0xf
	v_pk_fma_f32 v[144:145], v[164:165], v[128:129], v[144:145]
	v_mov_b32_dpp v194, v74 row_shr:1 row_mask:0xf bank_mask:0xf
	v_pk_fma_f32 v[132:133], v[160:161], v[132:133], v[144:145]
	v_pk_mul_f32 v[136:137], v[136:137], v[142:143]
	v_mov_b32_dpp v195, v75 row_shr:1 row_mask:0xf bank_mask:0xf
	v_pk_mul_f32 v[132:133], v[132:133], v[136:137]
	v_pk_fma_f32 v[136:137], v[90:91], v[186:187], v[190:191]
	v_mov_b32_dpp v138, v66 row_shr:1 row_mask:0xf bank_mask:0xf
	v_mov_b32_dpp v139, v67 row_shr:1 row_mask:0xf bank_mask:0xf
	v_pk_fma_f32 v[136:137], v[182:183], v[194:195], v[136:137]
	v_mov_b32_dpp v130, v86 row_shr:1 row_mask:0xf bank_mask:0xf
	v_pk_fma_f32 v[136:137], v[178:179], v[138:139], v[136:137]
	v_mov_b32_dpp v131, v87 row_shr:1 row_mask:0xf bank_mask:0xf
	v_exp_f32_e32 v139, v136
	v_exp_f32_e32 v142, v137
	v_cvt_pk_bf16_f32 v144, v132, v133
	v_add_f32_e32 v132, 1.0, v139
	v_rcp_f32_e32 v132, v132
	v_add_f32_e32 v133, 1.0, v142
	v_rcp_f32_e32 v133, v133
	v_pk_fma_f32 v[142:143], v[94:95], v[170:171], v[174:175]
	v_mov_b32_dpp v134, v78 row_shr:1 row_mask:0xf bank_mask:0xf
	v_mov_b32_dpp v135, v79 row_shr:1 row_mask:0xf bank_mask:0xf
	v_pk_mul_f32 v[132:133], v[136:137], v[132:133]
	v_pk_fma_f32 v[136:137], v[68:69], v[184:185], v[188:189]
	v_pk_fma_f32 v[142:143], v[166:167], v[130:131], v[142:143]
	v_pk_fma_f32 v[136:137], v[88:89], v[180:181], v[136:137]
	v_pk_fma_f32 v[134:135], v[162:163], v[134:135], v[142:143]
	v_pk_fma_f32 v[136:137], v[176:177], v[192:193], v[136:137]
	v_add_u32_e32 v146, 0x80, v245
	v_exp_f32_e32 v142, v136
	v_exp_f32_e32 v143, v137
	v_pk_mul_f32 v[132:133], v[134:135], v[132:133]
	v_mov_b64_e32 v[134:135], s[60:61]
	v_cvt_pk_bf16_f32 v145, v132, v133
	v_mad_i64_i32 v[132:133], s[34:35], v146, s63, v[134:135]
	v_lshl_add_u64 v[132:133], v[132:133], 0, v[204:205]
	v_add_f32_e32 v138, 1.0, v142
	v_add_f32_e32 v139, 1.0, v143
	v_rcp_f32_e32 v138, v138
	v_rcp_f32_e32 v139, v139
	v_pk_fma_f32 v[142:143], v[80:81], v[168:169], v[172:173]
	v_pk_fma_f32 v[72:73], v[72:73], v[184:185], v[188:189]
	v_pk_fma_f32 v[142:143], v[92:93], v[164:165], v[142:143]
	v_pk_mul_f32 v[136:137], v[136:137], v[138:139]
	v_pk_fma_f32 v[128:129], v[160:161], v[128:129], v[142:143]
	v_pk_fma_f32 v[84:85], v[84:85], v[168:169], v[172:173]
	v_pk_mul_f32 v[128:129], v[128:129], v[136:137]
	v_pk_fma_f32 v[136:137], v[70:71], v[186:187], v[190:191]
	s_nop 0
	v_pk_fma_f32 v[136:137], v[90:91], v[182:183], v[136:137]
	s_nop 0
	v_pk_fma_f32 v[136:137], v[178:179], v[194:195], v[136:137]
	s_nop 0
	v_exp_f32_e32 v139, v136
	v_exp_f32_e32 v142, v137
	v_cvt_pk_bf16_f32 v138, v128, v129
	v_add_f32_e32 v128, 1.0, v139
	v_rcp_f32_e32 v128, v128
	v_add_f32_e32 v129, 1.0, v142
	v_rcp_f32_e32 v129, v129
	v_pk_fma_f32 v[142:143], v[82:83], v[170:171], v[174:175]
	v_pk_mul_f32 v[128:129], v[136:137], v[128:129]
	v_pk_fma_f32 v[142:143], v[94:95], v[166:167], v[142:143]
	v_pk_fma_f32 v[136:137], v[76:77], v[168:169], v[172:173]
; #define LAS __attribute__((address_space(3)))
; __device__ __forceinline__ float sigmoidf_(float x) { return __builtin_amdgcn_rcpf(1.0f + __expf(-x)); }
;     __device__ __forceinline__ void operator()(AccRef acc, const Unit& u, int wr, int wc, int fr, int fq) const {
;     ...
;                 f32x4 h2v = (f32x4){0.f, 0.f, 0.f, 0.f}, h3v = h2v, h2g = h2v, h3g = h2v;
;                 const int pb = ai * 2 + wr - 1;
;                 if (pb >= 0 && fr == 0) { const LAS float* xp = xch + (pb * 2) * 256 + clb + 4 * n;
;                     h2v = *(const LAS f32x4*)(xp); h3v = *(const LAS f32x4*)(xp + 256); h2g = *(const LAS f32x4*)(xp + 128); h3g = *(const LAS f32x4*)(xp + 256 + 128); }
;                 float o[4][4];
; #pragma unroll
;                 for (int j = 0; j < 4; ++j) {
;                     const float v0 = acc[ai][0][0][n][j], v1 = acc[ai][0][1][n][j], v2 = acc[ai][0][2][n][j], v3 = acc[ai][0][3][n][j];
;                     const float g0 = acc[ai][1][0][n][j], g1 = acc[ai][1][1][n][j], g2 = acc[ai][1][2][n][j], g3 = acc[ai][1][3][n][j];
;                     const float pv3 = dpp_upd<0x111>(h3v[j], v3), pv2 = dpp_upd<0x111>(h2v[j], v2), pg3 = dpp_upd<0x111>(h3g[j], g3), pg2 = dpp_upd<0x111>(h2g[j], g2);
;                     const float hv0 = bvv[j] + w2v[j] * v0 + w1v[j] * pv3 + w0v[j] * pv2, hv1 = bvv[j] + w2v[j] * v1 + w1v[j] * v0 + w0v[j] * pv3;
;                     const float hv2 = bvv[j] + w2v[j] * v2 + w1v[j] * v1 + w0v[j] * v0, hv3 = bvv[j] + w2v[j] * v3 + w1v[j] * v2 + w0v[j] * v1;
;                     const float hg0 = bvg[j] + w2g[j] * g0 + w1g[j] * pg3 + w0g[j] * pg2, hg1 = bvg[j] + w2g[j] * g1 + w1g[j] * g0 + w0g[j] * pg3;
;                     const float hg2 = bvg[j] + w2g[j] * g2 + w1g[j] * g1 + w0g[j] * g0, hg3 = bvg[j] + w2g[j] * g3 + w1g[j] * g2 + w0g[j] * g1;
;                     o[0][j] = hg0 * sigmoidf_(hg0) * hv0; o[1][j] = hg1 * sigmoidf_(hg1) * hv1; o[2][j] = hg2 * sigmoidf_(hg2) * hv2; o[3][j] = hg3 * sigmoidf_(hg3) * hv3; }
; #pragma unroll
;                 for (int m = 0; m < 4; ++m) { u32x2 w; w.x = cvt_pk_bf16(o[m][0], o[m][1]); w.y = cvt_pk_bf16(o[m][2], o[m][3]);
;                     *(u32x2*)(Aout + (size_t)(row0 + ai * 128 + m) * FH + hc0 + 4 * n) = w; } } }
	v_pk_fma_f32 v[130:131], v[162:163], v[130:131], v[142:143]
	v_pk_fma_f32 v[136:137], v[80:81], v[164:165], v[136:137]
	v_pk_mul_f32 v[128:129], v[130:131], v[128:129]
	v_pk_fma_f32 v[130:131], v[64:65], v[184:185], v[188:189]
	v_pk_fma_f32 v[64:65], v[64:65], v[180:181], v[72:73]
	v_pk_fma_f32 v[130:131], v[68:69], v[180:181], v[130:131]
	v_pk_fma_f32 v[64:65], v[68:69], v[176:177], v[64:65]
	v_pk_fma_f32 v[88:89], v[88:89], v[176:177], v[130:131]
	v_pk_fma_f32 v[92:93], v[92:93], v[160:161], v[136:137]
	v_exp_f32_e32 v130, v88
	v_exp_f32_e32 v131, v89
	v_exp_f32_e32 v72, v64
	v_pk_add_f32 v[130:131], v[130:131], 1.0 op_sel_hi:[1,0]
	v_rcp_f32_e32 v130, v130
	v_rcp_f32_e32 v131, v131
	v_pk_fma_f32 v[68:69], v[74:75], v[186:187], v[190:191]
	v_exp_f32_e32 v73, v65
	v_pk_mul_f32 v[88:89], v[88:89], v[130:131]
	v_pk_mul_f32 v[88:89], v[92:93], v[88:89]
	v_pk_fma_f32 v[92:93], v[66:67], v[186:187], v[190:191]
	v_pk_fma_f32 v[66:67], v[66:67], v[182:183], v[68:69]
	v_pk_fma_f32 v[92:93], v[70:71], v[182:183], v[92:93]
	v_pk_fma_f32 v[66:67], v[70:71], v[178:179], v[66:67]
	v_pk_fma_f32 v[90:91], v[90:91], v[178:179], v[92:93]
	v_exp_f32_e32 v93, v90
	v_exp_f32_e32 v68, v66
	v_exp_f32_e32 v69, v67
	v_exp_f32_e32 v130, v91
	v_pk_add_f32 v[72:73], v[72:73], 1.0 op_sel_hi:[1,0]
	v_pk_add_f32 v[68:69], v[68:69], 1.0 op_sel_hi:[1,0]
	v_cvt_pk_bf16_f32 v198, v88, v89
	v_add_f32_e32 v88, 1.0, v93
	v_add_f32_e32 v89, 1.0, v130
	v_rcp_f32_e32 v72, v72
	v_rcp_f32_e32 v73, v73
	v_rcp_f32_e32 v68, v68
	v_rcp_f32_e32 v69, v69
	v_rcp_f32_e32 v88, v88
	v_rcp_f32_e32 v89, v89
	v_pk_fma_f32 v[74:75], v[86:87], v[170:171], v[174:175]
	v_pk_fma_f32 v[130:131], v[78:79], v[170:171], v[174:175]
	v_pk_fma_f32 v[76:77], v[76:77], v[164:165], v[84:85]
	v_pk_fma_f32 v[70:71], v[78:79], v[166:167], v[74:75]
	v_pk_fma_f32 v[130:131], v[82:83], v[166:167], v[130:131]
	v_pk_fma_f32 v[76:77], v[80:81], v[160:161], v[76:77]
	v_pk_mul_f32 v[64:65], v[64:65], v[72:73]
	v_pk_fma_f32 v[70:71], v[82:83], v[162:163], v[70:71]
	v_pk_mul_f32 v[66:67], v[66:67], v[68:69]
	v_pk_fma_f32 v[94:95], v[94:95], v[162:163], v[130:131]
	v_pk_mul_f32 v[88:89], v[90:91], v[88:89]
	v_pk_mul_f32 v[64:65], v[76:77], v[64:65]
	v_pk_mul_f32 v[66:67], v[70:71], v[66:67]
	v_pk_mul_f32 v[88:89], v[94:95], v[88:89]
	v_cvt_pk_bf16_f32 v148, v64, v65
	v_cvt_pk_bf16_f32 v149, v66, v67
	v_add_u32_e32 v66, 0x83, v245
	v_cvt_pk_bf16_f32 v155, v128, v129
	v_add_u32_e32 v128, 0x81, v245
	v_cvt_pk_bf16_f32 v199, v88, v89
	v_add_u32_e32 v88, 0x82, v245
	v_mad_i64_i32 v[66:67], s[34:35], v66, s63, v[134:135]
	v_mad_i64_i32 v[128:129], s[34:35], v128, s63, v[134:135]
	v_mad_i64_i32 v[88:89], s[34:35], v88, s63, v[134:135]
	v_lshl_add_u64 v[82:83], v[66:67], 0, v[204:205]
	v_lshl_add_u64 v[128:129], v[128:129], 0, v[204:205]
	v_lshl_add_u64 v[88:89], v[88:89], 0, v[204:205]
	v_mov_b32_e32 v64, 0
	v_mov_b64_e32 v[70:71], 0
	v_mov_b64_e32 v[72:73], 0
	v_mov_b64_e32 v[78:79], 0
	v_mov_b64_e32 v[80:81], 0
	v_mov_b64_e32 v[66:67], 0
	v_mov_b64_e32 v[68:69], 0
	v_mov_b64_e32 v[74:75], 0
	v_mov_b64_e32 v[76:77], 0
	v_mov_b32_e32 v154, v138
	s_and_saveexec_b64 s[34:35], s[20:21]
	s_cbranch_execz .LBB0_1953
	ds_read_b128 v[74:77], v241
	ds_read_b128 v[66:69], v240
	ds_read_b128 v[78:81], v239
	ds_read_b128 v[70:73], v238
; #define LAS __attribute__((address_space(3)))
; __device__ __forceinline__ float sigmoidf_(float x) { return __builtin_amdgcn_rcpf(1.0f + __expf(-x)); }
;     __device__ __forceinline__ void operator()(AccRef acc, const Unit& u, int wr, int wc, int fr, int fq) const {
;     ...
;                 f32x4 h2v = (f32x4){0.f, 0.f, 0.f, 0.f}, h3v = h2v, h2g = h2v, h3g = h2v;
;                 const int pb = ai * 2 + wr - 1;
;                 if (pb >= 0 && fr == 0) { const LAS float* xp = xch + (pb * 2) * 256 + clb + 4 * n;
;                     h2v = *(const LAS f32x4*)(xp); h3v = *(const LAS f32x4*)(xp + 256); h2g = *(const LAS f32x4*)(xp + 128); h3g = *(const LAS f32x4*)(xp + 256 + 128); }
;                 float o[4][4];
; #pragma unroll
;                 for (int j = 0; j < 4; ++j) {
;                     const float v0 = acc[ai][0][0][n][j], v1 = acc[ai][0][1][n][j], v2 = acc[ai][0][2][n][j], v3 = acc[ai][0][3][n][j];
;                     const float g0 = acc[ai][1][0][n][j], g1 = acc[ai][1][1][n][j], g2 = acc[ai][1][2][n][j], g3 = acc[ai][1][3][n][j];
;                     const float pv3 = dpp_upd<0x111>(h3v[j], v3), pv2 = dpp_upd<0x111>(h2v[j], v2), pg3 = dpp_upd<0x111>(h3g[j], g3), pg2 = dpp_upd<0x111>(h2g[j], g2);
;                     const float hv0 = bvv[j] + w2v[j] * v0 + w1v[j] * pv3 + w0v[j] * pv2, hv1 = bvv[j] + w2v[j] * v1 + w1v[j] * v0 + w0v[j] * pv3;
;                     const float hv2 = bvv[j] + w2v[j] * v2 + w1v[j] * v1 + w0v[j] * v0, hv3 = bvv[j] + w2v[j] * v3 + w1v[j] * v2 + w0v[j] * v1;
;                     const float hg0 = bvg[j] + w2g[j] * g0 + w1g[j] * pg3 + w0g[j] * pg2, hg1 = bvg[j] + w2g[j] * g1 + w1g[j] * g0 + w0g[j] * pg3;
;                     const float hg2 = bvg[j] + w2g[j] * g2 + w1g[j] * g1 + w0g[j] * g0, hg3 = bvg[j] + w2g[j] * g3 + w1g[j] * g2 + w0g[j] * g1;
;                     o[0][j] = hg0 * sigmoidf_(hg0) * hv0; o[1][j] = hg1 * sigmoidf_(hg1) * hv1; o[2][j] = hg2 * sigmoidf_(hg2) * hv2; o[3][j] = hg3 * sigmoidf_(hg3) * hv3; }
; #pragma unroll
;                 for (int m = 0; m < 4; ++m) { u32x2 w; w.x = cvt_pk_bf16(o[m][0], o[m][1]); w.y = cvt_pk_bf16(o[m][2], o[m][3]);
;                     *(u32x2*)(Aout + (size_t)(row0 + ai * 128 + m) * FH + hc0 + 4 * n) = w; } } }
.LBB0_1953:
	s_or_b64 exec, exec, s[34:35]
	s_waitcnt lgkmcnt(0)
	v_mov_b32_dpp v70, v44 row_shr:1 row_mask:0xf bank_mask:0xf
	v_mov_b32_dpp v71, v45 row_shr:1 row_mask:0xf bank_mask:0xf
	s_waitcnt vmcnt(0)
	v_pk_fma_f32 v[84:85], v[56:57], v[120:121], v[124:125]
	v_mov_b32_dpp v78, v32 row_shr:1 row_mask:0xf bank_mask:0xf
	v_mov_b32_dpp v79, v33 row_shr:1 row_mask:0xf bank_mask:0xf
	v_pk_fma_f32 v[84:85], v[116:117], v[70:71], v[84:85]
	v_mov_b32_dpp v66, v52 row_shr:1 row_mask:0xf bank_mask:0xf
	v_pk_fma_f32 v[78:79], v[112:113], v[78:79], v[84:85]
	v_mov_b32_dpp v67, v53 row_shr:1 row_mask:0xf bank_mask:0xf
	v_exp_f32_e32 v84, v78
	v_exp_f32_e32 v85, v79
	v_pk_fma_f32 v[86:87], v[60:61], v[104:105], v[108:109]
	v_pk_add_f32 v[84:85], v[84:85], 1.0 op_sel_hi:[1,0]
	v_rcp_f32_e32 v84, v84
	v_rcp_f32_e32 v85, v85
	v_mov_b32_dpp v74, v40 row_shr:1 row_mask:0xf bank_mask:0xf
	v_mov_b32_dpp v75, v41 row_shr:1 row_mask:0xf bank_mask:0xf
	v_pk_fma_f32 v[86:87], v[100:101], v[66:67], v[86:87]
	v_pk_mul_f32 v[78:79], v[78:79], v[84:85]
	v_pk_fma_f32 v[74:75], v[96:97], v[74:75], v[86:87]
	v_mov_b32_dpp v72, v46 row_shr:1 row_mask:0xf bank_mask:0xf
	v_mov_b32_dpp v73, v47 row_shr:1 row_mask:0xf bank_mask:0xf
	v_pk_mul_f32 v[74:75], v[74:75], v[78:79]
	v_pk_fma_f32 v[78:79], v[58:59], v[122:123], v[126:127]
	v_mov_b32_dpp v80, v34 row_shr:1 row_mask:0xf bank_mask:0xf
	v_mov_b32_dpp v81, v35 row_shr:1 row_mask:0xf bank_mask:0xf
	v_pk_fma_f32 v[78:79], v[118:119], v[72:73], v[78:79]
	v_mov_b32_dpp v68, v54 row_shr:1 row_mask:0xf bank_mask:0xf
	v_pk_fma_f32 v[78:79], v[114:115], v[80:81], v[78:79]
	v_mov_b32_dpp v69, v55 row_shr:1 row_mask:0xf bank_mask:0xf
	v_exp_f32_e32 v80, v78
	v_exp_f32_e32 v81, v79
	v_pk_fma_f32 v[84:85], v[62:63], v[106:107], v[110:111]
	v_pk_add_f32 v[80:81], v[80:81], 1.0 op_sel_hi:[1,0]
	v_rcp_f32_e32 v80, v80
	v_rcp_f32_e32 v81, v81
	v_mov_b32_dpp v76, v42 row_shr:1 row_mask:0xf bank_mask:0xf
	v_mov_b32_dpp v77, v43 row_shr:1 row_mask:0xf bank_mask:0xf
	v_pk_fma_f32 v[84:85], v[102:103], v[68:69], v[84:85]
	v_pk_mul_f32 v[78:79], v[78:79], v[80:81]
	v_pk_fma_f32 v[76:77], v[98:99], v[76:77], v[84:85]
	v_cvt_pk_bf16_f32 v92, v74, v75
	v_pk_mul_f32 v[76:77], v[76:77], v[78:79]
	v_pk_fma_f32 v[44:45], v[44:45], v[120:121], v[124:125]
	v_cvt_pk_bf16_f32 v93, v76, v77
	v_pk_fma_f32 v[76:77], v[36:37], v[120:121], v[124:125]
	v_mov_b32_e32 v90, v246
	v_mov_b32_e32 v91, v247
	global_store_dwordx4 v[202:203], v[90:93], off
	v_pk_fma_f32 v[76:77], v[56:57], v[116:117], v[76:77]
	v_pk_fma_f32 v[52:53], v[52:53], v[104:105], v[108:109]
	v_pk_fma_f32 v[70:71], v[112:113], v[70:71], v[76:77]
	s_nop 0
	v_exp_f32_e32 v74, v70
	v_exp_f32_e32 v75, v71
	s_nop 0
	v_pk_add_f32 v[74:75], v[74:75], 1.0 op_sel_hi:[1,0]
	v_rcp_f32_e32 v74, v74
	v_rcp_f32_e32 v75, v75
	v_pk_fma_f32 v[76:77], v[48:49], v[104:105], v[108:109]
	v_pk_mul_f32 v[70:71], v[70:71], v[74:75]
	v_pk_fma_f32 v[76:77], v[60:61], v[100:101], v[76:77]
	v_pk_fma_f32 v[74:75], v[50:51], v[106:107], v[110:111]
	v_pk_fma_f32 v[66:67], v[96:97], v[66:67], v[76:77]
	v_pk_fma_f32 v[74:75], v[62:63], v[102:103], v[74:75]
	v_pk_mul_f32 v[66:67], v[66:67], v[70:71]
	v_pk_fma_f32 v[70:71], v[38:39], v[122:123], v[126:127]
	v_pk_fma_f32 v[68:69], v[98:99], v[68:69], v[74:75]
	v_pk_fma_f32 v[70:71], v[58:59], v[118:119], v[70:71]
	v_cvt_pk_bf16_f32 v136, v66, v67
	v_pk_fma_f32 v[70:71], v[114:115], v[72:73], v[70:71]
	s_nop 0
	v_exp_f32_e32 v72, v70
	v_exp_f32_e32 v73, v71
	s_nop 0
	v_pk_add_f32 v[72:73], v[72:73], 1.0 op_sel_hi:[1,0]
	v_rcp_f32_e32 v72, v72
	v_rcp_f32_e32 v73, v73
	s_nop 0
	v_pk_mul_f32 v[70:71], v[70:71], v[72:73]
	s_nop 0
	v_pk_mul_f32 v[68:69], v[68:69], v[70:71]
	s_nop 0
	v_cvt_pk_bf16_f32 v137, v68, v69
	v_pk_fma_f32 v[68:69], v[32:33], v[120:121], v[124:125]
	v_mov_b32_e32 v134, v248
	v_mov_b32_e32 v135, v249
	global_store_dwordx4 v[196:197], v[134:137], off
	v_pk_fma_f32 v[68:69], v[36:37], v[116:117], v[68:69]
	v_pk_fma_f32 v[32:33], v[32:33], v[116:117], v[44:45]
	v_pk_fma_f32 v[56:57], v[56:57], v[112:113], v[68:69]
	v_pk_fma_f32 v[32:33], v[36:37], v[112:113], v[32:33]
	v_exp_f32_e32 v66, v56
	v_exp_f32_e32 v67, v57
	s_nop 0
	v_pk_add_f32 v[66:67], v[66:67], 1.0 op_sel_hi:[1,0]
	v_rcp_f32_e32 v66, v66
	v_rcp_f32_e32 v67, v67
	v_pk_fma_f32 v[68:69], v[40:41], v[104:105], v[108:109]
	v_exp_f32_e32 v44, v32
	v_pk_fma_f32 v[68:69], v[48:49], v[100:101], v[68:69]
	v_pk_mul_f32 v[56:57], v[56:57], v[66:67]
	v_pk_fma_f32 v[60:61], v[60:61], v[96:97], v[68:69]
	v_pk_fma_f32 v[36:37], v[46:47], v[122:123], v[126:127]
	v_pk_mul_f32 v[56:57], v[60:61], v[56:57]
	v_pk_fma_f32 v[60:61], v[34:35], v[122:123], v[126:127]
	v_pk_fma_f32 v[34:35], v[34:35], v[118:119], v[36:37]
	v_pk_fma_f32 v[60:61], v[38:39], v[118:119], v[60:61]
	v_pk_fma_f32 v[34:35], v[38:39], v[114:115], v[34:35]
	v_pk_fma_f32 v[58:59], v[58:59], v[114:115], v[60:61]
	v_exp_f32_e32 v60, v58
	v_exp_f32_e32 v45, v33
	v_exp_f32_e32 v36, v34
	v_exp_f32_e32 v37, v35
	v_exp_f32_e32 v61, v59
	v_cvt_pk_bf16_f32 v164, v56, v57
	v_pk_add_f32 v[44:45], v[44:45], 1.0 op_sel_hi:[1,0]
	v_pk_add_f32 v[36:37], v[36:37], 1.0 op_sel_hi:[1,0]
	v_pk_add_f32 v[60:61], v[60:61], 1.0 op_sel_hi:[1,0]
	v_rcp_f32_e32 v44, v44
	v_rcp_f32_e32 v45, v45
	v_rcp_f32_e32 v36, v36
	v_rcp_f32_e32 v37, v37
	v_rcp_f32_e32 v60, v60
	v_rcp_f32_e32 v61, v61
	v_pk_fma_f32 v[46:47], v[54:55], v[106:107], v[110:111]
	v_pk_fma_f32 v[66:67], v[42:43], v[106:107], v[110:111]
	v_pk_fma_f32 v[40:41], v[40:41], v[100:101], v[52:53]
	v_pk_fma_f32 v[38:39], v[42:43], v[102:103], v[46:47]
	v_pk_fma_f32 v[66:67], v[50:51], v[102:103], v[66:67]
	v_pk_fma_f32 v[40:41], v[48:49], v[96:97], v[40:41]
	v_pk_mul_f32 v[32:33], v[32:33], v[44:45]
	v_pk_fma_f32 v[38:39], v[50:51], v[98:99], v[38:39]
	v_pk_mul_f32 v[34:35], v[34:35], v[36:37]
	v_pk_fma_f32 v[62:63], v[62:63], v[98:99], v[66:67]
	v_pk_mul_f32 v[58:59], v[58:59], v[60:61]
	v_pk_mul_f32 v[32:33], v[40:41], v[32:33]
	v_pk_mul_f32 v[34:35], v[38:39], v[34:35]
	v_pk_mul_f32 v[58:59], v[62:63], v[58:59]
	v_cvt_pk_bf16_f32 v160, v32, v33
	v_cvt_pk_bf16_f32 v161, v34, v35
	v_cvt_pk_bf16_f32 v165, v58, v59
	v_mov_b32_e32 v158, v250
	v_mov_b32_e32 v159, v251
	global_store_dwordx4 v[140:141], v[158:161], off
	v_mov_b32_e32 v65, 0
	v_mov_b64_e32 v[66:67], 0
	v_mov_b64_e32 v[40:41], 0
	v_mov_b64_e32 v[42:43], 0
	v_mov_b64_e32 v[32:33], 0
	v_mov_b64_e32 v[34:35], 0
	v_mov_b64_e32 v[36:37], 0
	v_mov_b64_e32 v[38:39], 0
	v_mov_b32_e32 v162, v253
	v_mov_b32_e32 v163, v254
	global_store_dwordx4 v[152:153], v[162:165], off
	s_and_saveexec_b64 s[34:35], s[22:23]
	s_cbranch_execz .LBB0_1936
	ds_read_b128 v[36:39], v236 offset:2064
	ds_read_b128 v[40:43], v236 offset:2576
	ds_read_b128 v[32:35], v236 offset:3088
	ds_read_b128 v[64:67], v236 offset:3600
	s_branch .LBB0_1936
